# k-blocked bf16 layouts for all three big GEMM operands (activations h, y and transposed weights) so every LDS-DMA reads 1 KiB contiguous; adaLN/ynorm writers and PEER gather reader adapted
# speedup vs baseline: 1.1011x; 1.0381x over previous
; DEV int ltid() { int t = threadIdx.x; asm volatile("" : "+v"(t)); return t; }
; DEV unsigned pack2(float a, float b) { float2v v = {a, b}; return __builtin_bit_cast(unsigned, __builtin_convertvector(v, bf16x2v)); }
; DEV void ph_transpose(const float* src, int K, int N, int Npad, u16* dst, int item, float* sm) {
;   const int ntl = Npad / 64, kt = item / ntl, nti = item % ntl, tid = ltid();
;   const int c4 = tid & 15, r0 = tid >> 4;
;   float4 v[4];
; #pragma unroll
;   for (int ps = 0; ps < 4; ++ps) {
;     const int k = ps * 16 + r0, n = nti * 64 + c4 * 4;
;     v[ps] = (n < N) ? *(const float4*)(src + (size_t)(kt * 64 + k) * N + n) : make_float4(0.f, 0.f, 0.f, 0.f);
;   }
; #pragma unroll
;   for (int ps = 0; ps < 4; ++ps) {
;     const int k = ps * 16 + r0;
;     sm[k * 65 + c4 * 4 + 0] = v[ps].x; sm[k * 65 + c4 * 4 + 1] = v[ps].y; sm[k * 65 + c4 * 4 + 2] = v[ps].z; sm[k * 65 + c4 * 4 + 3] = v[ps].w;
;   }
;   __syncthreads();
;   {
;     const int n = tid >> 2, q = tid & 3;
;     u32x4 o0, o1;
; #pragma unroll
;     for (int e = 0; e < 4; ++e) {
;       o0[e] = pack2(sm[(q * 16 + 2 * e) * 65 + n], sm[(q * 16 + 2 * e + 1) * 65 + n]);
;       o1[e] = pack2(sm[(q * 16 + 8 + 2 * e) * 65 + n], sm[(q * 16 + 8 + 2 * e + 1) * 65 + n]);
;     }
;     u16* d = dst + (size_t)(nti * 64 + n) * K + kt * 64 + q * 16;
;     *(u32x4*)d = o0; *(u32x4*)(d + 8) = o1;
;   }
;   __syncthreads();
.LBB0_53:
	s_andn2_b64 vcc, exec, s[12:13]
	s_cbranch_vccnz .LBB0_55
	s_lshl_b32 s12, s9, 6
	v_mov_b32_e32 v8, v0
	s_and_b32 s13, s12, 0x7c0
	s_lshl_b32 s12, s9, 1
	s_waitcnt lgkmcnt(0)
	s_load_dwordx16 s[36:51], s[0:1], 0xc0
	s_add_i32 s12, s12, 0x1e280
	v_lshlrev_b32_e32 v2, 2, v8
	v_ashrrev_i32_e32 v9, 4, v8
	v_and_b32_e32 v10, 60, v2
	s_and_b32 s12, s12, 0x1ffc0
	v_or_b32_e32 v3, s13, v10
	v_add_u32_e32 v2, s12, v9
	v_lshlrev_b32_e32 v36, 2, v3
	v_ashrrev_i32_e32 v3, 31, v2
	s_waitcnt lgkmcnt(0)
	v_lshl_add_u64 v[4:5], s[36:37], 0, v[36:37]
	v_lshlrev_b64 v[2:3], 13, v[2:3]
	v_lshl_add_u64 v[6:7], v[4:5], 0, v[2:3]
	v_lshl_add_u32 v2, v9, 6, v9
	v_add_lshl_u32 v9, v2, v10, 2
	global_load_dwordx4 v[2:5], v[6:7], off
	v_add_u32_e32 v10, 0x1040, v9
	v_ashrrev_i32_e32 v12, 2, v8
	s_lshl_b32 s16, s12, 1
	s_waitcnt vmcnt(0)
	ds_write2_b32 v9, v2, v3 offset1:1
	ds_write2_b32 v9, v4, v5 offset0:2 offset1:3
	v_add_co_u32_e32 v2, vcc, s96, v6
	s_nop 1
	v_addc_co_u32_e32 v3, vcc, 0, v7, vcc
	global_load_dwordx4 v[2:5], v[2:3], off
	s_waitcnt vmcnt(0)
	ds_write2_b32 v10, v2, v3 offset1:1
	v_add_u32_e32 v2, 0x1048, v9
	ds_write2_b32 v2, v4, v5 offset1:1
	v_add_co_u32_e32 v2, vcc, s97, v6
	v_add_u32_e32 v10, 0x2080, v9
	s_nop 0
	v_addc_co_u32_e32 v3, vcc, 0, v7, vcc
	global_load_dwordx4 v[2:5], v[2:3], off
	s_waitcnt vmcnt(0)
	ds_write2_b32 v10, v2, v3 offset1:1
	v_add_u32_e32 v2, 0x2088, v9
	ds_write2_b32 v2, v4, v5 offset1:1
	v_add_co_u32_e32 v2, vcc, s5, v6
	v_add_u32_e32 v10, 0x30c0, v9
	s_nop 0
	v_addc_co_u32_e32 v3, vcc, 0, v7, vcc
	global_load_dwordx4 v[2:5], v[2:3], off
	s_waitcnt vmcnt(0)
	ds_write2_b32 v10, v2, v3 offset1:1
	v_add_u32_e32 v2, 0x30c8, v9
	ds_write2_b32 v2, v4, v5 offset1:1
	v_lshlrev_b32_e32 v2, 4, v8
	v_and_b32_e32 v13, 48, v2
	v_mul_u32_u24_e32 v2, 0x41, v13
	v_and_b32_e32 v3, -4, v8
	v_lshl_add_u32 v8, v2, 2, v3
	v_add_u32_e32 v7, 0x800, v8
	s_waitcnt lgkmcnt(0)
	s_barrier
	ds_read2_b32 v[4:5], v7 offset0:8 offset1:73
	ds_read2_b32 v[2:3], v8 offset1:65
	v_add_u32_e32 v10, 0x400, v8
	v_add_u32_e32 v14, 0xc00, v8
	v_lshlrev_b32_e32 v36, 1, v13
	s_waitcnt lgkmcnt(1)
	v_cvt_pk_bf16_f32 v6, v4, v5
	ds_read2_b32 v[4:5], v8 offset0:130 offset1:195
	s_waitcnt lgkmcnt(1)
	v_cvt_pk_bf16_f32 v2, v2, v3
	ds_read2_b32 v[8:9], v14 offset0:12 offset1:77
	s_waitcnt lgkmcnt(1)
	v_cvt_pk_bf16_f32 v3, v4, v5
	ds_read2_b32 v[4:5], v7 offset0:138 offset1:203
	s_waitcnt lgkmcnt(1)
	v_cvt_pk_bf16_f32 v8, v8, v9
	s_waitcnt lgkmcnt(0)
	v_cvt_pk_bf16_f32 v7, v4, v5
	ds_read2_b32 v[4:5], v10 offset0:4 offset1:69
	ds_read2_b32 v[10:11], v10 offset0:134 offset1:199
	s_waitcnt lgkmcnt(1)
	v_cvt_pk_bf16_f32 v4, v4, v5
	s_waitcnt lgkmcnt(0)
	v_cvt_pk_bf16_f32 v5, v10, v11
	ds_read2_b32 v[10:11], v14 offset0:142 offset1:207
	s_waitcnt lgkmcnt(0)
	v_cvt_pk_bf16_f32 v9, v10, v11
	v_add_u32_e32 v10, s13, v12
	v_ashrrev_i32_e32 v11, 31, v10
	v_lshlrev_b64 v[10:11], 6, v[10:11]
	v_lshl_add_u64 v[10:11], s[50:51], 0, v[10:11]
	v_lshrrev_b32_e32 v14, 6, v36
	v_lshrrev_b32_e64 v12, 6, s16
	v_add_u32_e32 v14, v14, v12
	v_mul_u32_u24_e32 v14, 0x20000, v14
	v_and_b32_e32 v36, 32, v36
	v_add_u32_e32 v36, v36, v14
	v_lshl_add_u64 v[10:11], v[10:11], 0, v[36:37]
	global_store_dwordx4 v[10:11], v[2:5], off
	global_store_dwordx4 v[10:11], v[6:9], off offset:16
	s_barrier

; DEV int ltid() { int t = threadIdx.x; asm volatile("" : "+v"(t)); return t; }
; DEV unsigned pack2(float a, float b) { float2v v = {a, b}; return __builtin_bit_cast(unsigned, __builtin_convertvector(v, bf16x2v)); }
; DEV void ph_transpose(const float* src, int K, int N, int Npad, u16* dst, int item, float* sm) {
;   const int ntl = Npad / 64, kt = item / ntl, nti = item % ntl, tid = ltid();
;   const int c4 = tid & 15, r0 = tid >> 4;
;   float4 v[4];
; #pragma unroll
;   for (int ps = 0; ps < 4; ++ps) {
;     const int k = ps * 16 + r0, n = nti * 64 + c4 * 4;
;     v[ps] = (n < N) ? *(const float4*)(src + (size_t)(kt * 64 + k) * N + n) : make_float4(0.f, 0.f, 0.f, 0.f);
;   }
; #pragma unroll
;   for (int ps = 0; ps < 4; ++ps) {
;     const int k = ps * 16 + r0;
;     sm[k * 65 + c4 * 4 + 0] = v[ps].x; sm[k * 65 + c4 * 4 + 1] = v[ps].y; sm[k * 65 + c4 * 4 + 2] = v[ps].z; sm[k * 65 + c4 * 4 + 3] = v[ps].w;
;   }
;   __syncthreads();
;   {
;     const int n = tid >> 2, q = tid & 3;
;     u32x4 o0, o1;
; #pragma unroll
;     for (int e = 0; e < 4; ++e) {
;       o0[e] = pack2(sm[(q * 16 + 2 * e) * 65 + n], sm[(q * 16 + 2 * e + 1) * 65 + n]);
;       o1[e] = pack2(sm[(q * 16 + 8 + 2 * e) * 65 + n], sm[(q * 16 + 8 + 2 * e + 1) * 65 + n]);
;     }
;     u16* d = dst + (size_t)(nti * 64 + n) * K + kt * 64 + q * 16;
;     *(u32x4*)d = o0; *(u32x4*)(d + 8) = o1;
;   }
;   __syncthreads();
.LBB0_56:
	s_andn2_b64 vcc, exec, s[12:13]
	s_cbranch_vccnz .LBB0_58
	s_lshl_b32 s12, s9, 6
	v_mov_b32_e32 v8, v0
	s_and_b32 s13, s12, 0x7c0
	s_lshl_b32 s12, s9, 1
	s_waitcnt lgkmcnt(0)
	s_load_dwordx16 s[36:51], s[0:1], 0x0
	s_add_i32 s12, s12, 0x1ea80
	v_lshlrev_b32_e32 v2, 2, v8
	v_ashrrev_i32_e32 v9, 4, v8
	v_and_b32_e32 v10, 60, v2
	s_and_b32 s12, s12, 0x1ffc0
	v_or_b32_e32 v3, s13, v10
	v_add_u32_e32 v2, s12, v9
	v_lshlrev_b32_e32 v36, 2, v3
	v_ashrrev_i32_e32 v3, 31, v2
	s_waitcnt lgkmcnt(0)
	v_lshl_add_u64 v[4:5], s[50:51], 0, v[36:37]
	v_lshlrev_b64 v[2:3], 13, v[2:3]
	v_lshl_add_u64 v[6:7], v[4:5], 0, v[2:3]
	v_lshl_add_u32 v2, v9, 6, v9
	v_add_lshl_u32 v9, v2, v10, 2
	global_load_dwordx4 v[2:5], v[6:7], off
	v_add_u32_e32 v10, 0x1040, v9
	v_ashrrev_i32_e32 v12, 2, v8
	s_load_dwordx16 s[36:51], s[0:1], 0xc0
	s_lshl_b32 s16, s12, 1
	s_waitcnt vmcnt(0)
	ds_write2_b32 v9, v2, v3 offset1:1
	ds_write2_b32 v9, v4, v5 offset0:2 offset1:3
	v_add_co_u32_e32 v2, vcc, s96, v6
	s_nop 1
	v_addc_co_u32_e32 v3, vcc, 0, v7, vcc
	global_load_dwordx4 v[2:5], v[2:3], off
	s_waitcnt vmcnt(0)
	ds_write2_b32 v10, v2, v3 offset1:1
	v_add_u32_e32 v2, 0x1048, v9
	ds_write2_b32 v2, v4, v5 offset1:1
	v_add_co_u32_e32 v2, vcc, s97, v6
	v_add_u32_e32 v10, 0x2080, v9
	s_nop 0
	v_addc_co_u32_e32 v3, vcc, 0, v7, vcc
	global_load_dwordx4 v[2:5], v[2:3], off
	s_waitcnt vmcnt(0)
	ds_write2_b32 v10, v2, v3 offset1:1
	v_add_u32_e32 v2, 0x2088, v9
	ds_write2_b32 v2, v4, v5 offset1:1
	v_add_co_u32_e32 v2, vcc, s5, v6
	v_add_u32_e32 v10, 0x30c0, v9
	s_nop 0
	v_addc_co_u32_e32 v3, vcc, 0, v7, vcc
	global_load_dwordx4 v[2:5], v[2:3], off
	s_waitcnt vmcnt(0)
	ds_write2_b32 v10, v2, v3 offset1:1
	v_add_u32_e32 v2, 0x30c8, v9
	ds_write2_b32 v2, v4, v5 offset1:1
	v_lshlrev_b32_e32 v2, 4, v8
	v_and_b32_e32 v13, 48, v2
	v_mul_u32_u24_e32 v2, 0x41, v13
	v_and_b32_e32 v3, -4, v8
	v_lshl_add_u32 v8, v2, 2, v3
	v_add_u32_e32 v7, 0x800, v8
	s_waitcnt lgkmcnt(0)
	s_barrier
	ds_read2_b32 v[4:5], v7 offset0:8 offset1:73
	ds_read2_b32 v[2:3], v8 offset1:65
	v_add_u32_e32 v10, 0x400, v8
	v_add_u32_e32 v14, 0xc00, v8
	v_lshlrev_b32_e32 v36, 1, v13
	s_waitcnt lgkmcnt(1)
	v_cvt_pk_bf16_f32 v6, v4, v5
	ds_read2_b32 v[4:5], v8 offset0:130 offset1:195
	s_waitcnt lgkmcnt(1)
	v_cvt_pk_bf16_f32 v2, v2, v3
	ds_read2_b32 v[8:9], v14 offset0:12 offset1:77
	s_waitcnt lgkmcnt(1)
	v_cvt_pk_bf16_f32 v3, v4, v5
	ds_read2_b32 v[4:5], v7 offset0:138 offset1:203
	s_waitcnt lgkmcnt(1)
	v_cvt_pk_bf16_f32 v8, v8, v9
	s_waitcnt lgkmcnt(0)
	v_cvt_pk_bf16_f32 v7, v4, v5
	ds_read2_b32 v[4:5], v10 offset0:4 offset1:69
	ds_read2_b32 v[10:11], v10 offset0:134 offset1:199
	s_waitcnt lgkmcnt(1)
	v_cvt_pk_bf16_f32 v4, v4, v5
	s_waitcnt lgkmcnt(0)
	v_cvt_pk_bf16_f32 v5, v10, v11
	ds_read2_b32 v[10:11], v14 offset0:142 offset1:207
	s_waitcnt lgkmcnt(0)
	v_cvt_pk_bf16_f32 v9, v10, v11
	v_add_u32_e32 v10, s13, v12
	v_ashrrev_i32_e32 v11, 31, v10
	v_lshlrev_b64 v[10:11], 6, v[10:11]
	v_lshl_add_u64 v[10:11], s[48:49], 0, v[10:11]
	v_lshrrev_b32_e32 v14, 6, v36
	v_lshrrev_b32_e64 v12, 6, s16
	v_add_u32_e32 v14, v14, v12
	v_mul_u32_u24_e32 v14, 0x20000, v14
	v_and_b32_e32 v36, 32, v36
	v_add_u32_e32 v36, v36, v14
	v_lshl_add_u64 v[10:11], v[10:11], 0, v[36:37]
	global_store_dwordx4 v[10:11], v[2:5], off
	global_store_dwordx4 v[10:11], v[6:9], off offset:16
	s_barrier

; DEV int ltid() { int t = threadIdx.x; asm volatile("" : "+v"(t)); return t; }
; DEV unsigned pack2(float a, float b) { float2v v = {a, b}; return __builtin_bit_cast(unsigned, __builtin_convertvector(v, bf16x2v)); }
; DEV void ph_transpose(const float* src, int K, int N, int Npad, u16* dst, int item, float* sm) {
;   const int ntl = Npad / 64, kt = item / ntl, nti = item % ntl, tid = ltid();
;   const int c4 = tid & 15, r0 = tid >> 4;
;   float4 v[4];
; #pragma unroll
;   for (int ps = 0; ps < 4; ++ps) {
;     const int k = ps * 16 + r0, n = nti * 64 + c4 * 4;
;     v[ps] = (n < N) ? *(const float4*)(src + (size_t)(kt * 64 + k) * N + n) : make_float4(0.f, 0.f, 0.f, 0.f);
;   }
; #pragma unroll
;   for (int ps = 0; ps < 4; ++ps) {
;     const int k = ps * 16 + r0;
;     sm[k * 65 + c4 * 4 + 0] = v[ps].x; sm[k * 65 + c4 * 4 + 1] = v[ps].y; sm[k * 65 + c4 * 4 + 2] = v[ps].z; sm[k * 65 + c4 * 4 + 3] = v[ps].w;
;   }
;   __syncthreads();
;   {
;     const int n = tid >> 2, q = tid & 3;
;     u32x4 o0, o1;
; #pragma unroll
;     for (int e = 0; e < 4; ++e) {
;       o0[e] = pack2(sm[(q * 16 + 2 * e) * 65 + n], sm[(q * 16 + 2 * e + 1) * 65 + n]);
;       o1[e] = pack2(sm[(q * 16 + 8 + 2 * e) * 65 + n], sm[(q * 16 + 8 + 2 * e + 1) * 65 + n]);
;     }
;     u16* d = dst + (size_t)(nti * 64 + n) * K + kt * 64 + q * 16;
;     *(u32x4*)d = o0; *(u32x4*)(d + 8) = o1;
;   }
;   __syncthreads();
.LBB0_68:
	s_or_b64 exec, exec, s[12:13]
	s_movk_i32 s12, 0x104
	v_mul_lo_u32 v18, v21, s12
	v_lshl_add_u32 v18, v22, 2, v18
	s_waitcnt vmcnt(0)
	ds_write2_b32 v18, v6, v7 offset1:1
	ds_write2_b32 v18, v8, v9 offset0:2 offset1:3
	v_add_u32_e32 v6, 0x1040, v18
	ds_write2_b32 v6, v2, v3 offset1:1
	v_add_u32_e32 v2, 0x1048, v18
	ds_write2_b32 v2, v4, v5 offset1:1
	v_add_u32_e32 v2, 0x2080, v18
	ds_write2_b32 v2, v14, v15 offset1:1
	v_add_u32_e32 v2, 0x2088, v18
	ds_write2_b32 v2, v16, v17 offset1:1
	v_add_u32_e32 v2, 0x30c0, v18
	ds_write2_b32 v2, v10, v11 offset1:1
	v_add_u32_e32 v2, 0x30c8, v18
	ds_write2_b32 v2, v12, v13 offset1:1
	v_lshlrev_b32_e32 v2, 4, v20
	v_and_b32_e32 v13, 48, v2
	v_mul_u32_u24_e32 v2, 0x41, v13
	v_and_b32_e32 v3, -4, v20
	v_lshl_add_u32 v8, v2, 2, v3
	v_add_u32_e32 v7, 0x800, v8
	s_waitcnt lgkmcnt(0)
	s_barrier
	ds_read2_b32 v[4:5], v7 offset0:8 offset1:73
	ds_read2_b32 v[2:3], v8 offset1:65
	v_add_u32_e32 v10, 0x400, v8
	v_add_u32_e32 v14, 0xc00, v8
	s_load_dwordx16 s[36:51], s[0:1], 0xc0
	s_waitcnt lgkmcnt(0)
	v_cvt_pk_bf16_f32 v6, v4, v5
	ds_read2_b32 v[4:5], v8 offset0:130 offset1:195
	v_cvt_pk_bf16_f32 v2, v2, v3
	ds_read2_b32 v[8:9], v14 offset0:12 offset1:77
	v_ashrrev_i32_e32 v12, 2, v20
	s_and_b32 s12, 0xffff, s15
	s_waitcnt lgkmcnt(1)
	v_cvt_pk_bf16_f32 v3, v4, v5
	ds_read2_b32 v[4:5], v7 offset0:138 offset1:203
	s_waitcnt lgkmcnt(1)
	v_cvt_pk_bf16_f32 v8, v8, v9
	s_lshl_b32 s16, s12, 1
	v_lshlrev_b32_e32 v36, 1, v13
	s_waitcnt lgkmcnt(0)
	v_cvt_pk_bf16_f32 v7, v4, v5
	ds_read2_b32 v[4:5], v10 offset0:4 offset1:69
	ds_read2_b32 v[10:11], v10 offset0:134 offset1:199
	s_waitcnt lgkmcnt(1)
	v_cvt_pk_bf16_f32 v4, v4, v5
	s_waitcnt lgkmcnt(0)
	v_cvt_pk_bf16_f32 v5, v10, v11
	ds_read2_b32 v[10:11], v14 offset0:142 offset1:207
	s_waitcnt lgkmcnt(0)
	v_cvt_pk_bf16_f32 v9, v10, v11
	v_add_u32_e32 v10, s14, v12
	v_ashrrev_i32_e32 v11, 31, v10
	v_lshlrev_b64 v[10:11], 6, v[10:11]
	v_lshl_add_u64 v[10:11], s[46:47], 0, v[10:11]
	v_lshrrev_b32_e32 v14, 6, v36
	v_lshrrev_b32_e64 v12, 6, s16
	v_add_u32_e32 v14, v14, v12
	v_mul_u32_u24_e32 v14, 0x4a000, v14
	v_and_b32_e32 v36, 32, v36
	v_add_u32_e32 v36, v36, v14
	v_lshl_add_u64 v[10:11], v[10:11], 0, v[36:37]
	global_store_dwordx4 v[10:11], v[2:5], off
	global_store_dwordx4 v[10:11], v[6:9], off offset:16
	s_barrier

; DEV int ltid() { int t = threadIdx.x; asm volatile("" : "+v"(t)); return t; }
; DEV void ph_adaln_row(const float* xin, const float* g, const float* mod, int sh_off, int sc_off, u16* hout, int row) {
;   const int lane = ltid() & 63, b = row >> 11;
;   const float* xr = xin + (size_t)row * 2048;
;   float4 v[8];
;   float ss = 0.f;
; #pragma unroll
;   for (int i = 0; i < 8; ++i) {
;     v[i] = *(const float4*)(xr + i * 256 + lane * 4);
;     ss += v[i].x * v[i].x + v[i].y * v[i].y + v[i].z * v[i].z + v[i].w * v[i].w;
;   }
;   ss = wave_sum(ss);
;   const float rstd = rsqrtf(ss * (1.f / 2048.f) + 1e-6f);
;   const float* mb = mod + (size_t)b * 12288;
; #pragma unroll
;   for (int i = 0; i < 8; ++i) {
;     int col = i * 256 + lane * 4;
;     float4 g4 = *(const float4*)(g + col);
;     float4 sc = *(const float4*)(mb + sc_off + col);
;     float4 sh = *(const float4*)(mb + sh_off + col);
; __global__ void __launch_bounds__(256, 2) fwd_megakernel(Params p) {
;     ...
;   for (int row = bid * 4 + wid; row < T_; row += nb * 4) ph_adaln_row(p.x, p.norm_mix_g, p.mod, 0, 2048, p.h, row);
.LBB0_189:
	s_or_b64 exec, exec, s[0:1]
	v_readlane_b32 s0, v254, 0
	s_lshl_b32 s2, s0, 2
	v_mov_b32_e32 v1, v0
	v_readlane_b32 s1, v254, 1
	s_mov_b32 s0, s2
	s_waitcnt lgkmcnt(0)
	s_barrier
	v_writelane_b32 v255, s0, 41
	v_ashrrev_i32_e32 v2, 6, v1
	v_add_u32_e32 v1, s2, v2
	v_writelane_b32 v255, s1, 42
	s_movk_i32 s0, 0x4000
	v_cmp_gt_i32_e32 vcc, s0, v1
	s_and_saveexec_b64 s[0:1], vcc
	v_readlane_b32 s8, v254, 25
	v_readlane_b32 s9, v254, 26
	v_readlane_b32 s16, v254, 33
	v_readlane_b32 s17, v254, 34
	v_readlane_b32 s10, v254, 27
	v_readlane_b32 s11, v254, 28
	v_readlane_b32 s12, v254, 29
	v_readlane_b32 s13, v254, 30
	v_readlane_b32 s14, v254, 31
	v_readlane_b32 s15, v254, 32
	v_readlane_b32 s18, v254, 35
	v_readlane_b32 s19, v254, 36
	v_readlane_b32 s20, v254, 37
	v_readlane_b32 s21, v254, 38
	v_readlane_b32 s22, v254, 39
	v_readlane_b32 s23, v254, 40
	s_cbranch_execz .LBB0_192
	v_and_b32_e32 v2, 63, v0
	v_lshrrev_b32_e32 v3, 6, v0
	v_lshlrev_b32_e32 v235, 4, v2
	v_lshlrev_b32_e32 v237, 3, v2
	v_readfirstlane_b32 s13, v3
	v_readlane_b32 s10, v254, 0
	v_add_u32_e32 v236, 0x1000, v235
	v_add_u32_e32 v238, 0x2000, v235
	v_add_u32_e32 v239, 0x3000, v235
	v_add_u32_e32 v240, 0x0, v235
	v_add_u32_e32 v241, 0x1000, v235
	v_mov_b32_e32 v233, 0x358637bd
	v_lshrrev_b32_e32 v3, 3, v2
	v_and_b32_e32 v2, 7, v2
	v_lshlrev_b32_e32 v3, 20, v3
	v_lshl_or_b32 v242, v2, 3, v3
	v_add_u32_e32 v243, 0x800000, v242
	v_add_u32_e32 v244, 0x1000000, v242
	v_add_u32_e32 v245, 0x1800000, v242
	v_add_u32_e32 v246, 0x2000000, v242
	v_add_u32_e32 v247, 0x2800000, v242
	v_add_u32_e32 v248, 0x3000000, v242
	v_add_u32_e32 v249, 0x3800000, v242
	v_mov_b32_e32 v234, 0x800000
	s_lshl_b32 s10, s10, 2
	s_add_i32 s10, s10, s13
	s_lshl_b32 s11, s92, 2
	s_cmpk_lt_u32 s10, 0x4000
	s_cbranch_scc0 .Lad_end_p1
	v_readlane_b32 s2, v254, 33
	v_readlane_b32 s3, v254, 34
	s_nop 4
	global_load_dwordx4 v[194:197], v235, s[2:3]
	global_load_dwordx4 v[198:201], v235, s[2:3] offset:1024
	global_load_dwordx4 v[202:205], v235, s[2:3] offset:2048
	global_load_dwordx4 v[206:209], v235, s[2:3] offset:3072
	global_load_dwordx4 v[210:213], v236, s[2:3]
	global_load_dwordx4 v[214:217], v236, s[2:3] offset:1024
	global_load_dwordx4 v[218:221], v236, s[2:3] offset:2048
	global_load_dwordx4 v[222:225], v236, s[2:3] offset:3072
	v_readlane_b32 s2, v254, 25
	v_readlane_b32 s3, v254, 26
	s_lshl_b32 s13, s10, 13
	s_add_u32 s2, s2, s13
	s_addc_u32 s3, s3, 0
	s_lshr_b32 s13, s10, 11
	s_mul_i32 s13, s13, 0xc000
	s_add_u32 s4, s78, s13
	s_addc_u32 s5, s79, 0
	global_load_dwordx4 v[2:5], v235, s[2:3]
	global_load_dwordx4 v[6:9], v235, s[2:3] offset:1024
	global_load_dwordx4 v[10:13], v235, s[2:3] offset:2048
	global_load_dwordx4 v[14:17], v235, s[2:3] offset:3072
	global_load_dwordx4 v[18:21], v236, s[2:3]
	global_load_dwordx4 v[22:25], v236, s[2:3] offset:1024
	global_load_dwordx4 v[26:29], v236, s[2:3] offset:2048
	global_load_dwordx4 v[30:33], v236, s[2:3] offset:3072
	global_load_dwordx4 v[34:37], v238, s[4:5]
	global_load_dwordx4 v[38:41], v238, s[4:5] offset:1024
	global_load_dwordx4 v[42:45], v238, s[4:5] offset:2048
	global_load_dwordx4 v[46:49], v238, s[4:5] offset:3072
	global_load_dwordx4 v[50:53], v239, s[4:5]
	global_load_dwordx4 v[54:57], v239, s[4:5] offset:1024
	global_load_dwordx4 v[58:61], v239, s[4:5] offset:2048
	global_load_dwordx4 v[62:65], v239, s[4:5] offset:3072
	global_load_dwordx4 v[66:69], v240, s[4:5]
	global_load_dwordx4 v[70:73], v240, s[4:5] offset:1024
	global_load_dwordx4 v[74:77], v240, s[4:5] offset:2048
	global_load_dwordx4 v[78:81], v240, s[4:5] offset:3072
	global_load_dwordx4 v[82:85], v241, s[4:5]
	global_load_dwordx4 v[86:89], v241, s[4:5] offset:1024
	global_load_dwordx4 v[90:93], v241, s[4:5] offset:2048
	global_load_dwordx4 v[94:97], v241, s[4:5] offset:3072
.Lad_loop_p1:
	s_add_i32 s12, s10, s11
	s_cmpk_lt_u32 s12, 0x4000
	s_cbranch_scc0 .Lad_last_p1_0
	v_readlane_b32 s2, v254, 25
	v_readlane_b32 s3, v254, 26
	s_lshl_b32 s13, s12, 13
	s_add_u32 s2, s2, s13
	s_addc_u32 s3, s3, 0
	s_lshr_b32 s13, s12, 11
	s_mul_i32 s13, s13, 0xc000
	s_add_u32 s4, s78, s13
	s_addc_u32 s5, s79, 0
	global_load_dwordx4 v[98:101], v235, s[2:3]
	global_load_dwordx4 v[102:105], v235, s[2:3] offset:1024
	global_load_dwordx4 v[106:109], v235, s[2:3] offset:2048
	global_load_dwordx4 v[110:113], v235, s[2:3] offset:3072
	global_load_dwordx4 v[114:117], v236, s[2:3]
	global_load_dwordx4 v[118:121], v236, s[2:3] offset:1024
	global_load_dwordx4 v[122:125], v236, s[2:3] offset:2048
	global_load_dwordx4 v[126:129], v236, s[2:3] offset:3072
	global_load_dwordx4 v[130:133], v238, s[4:5]
	global_load_dwordx4 v[134:137], v238, s[4:5] offset:1024
	global_load_dwordx4 v[138:141], v238, s[4:5] offset:2048
	global_load_dwordx4 v[142:145], v238, s[4:5] offset:3072
	global_load_dwordx4 v[146:149], v239, s[4:5]
	global_load_dwordx4 v[150:153], v239, s[4:5] offset:1024
	global_load_dwordx4 v[154:157], v239, s[4:5] offset:2048
	global_load_dwordx4 v[158:161], v239, s[4:5] offset:3072
	global_load_dwordx4 v[162:165], v240, s[4:5]
	global_load_dwordx4 v[166:169], v240, s[4:5] offset:1024
	global_load_dwordx4 v[170:173], v240, s[4:5] offset:2048
	global_load_dwordx4 v[174:177], v240, s[4:5] offset:3072
	global_load_dwordx4 v[178:181], v241, s[4:5]
	global_load_dwordx4 v[182:185], v241, s[4:5] offset:1024
	global_load_dwordx4 v[186:189], v241, s[4:5] offset:2048
	global_load_dwordx4 v[190:193], v241, s[4:5] offset:3072
	s_waitcnt vmcnt(24)
; DEV unsigned pack2(float a, float b) { float2v v = {a, b}; return __builtin_bit_cast(unsigned, __builtin_convertvector(v, bf16x2v)); }
; DEV void ph_adaln_row(const float* xin, const float* g, const float* mod, int sh_off, int sc_off, u16* hout, int row) {
;     ...
;     ss += v[i].x * v[i].x + v[i].y * v[i].y + v[i].z * v[i].z + v[i].w * v[i].w;
;   }
;   ss = wave_sum(ss);
;   const float rstd = rsqrtf(ss * (1.f / 2048.f) + 1e-6f);
;   const float* mb = mod + (size_t)b * 12288;
; #pragma unroll
;   for (int i = 0; i < 8; ++i) {
;     int col = i * 256 + lane * 4;
;     float4 g4 = *(const float4*)(g + col);
;     float4 sc = *(const float4*)(mb + sc_off + col);
;     float4 sh = *(const float4*)(mb + sh_off + col);
;     float y0 = v[i].x * rstd * g4.x * (1.f + sc.x) + sh.x;
;     float y1 = v[i].y * rstd * g4.y * (1.f + sc.y) + sh.y;
;     float y2 = v[i].z * rstd * g4.z * (1.f + sc.z) + sh.z;
;     float y3 = v[i].w * rstd * g4.w * (1.f + sc.w) + sh.w;
;     u32x2 pk; pk[0] = pack2(y0, y1); pk[1] = pack2(y2, y3);
;     *(u32x2*)(hout + (size_t)row * 2048 + col) = pk;
	v_mul_f32_e32 v226, v2, v2
	v_mul_f32_e32 v227, v3, v3
	v_mul_f32_e32 v228, v4, v4
	v_mul_f32_e32 v229, v5, v5
	v_fmac_f32_e32 v226, v6, v6
	v_fmac_f32_e32 v227, v7, v7
	v_fmac_f32_e32 v228, v8, v8
	v_fmac_f32_e32 v229, v9, v9
	v_fmac_f32_e32 v226, v10, v10
	v_fmac_f32_e32 v227, v11, v11
	v_fmac_f32_e32 v228, v12, v12
	v_fmac_f32_e32 v229, v13, v13
	v_fmac_f32_e32 v226, v14, v14
	v_fmac_f32_e32 v227, v15, v15
	v_fmac_f32_e32 v228, v16, v16
	v_fmac_f32_e32 v229, v17, v17
	v_fmac_f32_e32 v226, v18, v18
	v_fmac_f32_e32 v227, v19, v19
	v_fmac_f32_e32 v228, v20, v20
	v_fmac_f32_e32 v229, v21, v21
	v_fmac_f32_e32 v226, v22, v22
	v_fmac_f32_e32 v227, v23, v23
	v_fmac_f32_e32 v228, v24, v24
	v_fmac_f32_e32 v229, v25, v25
	v_fmac_f32_e32 v226, v26, v26
	v_fmac_f32_e32 v227, v27, v27
	v_fmac_f32_e32 v228, v28, v28
	v_fmac_f32_e32 v229, v29, v29
	v_fmac_f32_e32 v226, v30, v30
	v_fmac_f32_e32 v227, v31, v31
	v_fmac_f32_e32 v228, v32, v32
	v_fmac_f32_e32 v229, v33, v33
	v_add_f32_e32 v226, v227, v226
	v_add_f32_e32 v228, v229, v228
	v_add_f32_e32 v226, v228, v226
	s_nop 1
	v_add_f32_dpp v226, v226, v226 quad_perm:[1,0,3,2] row_mask:0xf bank_mask:0xf bound_ctrl:1
	s_nop 1
	v_add_f32_dpp v226, v226, v226 quad_perm:[2,3,0,1] row_mask:0xf bank_mask:0xf bound_ctrl:1
	s_nop 1
	v_add_f32_dpp v226, v226, v226 row_half_mirror row_mask:0xf bank_mask:0xf bound_ctrl:1
	s_nop 1
	v_add_f32_dpp v226, v226, v226 row_mirror row_mask:0xf bank_mask:0xf bound_ctrl:1
	s_nop 1
	v_add_f32_dpp v226, v226, v226 row_bcast:15 row_mask:0xa bank_mask:0xf
	s_nop 1
	v_add_f32_dpp v226, v226, v226 row_bcast:31 row_mask:0xc bank_mask:0xf
	s_nop 0
	v_readlane_b32 s12, v226, 63
	s_nop 1
	v_mov_b32_e32 v230, s12
	v_fmamk_f32 v230, v230, 0x3a000000, v233
	v_mul_f32_e32 v231, 0x4b800000, v230
	v_cmp_lt_f32_e32 vcc, v230, v234
	s_nop 1
	v_cndmask_b32_e32 v230, v230, v231, vcc
	v_rsq_f32_e32 v230, v230
	s_nop 0
	v_mul_f32_e32 v231, 0x45800000, v230
	v_cndmask_b32_e32 v232, v230, v231, vcc
	v_mul_f32_e32 v2, v2, v232
	v_mul_f32_e32 v2, v194, v2
	v_add_f32_e32 v34, 1.0, v34
	v_fma_f32 v2, v34, v2, v66
	v_mul_f32_e32 v3, v3, v232
	v_mul_f32_e32 v3, v195, v3
	v_add_f32_e32 v35, 1.0, v35
	v_fma_f32 v3, v35, v3, v67
	v_mul_f32_e32 v4, v4, v232
	v_mul_f32_e32 v4, v196, v4
	v_add_f32_e32 v36, 1.0, v36
	v_fma_f32 v4, v36, v4, v68
	v_mul_f32_e32 v5, v5, v232
	v_mul_f32_e32 v5, v197, v5
	v_add_f32_e32 v37, 1.0, v37
	v_fma_f32 v5, v37, v5, v69
	v_mul_f32_e32 v6, v6, v232
	v_mul_f32_e32 v6, v198, v6
	v_add_f32_e32 v38, 1.0, v38
	v_fma_f32 v6, v38, v6, v70
	v_mul_f32_e32 v7, v7, v232
	v_mul_f32_e32 v7, v199, v7
	v_add_f32_e32 v39, 1.0, v39
	v_fma_f32 v7, v39, v7, v71
	v_mul_f32_e32 v8, v8, v232
	v_mul_f32_e32 v8, v200, v8
	v_add_f32_e32 v40, 1.0, v40
	v_fma_f32 v8, v40, v8, v72
	v_mul_f32_e32 v9, v9, v232
	v_mul_f32_e32 v9, v201, v9
	v_add_f32_e32 v41, 1.0, v41
	v_fma_f32 v9, v41, v9, v73
	v_mul_f32_e32 v10, v10, v232
	v_mul_f32_e32 v10, v202, v10
	v_add_f32_e32 v42, 1.0, v42
	v_fma_f32 v10, v42, v10, v74
	v_mul_f32_e32 v11, v11, v232
	v_mul_f32_e32 v11, v203, v11
	v_add_f32_e32 v43, 1.0, v43
	v_fma_f32 v11, v43, v11, v75
	v_mul_f32_e32 v12, v12, v232
	v_mul_f32_e32 v12, v204, v12
	v_add_f32_e32 v44, 1.0, v44
	v_fma_f32 v12, v44, v12, v76
	v_mul_f32_e32 v13, v13, v232
	v_mul_f32_e32 v13, v205, v13
	v_add_f32_e32 v45, 1.0, v45
	v_fma_f32 v13, v45, v13, v77
	v_mul_f32_e32 v14, v14, v232
	v_mul_f32_e32 v14, v206, v14
	v_add_f32_e32 v46, 1.0, v46
	v_fma_f32 v14, v46, v14, v78
	v_mul_f32_e32 v15, v15, v232
	v_mul_f32_e32 v15, v207, v15
	v_add_f32_e32 v47, 1.0, v47
	v_fma_f32 v15, v47, v15, v79
	v_mul_f32_e32 v16, v16, v232
	v_mul_f32_e32 v16, v208, v16
	v_add_f32_e32 v48, 1.0, v48
	v_fma_f32 v16, v48, v16, v80
	v_mul_f32_e32 v17, v17, v232
	v_mul_f32_e32 v17, v209, v17
	v_add_f32_e32 v49, 1.0, v49
	v_fma_f32 v17, v49, v17, v81
	v_mul_f32_e32 v18, v18, v232
	v_mul_f32_e32 v18, v210, v18
	v_add_f32_e32 v50, 1.0, v50
	v_fma_f32 v18, v50, v18, v82
	v_mul_f32_e32 v19, v19, v232
	v_mul_f32_e32 v19, v211, v19
	v_add_f32_e32 v51, 1.0, v51
	v_fma_f32 v19, v51, v19, v83
	v_mul_f32_e32 v20, v20, v232
	v_mul_f32_e32 v20, v212, v20
	v_add_f32_e32 v52, 1.0, v52
	v_fma_f32 v20, v52, v20, v84
	v_mul_f32_e32 v21, v21, v232
	v_mul_f32_e32 v21, v213, v21
	v_add_f32_e32 v53, 1.0, v53
	v_fma_f32 v21, v53, v21, v85
	v_mul_f32_e32 v22, v22, v232
	v_mul_f32_e32 v22, v214, v22
	v_add_f32_e32 v54, 1.0, v54
	v_fma_f32 v22, v54, v22, v86
	v_mul_f32_e32 v23, v23, v232
	v_mul_f32_e32 v23, v215, v23
	v_add_f32_e32 v55, 1.0, v55
	v_fma_f32 v23, v55, v23, v87
	v_mul_f32_e32 v24, v24, v232
	v_mul_f32_e32 v24, v216, v24
	v_add_f32_e32 v56, 1.0, v56
	v_fma_f32 v24, v56, v24, v88
	v_mul_f32_e32 v25, v25, v232
	v_mul_f32_e32 v25, v217, v25
	v_add_f32_e32 v57, 1.0, v57
	v_fma_f32 v25, v57, v25, v89
	v_mul_f32_e32 v26, v26, v232
	v_mul_f32_e32 v26, v218, v26
	v_add_f32_e32 v58, 1.0, v58
	v_fma_f32 v26, v58, v26, v90
	v_mul_f32_e32 v27, v27, v232
	v_mul_f32_e32 v27, v219, v27
	v_add_f32_e32 v59, 1.0, v59
	v_fma_f32 v27, v59, v27, v91
	v_mul_f32_e32 v28, v28, v232
	v_mul_f32_e32 v28, v220, v28
	v_add_f32_e32 v60, 1.0, v60
	v_fma_f32 v28, v60, v28, v92
	v_mul_f32_e32 v29, v29, v232
	v_mul_f32_e32 v29, v221, v29
	v_add_f32_e32 v61, 1.0, v61
	v_fma_f32 v29, v61, v29, v93
	v_mul_f32_e32 v30, v30, v232
	v_mul_f32_e32 v30, v222, v30
	v_add_f32_e32 v62, 1.0, v62
	v_fma_f32 v30, v62, v30, v94
	v_mul_f32_e32 v31, v31, v232
	v_mul_f32_e32 v31, v223, v31
	v_add_f32_e32 v63, 1.0, v63
	v_fma_f32 v31, v63, v31, v95
	v_mul_f32_e32 v32, v32, v232
	v_mul_f32_e32 v32, v224, v32
	v_add_f32_e32 v64, 1.0, v64
	v_fma_f32 v32, v64, v32, v96
	v_mul_f32_e32 v33, v33, v232
	v_mul_f32_e32 v33, v225, v33
	v_add_f32_e32 v65, 1.0, v65
	v_fma_f32 v33, v65, v33, v97
	v_cvt_pk_bf16_f32 v2, v2, v3
	v_cvt_pk_bf16_f32 v3, v4, v5
	v_cvt_pk_bf16_f32 v4, v6, v7
	v_cvt_pk_bf16_f32 v5, v8, v9
	v_cvt_pk_bf16_f32 v6, v10, v11
	v_cvt_pk_bf16_f32 v7, v12, v13
	v_cvt_pk_bf16_f32 v8, v14, v15
	v_cvt_pk_bf16_f32 v9, v16, v17
	v_cvt_pk_bf16_f32 v10, v18, v19
	v_cvt_pk_bf16_f32 v11, v20, v21
	v_cvt_pk_bf16_f32 v12, v22, v23
	v_cvt_pk_bf16_f32 v13, v24, v25
	v_cvt_pk_bf16_f32 v14, v26, v27
	v_cvt_pk_bf16_f32 v15, v28, v29
	v_cvt_pk_bf16_f32 v16, v30, v31
	v_cvt_pk_bf16_f32 v17, v32, v33
	s_lshl_b32 s13, s10, 6
	s_add_u32 s8, s80, s13
	s_addc_u32 s9, s81, 0
	global_store_dwordx2 v242, v[2:3], s[8:9]
	global_store_dwordx2 v243, v[4:5], s[8:9]
	global_store_dwordx2 v244, v[6:7], s[8:9]
	global_store_dwordx2 v245, v[8:9], s[8:9]
	global_store_dwordx2 v246, v[10:11], s[8:9]
	global_store_dwordx2 v247, v[12:13], s[8:9]
	global_store_dwordx2 v248, v[14:15], s[8:9]
	global_store_dwordx2 v249, v[16:17], s[8:9]
	s_add_i32 s10, s10, s11
	s_add_i32 s12, s10, s11
	s_cmpk_lt_u32 s12, 0x4000
	s_cbranch_scc0 .Lad_last_p1_1
; DEV void ph_adaln_row(const float* xin, const float* g, const float* mod, int sh_off, int sc_off, u16* hout, int row) {
;     ...
;   for (int i = 0; i < 8; ++i) {
;     v[i] = *(const float4*)(xr + i * 256 + lane * 4);
;     ss += v[i].x * v[i].x + v[i].y * v[i].y + v[i].z * v[i].z + v[i].w * v[i].w;
;   }
;   ss = wave_sum(ss);
;   const float rstd = rsqrtf(ss * (1.f / 2048.f) + 1e-6f);
	v_readlane_b32 s2, v254, 25
	v_readlane_b32 s3, v254, 26
	s_lshl_b32 s13, s12, 13
	s_add_u32 s2, s2, s13
	s_addc_u32 s3, s3, 0
	s_lshr_b32 s13, s12, 11
	s_mul_i32 s13, s13, 0xc000
	s_add_u32 s4, s78, s13
	s_addc_u32 s5, s79, 0
	global_load_dwordx4 v[2:5], v235, s[2:3]
	global_load_dwordx4 v[6:9], v235, s[2:3] offset:1024
	global_load_dwordx4 v[10:13], v235, s[2:3] offset:2048
	global_load_dwordx4 v[14:17], v235, s[2:3] offset:3072
	global_load_dwordx4 v[18:21], v236, s[2:3]
	global_load_dwordx4 v[22:25], v236, s[2:3] offset:1024
	global_load_dwordx4 v[26:29], v236, s[2:3] offset:2048
	global_load_dwordx4 v[30:33], v236, s[2:3] offset:3072
	global_load_dwordx4 v[34:37], v238, s[4:5]
	global_load_dwordx4 v[38:41], v238, s[4:5] offset:1024
	global_load_dwordx4 v[42:45], v238, s[4:5] offset:2048
	global_load_dwordx4 v[46:49], v238, s[4:5] offset:3072
	global_load_dwordx4 v[50:53], v239, s[4:5]
	global_load_dwordx4 v[54:57], v239, s[4:5] offset:1024
	global_load_dwordx4 v[58:61], v239, s[4:5] offset:2048
	global_load_dwordx4 v[62:65], v239, s[4:5] offset:3072
	global_load_dwordx4 v[66:69], v240, s[4:5]
	global_load_dwordx4 v[70:73], v240, s[4:5] offset:1024
	global_load_dwordx4 v[74:77], v240, s[4:5] offset:2048
	global_load_dwordx4 v[78:81], v240, s[4:5] offset:3072
	global_load_dwordx4 v[82:85], v241, s[4:5]
	global_load_dwordx4 v[86:89], v241, s[4:5] offset:1024
	global_load_dwordx4 v[90:93], v241, s[4:5] offset:2048
	global_load_dwordx4 v[94:97], v241, s[4:5] offset:3072
	s_waitcnt vmcnt(24)
	v_mul_f32_e32 v226, v98, v98
	v_mul_f32_e32 v227, v99, v99
	v_mul_f32_e32 v228, v100, v100
	v_mul_f32_e32 v229, v101, v101
	v_fmac_f32_e32 v226, v102, v102
	v_fmac_f32_e32 v227, v103, v103
	v_fmac_f32_e32 v228, v104, v104
	v_fmac_f32_e32 v229, v105, v105
	v_fmac_f32_e32 v226, v106, v106
	v_fmac_f32_e32 v227, v107, v107
	v_fmac_f32_e32 v228, v108, v108
	v_fmac_f32_e32 v229, v109, v109
	v_fmac_f32_e32 v226, v110, v110
	v_fmac_f32_e32 v227, v111, v111
	v_fmac_f32_e32 v228, v112, v112
	v_fmac_f32_e32 v229, v113, v113
	v_fmac_f32_e32 v226, v114, v114
	v_fmac_f32_e32 v227, v115, v115
	v_fmac_f32_e32 v228, v116, v116
	v_fmac_f32_e32 v229, v117, v117
	v_fmac_f32_e32 v226, v118, v118
	v_fmac_f32_e32 v227, v119, v119
	v_fmac_f32_e32 v228, v120, v120
	v_fmac_f32_e32 v229, v121, v121
	v_fmac_f32_e32 v226, v122, v122
	v_fmac_f32_e32 v227, v123, v123
	v_fmac_f32_e32 v228, v124, v124
	v_fmac_f32_e32 v229, v125, v125
	v_fmac_f32_e32 v226, v126, v126
	v_fmac_f32_e32 v227, v127, v127
	v_fmac_f32_e32 v228, v128, v128
	v_fmac_f32_e32 v229, v129, v129
	v_add_f32_e32 v226, v227, v226
	v_add_f32_e32 v228, v229, v228
	v_add_f32_e32 v226, v228, v226
	s_nop 1
	v_add_f32_dpp v226, v226, v226 quad_perm:[1,0,3,2] row_mask:0xf bank_mask:0xf bound_ctrl:1
	s_nop 1
	v_add_f32_dpp v226, v226, v226 quad_perm:[2,3,0,1] row_mask:0xf bank_mask:0xf bound_ctrl:1
	s_nop 1
	v_add_f32_dpp v226, v226, v226 row_half_mirror row_mask:0xf bank_mask:0xf bound_ctrl:1
	s_nop 1
	v_add_f32_dpp v226, v226, v226 row_mirror row_mask:0xf bank_mask:0xf bound_ctrl:1
	s_nop 1
	v_add_f32_dpp v226, v226, v226 row_bcast:15 row_mask:0xa bank_mask:0xf
	s_nop 1
	v_add_f32_dpp v226, v226, v226 row_bcast:31 row_mask:0xc bank_mask:0xf
	s_nop 0
	v_readlane_b32 s12, v226, 63
	s_nop 1
	v_mov_b32_e32 v230, s12
	v_fmamk_f32 v230, v230, 0x3a000000, v233
	v_mul_f32_e32 v231, 0x4b800000, v230
	v_cmp_lt_f32_e32 vcc, v230, v234
	s_nop 1
	v_cndmask_b32_e32 v230, v230, v231, vcc
	v_rsq_f32_e32 v230, v230
	s_nop 0
	v_mul_f32_e32 v231, 0x45800000, v230
	v_cndmask_b32_e32 v232, v230, v231, vcc
	v_mul_f32_e32 v98, v98, v232
	v_mul_f32_e32 v98, v194, v98
	v_add_f32_e32 v130, 1.0, v130
	v_fma_f32 v98, v130, v98, v162
	v_mul_f32_e32 v99, v99, v232
	v_mul_f32_e32 v99, v195, v99
	v_add_f32_e32 v131, 1.0, v131
	v_fma_f32 v99, v131, v99, v163
	v_mul_f32_e32 v100, v100, v232
	v_mul_f32_e32 v100, v196, v100
	v_add_f32_e32 v132, 1.0, v132
	v_fma_f32 v100, v132, v100, v164
	v_mul_f32_e32 v101, v101, v232
	v_mul_f32_e32 v101, v197, v101
	v_add_f32_e32 v133, 1.0, v133
	v_fma_f32 v101, v133, v101, v165
	v_mul_f32_e32 v102, v102, v232
	v_mul_f32_e32 v102, v198, v102
	v_add_f32_e32 v134, 1.0, v134
	v_fma_f32 v102, v134, v102, v166
	v_mul_f32_e32 v103, v103, v232
	v_mul_f32_e32 v103, v199, v103
	v_add_f32_e32 v135, 1.0, v135
	v_fma_f32 v103, v135, v103, v167
	v_mul_f32_e32 v104, v104, v232
	v_mul_f32_e32 v104, v200, v104
	v_add_f32_e32 v136, 1.0, v136
	v_fma_f32 v104, v136, v104, v168
	v_mul_f32_e32 v105, v105, v232
	v_mul_f32_e32 v105, v201, v105
	v_add_f32_e32 v137, 1.0, v137
	v_fma_f32 v105, v137, v105, v169
	v_mul_f32_e32 v106, v106, v232
	v_mul_f32_e32 v106, v202, v106
	v_add_f32_e32 v138, 1.0, v138
	v_fma_f32 v106, v138, v106, v170
	v_mul_f32_e32 v107, v107, v232
	v_mul_f32_e32 v107, v203, v107
	v_add_f32_e32 v139, 1.0, v139
	v_fma_f32 v107, v139, v107, v171
	v_mul_f32_e32 v108, v108, v232
	v_mul_f32_e32 v108, v204, v108
	v_add_f32_e32 v140, 1.0, v140
	v_fma_f32 v108, v140, v108, v172
	v_mul_f32_e32 v109, v109, v232
	v_mul_f32_e32 v109, v205, v109
	v_add_f32_e32 v141, 1.0, v141
	v_fma_f32 v109, v141, v109, v173
	v_mul_f32_e32 v110, v110, v232
	v_mul_f32_e32 v110, v206, v110
	v_add_f32_e32 v142, 1.0, v142
	v_fma_f32 v110, v142, v110, v174
	v_mul_f32_e32 v111, v111, v232
	v_mul_f32_e32 v111, v207, v111
	v_add_f32_e32 v143, 1.0, v143
	v_fma_f32 v111, v143, v111, v175
	v_mul_f32_e32 v112, v112, v232
	v_mul_f32_e32 v112, v208, v112
	v_add_f32_e32 v144, 1.0, v144
	v_fma_f32 v112, v144, v112, v176
	v_mul_f32_e32 v113, v113, v232
	v_mul_f32_e32 v113, v209, v113
	v_add_f32_e32 v145, 1.0, v145
	v_fma_f32 v113, v145, v113, v177
	v_mul_f32_e32 v114, v114, v232
; DEV unsigned pack2(float a, float b) { float2v v = {a, b}; return __builtin_bit_cast(unsigned, __builtin_convertvector(v, bf16x2v)); }
; DEV void ph_adaln_row(const float* xin, const float* g, const float* mod, int sh_off, int sc_off, u16* hout, int row) {
;     ...
;     v[i] = *(const float4*)(xr + i * 256 + lane * 4);
;     ss += v[i].x * v[i].x + v[i].y * v[i].y + v[i].z * v[i].z + v[i].w * v[i].w;
;   }
;   ss = wave_sum(ss);
;   const float rstd = rsqrtf(ss * (1.f / 2048.f) + 1e-6f);
;     ...
;     float4 sc = *(const float4*)(mb + sc_off + col);
;     float4 sh = *(const float4*)(mb + sh_off + col);
;     float y0 = v[i].x * rstd * g4.x * (1.f + sc.x) + sh.x;
;     float y1 = v[i].y * rstd * g4.y * (1.f + sc.y) + sh.y;
;     float y2 = v[i].z * rstd * g4.z * (1.f + sc.z) + sh.z;
;     float y3 = v[i].w * rstd * g4.w * (1.f + sc.w) + sh.w;
;     u32x2 pk; pk[0] = pack2(y0, y1); pk[1] = pack2(y2, y3);
;     *(u32x2*)(hout + (size_t)row * 2048 + col) = pk;
	v_mul_f32_e32 v114, v210, v114
	v_add_f32_e32 v146, 1.0, v146
	v_fma_f32 v114, v146, v114, v178
	v_mul_f32_e32 v115, v115, v232
	v_mul_f32_e32 v115, v211, v115
	v_add_f32_e32 v147, 1.0, v147
	v_fma_f32 v115, v147, v115, v179
	v_mul_f32_e32 v116, v116, v232
	v_mul_f32_e32 v116, v212, v116
	v_add_f32_e32 v148, 1.0, v148
	v_fma_f32 v116, v148, v116, v180
	v_mul_f32_e32 v117, v117, v232
	v_mul_f32_e32 v117, v213, v117
	v_add_f32_e32 v149, 1.0, v149
	v_fma_f32 v117, v149, v117, v181
	v_mul_f32_e32 v118, v118, v232
	v_mul_f32_e32 v118, v214, v118
	v_add_f32_e32 v150, 1.0, v150
	v_fma_f32 v118, v150, v118, v182
	v_mul_f32_e32 v119, v119, v232
	v_mul_f32_e32 v119, v215, v119
	v_add_f32_e32 v151, 1.0, v151
	v_fma_f32 v119, v151, v119, v183
	v_mul_f32_e32 v120, v120, v232
	v_mul_f32_e32 v120, v216, v120
	v_add_f32_e32 v152, 1.0, v152
	v_fma_f32 v120, v152, v120, v184
	v_mul_f32_e32 v121, v121, v232
	v_mul_f32_e32 v121, v217, v121
	v_add_f32_e32 v153, 1.0, v153
	v_fma_f32 v121, v153, v121, v185
	v_mul_f32_e32 v122, v122, v232
	v_mul_f32_e32 v122, v218, v122
	v_add_f32_e32 v154, 1.0, v154
	v_fma_f32 v122, v154, v122, v186
	v_mul_f32_e32 v123, v123, v232
	v_mul_f32_e32 v123, v219, v123
	v_add_f32_e32 v155, 1.0, v155
	v_fma_f32 v123, v155, v123, v187
	v_mul_f32_e32 v124, v124, v232
	v_mul_f32_e32 v124, v220, v124
	v_add_f32_e32 v156, 1.0, v156
	v_fma_f32 v124, v156, v124, v188
	v_mul_f32_e32 v125, v125, v232
	v_mul_f32_e32 v125, v221, v125
	v_add_f32_e32 v157, 1.0, v157
	v_fma_f32 v125, v157, v125, v189
	v_mul_f32_e32 v126, v126, v232
	v_mul_f32_e32 v126, v222, v126
	v_add_f32_e32 v158, 1.0, v158
	v_fma_f32 v126, v158, v126, v190
	v_mul_f32_e32 v127, v127, v232
	v_mul_f32_e32 v127, v223, v127
	v_add_f32_e32 v159, 1.0, v159
	v_fma_f32 v127, v159, v127, v191
	v_mul_f32_e32 v128, v128, v232
	v_mul_f32_e32 v128, v224, v128
	v_add_f32_e32 v160, 1.0, v160
	v_fma_f32 v128, v160, v128, v192
	v_mul_f32_e32 v129, v129, v232
	v_mul_f32_e32 v129, v225, v129
	v_add_f32_e32 v161, 1.0, v161
	v_fma_f32 v129, v161, v129, v193
	v_cvt_pk_bf16_f32 v98, v98, v99
	v_cvt_pk_bf16_f32 v99, v100, v101
	v_cvt_pk_bf16_f32 v100, v102, v103
	v_cvt_pk_bf16_f32 v101, v104, v105
	v_cvt_pk_bf16_f32 v102, v106, v107
	v_cvt_pk_bf16_f32 v103, v108, v109
	v_cvt_pk_bf16_f32 v104, v110, v111
	v_cvt_pk_bf16_f32 v105, v112, v113
	v_cvt_pk_bf16_f32 v106, v114, v115
	v_cvt_pk_bf16_f32 v107, v116, v117
	v_cvt_pk_bf16_f32 v108, v118, v119
	v_cvt_pk_bf16_f32 v109, v120, v121
	v_cvt_pk_bf16_f32 v110, v122, v123
	v_cvt_pk_bf16_f32 v111, v124, v125
	v_cvt_pk_bf16_f32 v112, v126, v127
	v_cvt_pk_bf16_f32 v113, v128, v129
	s_lshl_b32 s13, s10, 6
	s_add_u32 s8, s80, s13
	s_addc_u32 s9, s81, 0
	global_store_dwordx2 v242, v[98:99], s[8:9]
	global_store_dwordx2 v243, v[100:101], s[8:9]
	global_store_dwordx2 v244, v[102:103], s[8:9]
	global_store_dwordx2 v245, v[104:105], s[8:9]
	global_store_dwordx2 v246, v[106:107], s[8:9]
	global_store_dwordx2 v247, v[108:109], s[8:9]
	global_store_dwordx2 v248, v[110:111], s[8:9]
	global_store_dwordx2 v249, v[112:113], s[8:9]
	s_add_i32 s10, s10, s11
	s_branch .Lad_loop_p1
.Lad_last_p1_0:
	s_waitcnt vmcnt(0)
	v_mul_f32_e32 v226, v2, v2
	v_mul_f32_e32 v227, v3, v3
	v_mul_f32_e32 v228, v4, v4
	v_mul_f32_e32 v229, v5, v5
	v_fmac_f32_e32 v226, v6, v6
	v_fmac_f32_e32 v227, v7, v7
	v_fmac_f32_e32 v228, v8, v8
	v_fmac_f32_e32 v229, v9, v9
	v_fmac_f32_e32 v226, v10, v10
	v_fmac_f32_e32 v227, v11, v11
	v_fmac_f32_e32 v228, v12, v12
	v_fmac_f32_e32 v229, v13, v13
	v_fmac_f32_e32 v226, v14, v14
	v_fmac_f32_e32 v227, v15, v15
	v_fmac_f32_e32 v228, v16, v16
	v_fmac_f32_e32 v229, v17, v17
	v_fmac_f32_e32 v226, v18, v18
	v_fmac_f32_e32 v227, v19, v19
	v_fmac_f32_e32 v228, v20, v20
	v_fmac_f32_e32 v229, v21, v21
	v_fmac_f32_e32 v226, v22, v22
	v_fmac_f32_e32 v227, v23, v23
	v_fmac_f32_e32 v228, v24, v24
	v_fmac_f32_e32 v229, v25, v25
	v_fmac_f32_e32 v226, v26, v26
	v_fmac_f32_e32 v227, v27, v27
	v_fmac_f32_e32 v228, v28, v28
	v_fmac_f32_e32 v229, v29, v29
	v_fmac_f32_e32 v226, v30, v30
	v_fmac_f32_e32 v227, v31, v31
	v_fmac_f32_e32 v228, v32, v32
	v_fmac_f32_e32 v229, v33, v33
	v_add_f32_e32 v226, v227, v226
	v_add_f32_e32 v228, v229, v228
	v_add_f32_e32 v226, v228, v226
	s_nop 1
	v_add_f32_dpp v226, v226, v226 quad_perm:[1,0,3,2] row_mask:0xf bank_mask:0xf bound_ctrl:1
	s_nop 1
	v_add_f32_dpp v226, v226, v226 quad_perm:[2,3,0,1] row_mask:0xf bank_mask:0xf bound_ctrl:1
	s_nop 1
	v_add_f32_dpp v226, v226, v226 row_half_mirror row_mask:0xf bank_mask:0xf bound_ctrl:1
	s_nop 1
	v_add_f32_dpp v226, v226, v226 row_mirror row_mask:0xf bank_mask:0xf bound_ctrl:1
	s_nop 1
	v_add_f32_dpp v226, v226, v226 row_bcast:15 row_mask:0xa bank_mask:0xf
	s_nop 1
	v_add_f32_dpp v226, v226, v226 row_bcast:31 row_mask:0xc bank_mask:0xf
	s_nop 0
	v_readlane_b32 s12, v226, 63
	s_nop 1
	v_mov_b32_e32 v230, s12
	v_fmamk_f32 v230, v230, 0x3a000000, v233
	v_mul_f32_e32 v231, 0x4b800000, v230
	v_cmp_lt_f32_e32 vcc, v230, v234
	s_nop 1
	v_cndmask_b32_e32 v230, v230, v231, vcc
	v_rsq_f32_e32 v230, v230
	s_nop 0
	v_mul_f32_e32 v231, 0x45800000, v230
	v_cndmask_b32_e32 v232, v230, v231, vcc
	v_mul_f32_e32 v2, v2, v232
	v_mul_f32_e32 v2, v194, v2
	v_add_f32_e32 v34, 1.0, v34
	v_fma_f32 v2, v34, v2, v66
	v_mul_f32_e32 v3, v3, v232
	v_mul_f32_e32 v3, v195, v3
	v_add_f32_e32 v35, 1.0, v35
	v_fma_f32 v3, v35, v3, v67
	v_mul_f32_e32 v4, v4, v232
	v_mul_f32_e32 v4, v196, v4
	v_add_f32_e32 v36, 1.0, v36
	v_fma_f32 v4, v36, v4, v68
	v_mul_f32_e32 v5, v5, v232
	v_mul_f32_e32 v5, v197, v5
	v_add_f32_e32 v37, 1.0, v37
	v_fma_f32 v5, v37, v5, v69
	v_mul_f32_e32 v6, v6, v232
	v_mul_f32_e32 v6, v198, v6
	v_add_f32_e32 v38, 1.0, v38
; DEV unsigned pack2(float a, float b) { float2v v = {a, b}; return __builtin_bit_cast(unsigned, __builtin_convertvector(v, bf16x2v)); }
; DEV void ph_adaln_row(const float* xin, const float* g, const float* mod, int sh_off, int sc_off, u16* hout, int row) {
;     ...
;     v[i] = *(const float4*)(xr + i * 256 + lane * 4);
;     ss += v[i].x * v[i].x + v[i].y * v[i].y + v[i].z * v[i].z + v[i].w * v[i].w;
;   }
;   ss = wave_sum(ss);
;     ...
;     float4 sc = *(const float4*)(mb + sc_off + col);
;     float4 sh = *(const float4*)(mb + sh_off + col);
;     float y0 = v[i].x * rstd * g4.x * (1.f + sc.x) + sh.x;
;     float y1 = v[i].y * rstd * g4.y * (1.f + sc.y) + sh.y;
;     float y2 = v[i].z * rstd * g4.z * (1.f + sc.z) + sh.z;
;     float y3 = v[i].w * rstd * g4.w * (1.f + sc.w) + sh.w;
;     u32x2 pk; pk[0] = pack2(y0, y1); pk[1] = pack2(y2, y3);
;     *(u32x2*)(hout + (size_t)row * 2048 + col) = pk;
	v_fma_f32 v6, v38, v6, v70
	v_mul_f32_e32 v7, v7, v232
	v_mul_f32_e32 v7, v199, v7
	v_add_f32_e32 v39, 1.0, v39
	v_fma_f32 v7, v39, v7, v71
	v_mul_f32_e32 v8, v8, v232
	v_mul_f32_e32 v8, v200, v8
	v_add_f32_e32 v40, 1.0, v40
	v_fma_f32 v8, v40, v8, v72
	v_mul_f32_e32 v9, v9, v232
	v_mul_f32_e32 v9, v201, v9
	v_add_f32_e32 v41, 1.0, v41
	v_fma_f32 v9, v41, v9, v73
	v_mul_f32_e32 v10, v10, v232
	v_mul_f32_e32 v10, v202, v10
	v_add_f32_e32 v42, 1.0, v42
	v_fma_f32 v10, v42, v10, v74
	v_mul_f32_e32 v11, v11, v232
	v_mul_f32_e32 v11, v203, v11
	v_add_f32_e32 v43, 1.0, v43
	v_fma_f32 v11, v43, v11, v75
	v_mul_f32_e32 v12, v12, v232
	v_mul_f32_e32 v12, v204, v12
	v_add_f32_e32 v44, 1.0, v44
	v_fma_f32 v12, v44, v12, v76
	v_mul_f32_e32 v13, v13, v232
	v_mul_f32_e32 v13, v205, v13
	v_add_f32_e32 v45, 1.0, v45
	v_fma_f32 v13, v45, v13, v77
	v_mul_f32_e32 v14, v14, v232
	v_mul_f32_e32 v14, v206, v14
	v_add_f32_e32 v46, 1.0, v46
	v_fma_f32 v14, v46, v14, v78
	v_mul_f32_e32 v15, v15, v232
	v_mul_f32_e32 v15, v207, v15
	v_add_f32_e32 v47, 1.0, v47
	v_fma_f32 v15, v47, v15, v79
	v_mul_f32_e32 v16, v16, v232
	v_mul_f32_e32 v16, v208, v16
	v_add_f32_e32 v48, 1.0, v48
	v_fma_f32 v16, v48, v16, v80
	v_mul_f32_e32 v17, v17, v232
	v_mul_f32_e32 v17, v209, v17
	v_add_f32_e32 v49, 1.0, v49
	v_fma_f32 v17, v49, v17, v81
	v_mul_f32_e32 v18, v18, v232
	v_mul_f32_e32 v18, v210, v18
	v_add_f32_e32 v50, 1.0, v50
	v_fma_f32 v18, v50, v18, v82
	v_mul_f32_e32 v19, v19, v232
	v_mul_f32_e32 v19, v211, v19
	v_add_f32_e32 v51, 1.0, v51
	v_fma_f32 v19, v51, v19, v83
	v_mul_f32_e32 v20, v20, v232
	v_mul_f32_e32 v20, v212, v20
	v_add_f32_e32 v52, 1.0, v52
	v_fma_f32 v20, v52, v20, v84
	v_mul_f32_e32 v21, v21, v232
	v_mul_f32_e32 v21, v213, v21
	v_add_f32_e32 v53, 1.0, v53
	v_fma_f32 v21, v53, v21, v85
	v_mul_f32_e32 v22, v22, v232
	v_mul_f32_e32 v22, v214, v22
	v_add_f32_e32 v54, 1.0, v54
	v_fma_f32 v22, v54, v22, v86
	v_mul_f32_e32 v23, v23, v232
	v_mul_f32_e32 v23, v215, v23
	v_add_f32_e32 v55, 1.0, v55
	v_fma_f32 v23, v55, v23, v87
	v_mul_f32_e32 v24, v24, v232
	v_mul_f32_e32 v24, v216, v24
	v_add_f32_e32 v56, 1.0, v56
	v_fma_f32 v24, v56, v24, v88
	v_mul_f32_e32 v25, v25, v232
	v_mul_f32_e32 v25, v217, v25
	v_add_f32_e32 v57, 1.0, v57
	v_fma_f32 v25, v57, v25, v89
	v_mul_f32_e32 v26, v26, v232
	v_mul_f32_e32 v26, v218, v26
	v_add_f32_e32 v58, 1.0, v58
	v_fma_f32 v26, v58, v26, v90
	v_mul_f32_e32 v27, v27, v232
	v_mul_f32_e32 v27, v219, v27
	v_add_f32_e32 v59, 1.0, v59
	v_fma_f32 v27, v59, v27, v91
	v_mul_f32_e32 v28, v28, v232
	v_mul_f32_e32 v28, v220, v28
	v_add_f32_e32 v60, 1.0, v60
	v_fma_f32 v28, v60, v28, v92
	v_mul_f32_e32 v29, v29, v232
	v_mul_f32_e32 v29, v221, v29
	v_add_f32_e32 v61, 1.0, v61
	v_fma_f32 v29, v61, v29, v93
	v_mul_f32_e32 v30, v30, v232
	v_mul_f32_e32 v30, v222, v30
	v_add_f32_e32 v62, 1.0, v62
	v_fma_f32 v30, v62, v30, v94
	v_mul_f32_e32 v31, v31, v232
	v_mul_f32_e32 v31, v223, v31
	v_add_f32_e32 v63, 1.0, v63
	v_fma_f32 v31, v63, v31, v95
	v_mul_f32_e32 v32, v32, v232
	v_mul_f32_e32 v32, v224, v32
	v_add_f32_e32 v64, 1.0, v64
	v_fma_f32 v32, v64, v32, v96
	v_mul_f32_e32 v33, v33, v232
	v_mul_f32_e32 v33, v225, v33
	v_add_f32_e32 v65, 1.0, v65
	v_fma_f32 v33, v65, v33, v97
	v_cvt_pk_bf16_f32 v2, v2, v3
	v_cvt_pk_bf16_f32 v3, v4, v5
	v_cvt_pk_bf16_f32 v4, v6, v7
	v_cvt_pk_bf16_f32 v5, v8, v9
	v_cvt_pk_bf16_f32 v6, v10, v11
	v_cvt_pk_bf16_f32 v7, v12, v13
	v_cvt_pk_bf16_f32 v8, v14, v15
	v_cvt_pk_bf16_f32 v9, v16, v17
	v_cvt_pk_bf16_f32 v10, v18, v19
	v_cvt_pk_bf16_f32 v11, v20, v21
	v_cvt_pk_bf16_f32 v12, v22, v23
	v_cvt_pk_bf16_f32 v13, v24, v25
	v_cvt_pk_bf16_f32 v14, v26, v27
	v_cvt_pk_bf16_f32 v15, v28, v29
	v_cvt_pk_bf16_f32 v16, v30, v31
	v_cvt_pk_bf16_f32 v17, v32, v33
	s_lshl_b32 s13, s10, 6
	s_add_u32 s8, s80, s13
	s_addc_u32 s9, s81, 0
	global_store_dwordx2 v242, v[2:3], s[8:9]
	global_store_dwordx2 v243, v[4:5], s[8:9]
	global_store_dwordx2 v244, v[6:7], s[8:9]
	global_store_dwordx2 v245, v[8:9], s[8:9]
	global_store_dwordx2 v246, v[10:11], s[8:9]
	global_store_dwordx2 v247, v[12:13], s[8:9]
	global_store_dwordx2 v248, v[14:15], s[8:9]
	global_store_dwordx2 v249, v[16:17], s[8:9]
	s_branch .Lad_end_p1
.Lad_last_p1_1:
	s_waitcnt vmcnt(0)
	v_mul_f32_e32 v226, v98, v98
	v_mul_f32_e32 v227, v99, v99
	v_mul_f32_e32 v228, v100, v100
	v_mul_f32_e32 v229, v101, v101
	v_fmac_f32_e32 v226, v102, v102
	v_fmac_f32_e32 v227, v103, v103
	v_fmac_f32_e32 v228, v104, v104
	v_fmac_f32_e32 v229, v105, v105
	v_fmac_f32_e32 v226, v106, v106
	v_fmac_f32_e32 v227, v107, v107
	v_fmac_f32_e32 v228, v108, v108
	v_fmac_f32_e32 v229, v109, v109
	v_fmac_f32_e32 v226, v110, v110
	v_fmac_f32_e32 v227, v111, v111
	v_fmac_f32_e32 v228, v112, v112
	v_fmac_f32_e32 v229, v113, v113
	v_fmac_f32_e32 v226, v114, v114
	v_fmac_f32_e32 v227, v115, v115
	v_fmac_f32_e32 v228, v116, v116
	v_fmac_f32_e32 v229, v117, v117
	v_fmac_f32_e32 v226, v118, v118
	v_fmac_f32_e32 v227, v119, v119
	v_fmac_f32_e32 v228, v120, v120
	v_fmac_f32_e32 v229, v121, v121
	v_fmac_f32_e32 v226, v122, v122
	v_fmac_f32_e32 v227, v123, v123
	v_fmac_f32_e32 v228, v124, v124
	v_fmac_f32_e32 v229, v125, v125
	v_fmac_f32_e32 v226, v126, v126
	v_fmac_f32_e32 v227, v127, v127
	v_fmac_f32_e32 v228, v128, v128
	v_fmac_f32_e32 v229, v129, v129
	v_add_f32_e32 v226, v227, v226
	v_add_f32_e32 v228, v229, v228
	v_add_f32_e32 v226, v228, v226
	s_nop 1
	v_add_f32_dpp v226, v226, v226 quad_perm:[1,0,3,2] row_mask:0xf bank_mask:0xf bound_ctrl:1
	s_nop 1
	v_add_f32_dpp v226, v226, v226 quad_perm:[2,3,0,1] row_mask:0xf bank_mask:0xf bound_ctrl:1
	s_nop 1
	v_add_f32_dpp v226, v226, v226 row_half_mirror row_mask:0xf bank_mask:0xf bound_ctrl:1
; DEV unsigned pack2(float a, float b) { float2v v = {a, b}; return __builtin_bit_cast(unsigned, __builtin_convertvector(v, bf16x2v)); }
; DEV void ph_adaln_row(const float* xin, const float* g, const float* mod, int sh_off, int sc_off, u16* hout, int row) {
;     ...
;   ss = wave_sum(ss);
;   const float rstd = rsqrtf(ss * (1.f / 2048.f) + 1e-6f);
;   const float* mb = mod + (size_t)b * 12288;
; #pragma unroll
;   for (int i = 0; i < 8; ++i) {
;     int col = i * 256 + lane * 4;
;     float4 g4 = *(const float4*)(g + col);
;     float4 sc = *(const float4*)(mb + sc_off + col);
;     float4 sh = *(const float4*)(mb + sh_off + col);
;     float y0 = v[i].x * rstd * g4.x * (1.f + sc.x) + sh.x;
;     float y1 = v[i].y * rstd * g4.y * (1.f + sc.y) + sh.y;
;     float y2 = v[i].z * rstd * g4.z * (1.f + sc.z) + sh.z;
;     float y3 = v[i].w * rstd * g4.w * (1.f + sc.w) + sh.w;
;     u32x2 pk; pk[0] = pack2(y0, y1); pk[1] = pack2(y2, y3);
;     *(u32x2*)(hout + (size_t)row * 2048 + col) = pk;
	s_nop 1
	v_add_f32_dpp v226, v226, v226 row_mirror row_mask:0xf bank_mask:0xf bound_ctrl:1
	s_nop 1
	v_add_f32_dpp v226, v226, v226 row_bcast:15 row_mask:0xa bank_mask:0xf
	s_nop 1
	v_add_f32_dpp v226, v226, v226 row_bcast:31 row_mask:0xc bank_mask:0xf
	s_nop 0
	v_readlane_b32 s12, v226, 63
	s_nop 1
	v_mov_b32_e32 v230, s12
	v_fmamk_f32 v230, v230, 0x3a000000, v233
	v_mul_f32_e32 v231, 0x4b800000, v230
	v_cmp_lt_f32_e32 vcc, v230, v234
	s_nop 1
	v_cndmask_b32_e32 v230, v230, v231, vcc
	v_rsq_f32_e32 v230, v230
	s_nop 0
	v_mul_f32_e32 v231, 0x45800000, v230
	v_cndmask_b32_e32 v232, v230, v231, vcc
	v_mul_f32_e32 v98, v98, v232
	v_mul_f32_e32 v98, v194, v98
	v_add_f32_e32 v130, 1.0, v130
	v_fma_f32 v98, v130, v98, v162
	v_mul_f32_e32 v99, v99, v232
	v_mul_f32_e32 v99, v195, v99
	v_add_f32_e32 v131, 1.0, v131
	v_fma_f32 v99, v131, v99, v163
	v_mul_f32_e32 v100, v100, v232
	v_mul_f32_e32 v100, v196, v100
	v_add_f32_e32 v132, 1.0, v132
	v_fma_f32 v100, v132, v100, v164
	v_mul_f32_e32 v101, v101, v232
	v_mul_f32_e32 v101, v197, v101
	v_add_f32_e32 v133, 1.0, v133
	v_fma_f32 v101, v133, v101, v165
	v_mul_f32_e32 v102, v102, v232
	v_mul_f32_e32 v102, v198, v102
	v_add_f32_e32 v134, 1.0, v134
	v_fma_f32 v102, v134, v102, v166
	v_mul_f32_e32 v103, v103, v232
	v_mul_f32_e32 v103, v199, v103
	v_add_f32_e32 v135, 1.0, v135
	v_fma_f32 v103, v135, v103, v167
	v_mul_f32_e32 v104, v104, v232
	v_mul_f32_e32 v104, v200, v104
	v_add_f32_e32 v136, 1.0, v136
	v_fma_f32 v104, v136, v104, v168
	v_mul_f32_e32 v105, v105, v232
	v_mul_f32_e32 v105, v201, v105
	v_add_f32_e32 v137, 1.0, v137
	v_fma_f32 v105, v137, v105, v169
	v_mul_f32_e32 v106, v106, v232
	v_mul_f32_e32 v106, v202, v106
	v_add_f32_e32 v138, 1.0, v138
	v_fma_f32 v106, v138, v106, v170
	v_mul_f32_e32 v107, v107, v232
	v_mul_f32_e32 v107, v203, v107
	v_add_f32_e32 v139, 1.0, v139
	v_fma_f32 v107, v139, v107, v171
	v_mul_f32_e32 v108, v108, v232
	v_mul_f32_e32 v108, v204, v108
	v_add_f32_e32 v140, 1.0, v140
	v_fma_f32 v108, v140, v108, v172
	v_mul_f32_e32 v109, v109, v232
	v_mul_f32_e32 v109, v205, v109
	v_add_f32_e32 v141, 1.0, v141
	v_fma_f32 v109, v141, v109, v173
	v_mul_f32_e32 v110, v110, v232
	v_mul_f32_e32 v110, v206, v110
	v_add_f32_e32 v142, 1.0, v142
	v_fma_f32 v110, v142, v110, v174
	v_mul_f32_e32 v111, v111, v232
	v_mul_f32_e32 v111, v207, v111
	v_add_f32_e32 v143, 1.0, v143
	v_fma_f32 v111, v143, v111, v175
	v_mul_f32_e32 v112, v112, v232
	v_mul_f32_e32 v112, v208, v112
	v_add_f32_e32 v144, 1.0, v144
	v_fma_f32 v112, v144, v112, v176
	v_mul_f32_e32 v113, v113, v232
	v_mul_f32_e32 v113, v209, v113
	v_add_f32_e32 v145, 1.0, v145
	v_fma_f32 v113, v145, v113, v177
	v_mul_f32_e32 v114, v114, v232
	v_mul_f32_e32 v114, v210, v114
	v_add_f32_e32 v146, 1.0, v146
	v_fma_f32 v114, v146, v114, v178
	v_mul_f32_e32 v115, v115, v232
	v_mul_f32_e32 v115, v211, v115
	v_add_f32_e32 v147, 1.0, v147
	v_fma_f32 v115, v147, v115, v179
	v_mul_f32_e32 v116, v116, v232
	v_mul_f32_e32 v116, v212, v116
	v_add_f32_e32 v148, 1.0, v148
	v_fma_f32 v116, v148, v116, v180
	v_mul_f32_e32 v117, v117, v232
	v_mul_f32_e32 v117, v213, v117
	v_add_f32_e32 v149, 1.0, v149
	v_fma_f32 v117, v149, v117, v181
	v_mul_f32_e32 v118, v118, v232
	v_mul_f32_e32 v118, v214, v118
	v_add_f32_e32 v150, 1.0, v150
	v_fma_f32 v118, v150, v118, v182
	v_mul_f32_e32 v119, v119, v232
	v_mul_f32_e32 v119, v215, v119
	v_add_f32_e32 v151, 1.0, v151
	v_fma_f32 v119, v151, v119, v183
	v_mul_f32_e32 v120, v120, v232
	v_mul_f32_e32 v120, v216, v120
	v_add_f32_e32 v152, 1.0, v152
	v_fma_f32 v120, v152, v120, v184
	v_mul_f32_e32 v121, v121, v232
	v_mul_f32_e32 v121, v217, v121
	v_add_f32_e32 v153, 1.0, v153
	v_fma_f32 v121, v153, v121, v185
	v_mul_f32_e32 v122, v122, v232
	v_mul_f32_e32 v122, v218, v122
	v_add_f32_e32 v154, 1.0, v154
	v_fma_f32 v122, v154, v122, v186
	v_mul_f32_e32 v123, v123, v232
	v_mul_f32_e32 v123, v219, v123
	v_add_f32_e32 v155, 1.0, v155
	v_fma_f32 v123, v155, v123, v187
	v_mul_f32_e32 v124, v124, v232
	v_mul_f32_e32 v124, v220, v124
	v_add_f32_e32 v156, 1.0, v156
	v_fma_f32 v124, v156, v124, v188
	v_mul_f32_e32 v125, v125, v232
	v_mul_f32_e32 v125, v221, v125
	v_add_f32_e32 v157, 1.0, v157
	v_fma_f32 v125, v157, v125, v189
	v_mul_f32_e32 v126, v126, v232
	v_mul_f32_e32 v126, v222, v126
	v_add_f32_e32 v158, 1.0, v158
	v_fma_f32 v126, v158, v126, v190
	v_mul_f32_e32 v127, v127, v232
	v_mul_f32_e32 v127, v223, v127
	v_add_f32_e32 v159, 1.0, v159
	v_fma_f32 v127, v159, v127, v191
	v_mul_f32_e32 v128, v128, v232
	v_mul_f32_e32 v128, v224, v128
	v_add_f32_e32 v160, 1.0, v160
	v_fma_f32 v128, v160, v128, v192
	v_mul_f32_e32 v129, v129, v232
	v_mul_f32_e32 v129, v225, v129
	v_add_f32_e32 v161, 1.0, v161
	v_fma_f32 v129, v161, v129, v193
	v_cvt_pk_bf16_f32 v98, v98, v99
	v_cvt_pk_bf16_f32 v99, v100, v101
	v_cvt_pk_bf16_f32 v100, v102, v103
	v_cvt_pk_bf16_f32 v101, v104, v105
	v_cvt_pk_bf16_f32 v102, v106, v107
	v_cvt_pk_bf16_f32 v103, v108, v109
	v_cvt_pk_bf16_f32 v104, v110, v111
	v_cvt_pk_bf16_f32 v105, v112, v113
	v_cvt_pk_bf16_f32 v106, v114, v115
	v_cvt_pk_bf16_f32 v107, v116, v117
	v_cvt_pk_bf16_f32 v108, v118, v119
	v_cvt_pk_bf16_f32 v109, v120, v121
	v_cvt_pk_bf16_f32 v110, v122, v123
	v_cvt_pk_bf16_f32 v111, v124, v125
	v_cvt_pk_bf16_f32 v112, v126, v127
	v_cvt_pk_bf16_f32 v113, v128, v129
	s_lshl_b32 s13, s10, 6
	s_add_u32 s8, s80, s13
	s_addc_u32 s9, s81, 0
	global_store_dwordx2 v242, v[98:99], s[8:9]
	global_store_dwordx2 v243, v[100:101], s[8:9]
	global_store_dwordx2 v244, v[102:103], s[8:9]
	global_store_dwordx2 v245, v[104:105], s[8:9]
	global_store_dwordx2 v246, v[106:107], s[8:9]
	global_store_dwordx2 v247, v[108:109], s[8:9]
	global_store_dwordx2 v248, v[110:111], s[8:9]
	global_store_dwordx2 v249, v[112:113], s[8:9]

; template <class AF, class EPI>
; DEV void gemm_tile256(AF aptr, const u16* Bt, int ldb, int K, EPI epi, char* smem) {
;     ...
;   asm volatile("s_waitcnt vmcnt(0)" ::: "memory");
;   __syncthreads();
;   stage(0, 0);
;   stage(1, 1);
;   const unsigned lbase = (unsigned)(size_t)(const __attribute__((address_space(3))) char*)smem;
;   const unsigned aoff = lbase + (wr * 128 + fr) * 64 + fq * 16, boff = lbase + 16384 + (wc * 64 + fr) * 64 + fq * 16;
;   int buf = 0;
; #pragma unroll 1
;   for (int t = 0; t < nk; ++t) {
;     if (t + 1 < nk) asm volatile("s_waitcnt vmcnt(6)" ::: "memory");
;     else asm volatile("s_waitcnt vmcnt(0)" ::: "memory");
;     __builtin_amdgcn_s_barrier();
;     if (t + 2 < nk) { int nb2 = buf + 2; if (nb2 >= 3) nb2 -= 3; stage(t + 2, nb2); }
; __global__ void __launch_bounds__(256, 2) fwd_megakernel(Params p) {
;     ...
;   for (int jt = (bid >> 3); jt < 8 * 37; jt += (nb >> 3)) {
;     const int pn = jt >> 3, pm = (bid & 7) * 8 + (jt & 7);
;     const u16* A = p.h + (size_t)pm * 256 * 2048;
;     gemm_tile256([&](int r, int k) { return A + (size_t)r * 2048 + k; }, p.Wt_in + (size_t)pn * 128 * 2048, 2048, 2048,
.LBB0_244:
	v_writelane_b32 v255, s76, 9
	s_nop 1
	v_writelane_b32 v255, s77, 10
	v_writelane_b32 v255, s78, 11
	v_writelane_b32 v255, s79, 12
	v_writelane_b32 v255, s80, 13
	v_writelane_b32 v255, s81, 14
	v_writelane_b32 v255, s82, 15
	v_writelane_b32 v255, s83, 16
	v_writelane_b32 v255, s84, 17
	v_writelane_b32 v255, s85, 18
	v_writelane_b32 v255, s86, 19
	v_writelane_b32 v255, s87, 20
	v_writelane_b32 v255, s88, 21
	v_writelane_b32 v255, s89, 22
	v_writelane_b32 v255, s90, 23
	v_writelane_b32 v255, s91, 24
	s_or_b64 exec, exec, s[0:1]
	v_readlane_b32 s0, v254, 0
	s_ashr_i32 s58, s0, 3
	v_mov_b32_e32 v1, v0
	s_cmpk_gt_i32 s58, 0x127
	s_waitcnt lgkmcnt(0)
	s_barrier
	v_readlane_b32 s1, v254, 1
	s_cbranch_scc1 .LBB0_359
	v_readlane_b32 s0, v254, 0
	s_mov_b32 s2, s0
	s_lshr_b32 s3, s0, 3
	s_lshl_b32 s0, s0, 3
	s_and_b32 s4, s0, 56
	s_lshr_b32 s0, s4, 2
	v_readlane_b32 s8, v254, 41
	s_sub_i32 s78, s0, 18
	v_readlane_b32 s10, v254, 43
	v_readlane_b32 s11, v254, 44
	s_add_u32 s80, s10, 0x400
	s_addc_u32 s81, s11, 0
	s_add_i32 s79, s0, -14
	v_readlane_b32 s9, v254, 42
	v_readlane_b32 s12, v254, 45
	v_readlane_b32 s13, v254, 46
	v_readlane_b32 s14, v254, 47
	v_readlane_b32 s15, v254, 48
	v_readlane_b32 s16, v254, 49
	v_readlane_b32 s17, v254, 50
	v_readlane_b32 s18, v254, 51
	v_readlane_b32 s19, v254, 52
	v_readlane_b32 s20, v254, 53
	v_readlane_b32 s21, v254, 54
	v_readlane_b32 s22, v254, 55
	v_readlane_b32 s23, v254, 56
	s_add_u32 s82, s10, 0x200
	s_addc_u32 s83, s11, 0
	v_readlane_b32 s8, v255, 9
	v_readlane_b32 s9, v255, 10
	v_readlane_b32 s10, v255, 11
	v_readlane_b32 s11, v255, 12
	v_readlane_b32 s12, v255, 13
	v_readlane_b32 s13, v255, 14
	v_readlane_b32 s14, v255, 15
	v_readlane_b32 s15, v255, 16
	v_readlane_b32 s16, v255, 17
	v_readlane_b32 s17, v255, 18
	v_readlane_b32 s18, v255, 19
	v_readlane_b32 s19, v255, 20
	s_ashr_i32 s77, s92, 3
	v_readlane_b32 s20, v255, 21
	v_readlane_b32 s21, v255, 22
	v_readlane_b32 s22, v255, 23
	v_readlane_b32 s23, v255, 24
	s_mov_b64 s[8:9], s[12:13]
	s_add_u32 s5, s8, 0x200000
	s_addc_u32 s76, s9, 0
	s_and_b32 s0, s2, 7
	v_readlane_b32 s36, v254, 4
	s_lshl_b32 s6, s0, 22
	v_readlane_b32 s46, v254, 14
	v_readlane_b32 s47, v254, 15
	s_add_u32 s7, s46, 0x94000
	s_mov_b64 s[10:11], s[14:15]
	s_mov_b64 s[12:13], s[16:17]
	s_addc_u32 s8, s47, 0
	s_add_u32 s10, s12, 0x9400
	s_mov_b64 s[14:15], s[18:19]
	v_readlane_b32 s37, v254, 5
	s_addc_u32 s11, s13, 0
	s_lshl_b32 s9, s0, 11
	s_mov_b64 s[16:17], s[20:21]
	s_mov_b64 s[18:19], s[22:23]
	s_movk_i32 s33, 0x80
	s_or_b32 s36, s9, 0x80
	s_mov_b32 s47, 0
	v_mov_b32_e32 v135, 0
	s_movk_i32 s13, 0x204
	s_movk_i32 s37, 0x4080
	s_movk_i32 s2, 0x2500
	s_mov_b32 s84, 0xfc000
	v_mov_b32_e32 v1, 0x358637bd
	s_mov_b32 s12, 0x800000
	s_mov_b64 s[14:15], 0x12800
	s_mov_b64 s[34:35], 0x1000
	v_mov_b32_e32 v158, 0x10200
	s_mov_b32 s93, s58
	v_readlane_b32 s1, v254, 1
	v_readlane_b32 s38, v254, 6
	v_readlane_b32 s39, v254, 7
	v_readlane_b32 s40, v254, 8
	v_readlane_b32 s41, v254, 9
	v_readlane_b32 s42, v254, 10
	v_readlane_b32 s43, v254, 11
	v_readlane_b32 s44, v254, 12
	v_readlane_b32 s45, v254, 13
	v_readlane_b32 s48, v254, 16
	v_readlane_b32 s49, v254, 17
	v_readlane_b32 s50, v254, 18
	v_readlane_b32 s51, v254, 19
	s_branch .LBB0_247

; template <class AF, class EPI>
; DEV void gemm_tile256(AF aptr, const u16* Bt, int ldb, int K, EPI epi, char* smem) {
;     ...
;   auto stage = [&](int kt, int buf) {
;     char* SA = smem + buf * 24576;
;     char* SB = SA + 16384;
; #pragma unroll
;     for (int i = 0; i < 4; ++i) {
;       int bo = tid * 16 + i * 4096, r = bo >> 6, c = (bo & 63) >> 1;
;       __builtin_amdgcn_global_load_lds((const unsigned*)aptr(r, kt * 32 + c), (__attribute__((address_space(3))) unsigned*)(SA + bo), 16, 0, 0);
;     }
; #pragma unroll
;     for (int i = 0; i < 2; ++i) {
;       int bo = tid * 16 + i * 4096, r = bo >> 6, c = (bo & 63) >> 1;
;       __builtin_amdgcn_global_load_lds((const unsigned*)(Bt + (size_t)r * ldb + kt * 32 + c), (__attribute__((address_space(3))) unsigned*)(SB + bo), 16, 0, 0);
;     }
;   };
;   asm volatile("s_waitcnt vmcnt(0)" ::: "memory");
;   __syncthreads();
;   stage(0, 0);
;   stage(1, 1);
;   const unsigned lbase = (unsigned)(size_t)(const __attribute__((address_space(3))) char*)smem;
;   const unsigned aoff = lbase + (wr * 128 + fr) * 64 + fq * 16, boff = lbase + 16384 + (wc * 64 + fr) * 64 + fq * 16;
; __global__ void __launch_bounds__(256, 2) fwd_megakernel(Params p) {
;     ...
;   for (int jt = (bid >> 3); jt < 8 * 37; jt += (nb >> 3)) {
;     const int pn = jt >> 3, pm = (bid & 7) * 8 + (jt & 7);
;     const u16* A = p.h + (size_t)pm * 256 * 2048;
;     gemm_tile256([&](int r, int k) { return A + (size_t)r * 2048 + k; }, p.Wt_in + (size_t)pn * 128 * 2048, 2048, 2048,
.LBB0_247:
	s_and_b32 s57, s3, 7
	s_lshl_b32 s0, s57, 19
	s_add_i32 s0, s6, s0
	s_lshr_b32 s44, s0, 5
	s_and_b32 s0, s93, 7
	s_or_b32 s56, s0, s4
	v_readlane_b32 s16, v255, 9
	v_mov_b32_e32 v144, v0
	s_ashr_i32 s38, s93, 3
	s_lshl_b32 s0, s56, 14
	v_readlane_b32 s20, v255, 13
	v_readlane_b32 s21, v255, 14
	v_ashrrev_i32_e32 v2, 2, v144
	s_add_u32 s40, s20, s0
	v_lshlrev_b32_e32 v148, 4, v144
	v_ashrrev_i32_e32 v3, 31, v2
	s_addc_u32 s41, s21, 0
	s_ashr_i32 s39, s38, 31
	v_lshlrev_b64 v[2:3], 12, v[2:3]
	v_lshrrev_b64 v[246:247], 6, v[2:3]
	s_mov_b64 s[86:87], 0x100000
	s_mov_b64 s[88:89], 0x4a000
	v_add_u32_e32 v10, 0x1000, v148
	s_lshl_b64 s[0:1], s[38:39], 13
	v_lshl_add_u64 v[4:5], s[40:41], 0, v[246:247]
	v_and_b32_e32 v134, 48, v148
	v_and_b32_e32 v253, 32, v144
	v_xor_b32_e32 v134, v134, v253
	v_readfirstlane_b32 s39, v148
	v_ashrrev_i32_e32 v6, 6, v10
	v_add_u32_e32 v14, 0x2000, v148
	v_readlane_b32 s17, v255, 10
	v_readlane_b32 s18, v255, 11
	v_readlane_b32 s19, v255, 12
	v_readlane_b32 s22, v255, 15
	v_readlane_b32 s23, v255, 16
	v_readlane_b32 s24, v255, 17
	v_readlane_b32 s25, v255, 18
	v_readlane_b32 s26, v255, 19
	v_readlane_b32 s27, v255, 20
	v_readlane_b32 s28, v255, 21
	v_readlane_b32 s29, v255, 22
	v_readlane_b32 s30, v255, 23
	v_readlane_b32 s31, v255, 24
	v_lshl_add_u64 v[4:5], v[4:5], 0, v[134:135]
	s_mov_b32 m0, s39
	v_ashrrev_i32_e32 v7, 31, v6
	v_readfirstlane_b32 s39, v10
	v_ashrrev_i32_e32 v10, 6, v14
	v_add_u32_e32 v18, 0x3000, v148
	v_readlane_b32 s16, v254, 4
	s_waitcnt vmcnt(0)
	s_barrier
; template <class AF, class EPI>
; DEV void gemm_tile256(AF aptr, const u16* Bt, int ldb, int K, EPI epi, char* smem) {
;     ...
;   auto stage = [&](int kt, int buf) {
;     char* SA = smem + buf * 24576;
;     char* SB = SA + 16384;
; #pragma unroll
;     for (int i = 0; i < 4; ++i) {
;       int bo = tid * 16 + i * 4096, r = bo >> 6, c = (bo & 63) >> 1;
;       __builtin_amdgcn_global_load_lds((const unsigned*)aptr(r, kt * 32 + c), (__attribute__((address_space(3))) unsigned*)(SA + bo), 16, 0, 0);
;     }
; #pragma unroll
;     for (int i = 0; i < 2; ++i) {
;       int bo = tid * 16 + i * 4096, r = bo >> 6, c = (bo & 63) >> 1;
;       __builtin_amdgcn_global_load_lds((const unsigned*)(Bt + (size_t)r * ldb + kt * 32 + c), (__attribute__((address_space(3))) unsigned*)(SB + bo), 16, 0, 0);
;     }
;   };
;   asm volatile("s_waitcnt vmcnt(0)" ::: "memory");
;   __syncthreads();
;   stage(0, 0);
;   stage(1, 1);
;   const unsigned lbase = (unsigned)(size_t)(const __attribute__((address_space(3))) char*)smem;
;   const unsigned aoff = lbase + (wr * 128 + fr) * 64 + fq * 16, boff = lbase + 16384 + (wc * 64 + fr) * 64 + fq * 16;
	global_load_lds_dwordx4 v[4:5], off
	v_lshlrev_b64 v[6:7], 12, v[6:7]
	v_lshrrev_b64 v[248:249], 6, v[6:7]
	s_mov_b32 m0, s39
	v_ashrrev_i32_e32 v11, 31, v10
	v_readfirstlane_b32 s39, v14
	v_ashrrev_i32_e32 v14, 6, v18
	v_readlane_b32 s26, v254, 14
	v_lshl_add_u64 v[8:9], s[40:41], 0, v[248:249]
	v_lshlrev_b64 v[10:11], 6, v[10:11]
	v_ashrrev_i32_e32 v15, 31, v14
	v_readlane_b32 s27, v254, 15
	s_add_u32 s42, s26, s0
	v_lshl_add_u64 v[8:9], v[8:9], 0, v[134:135]
	v_lshl_add_u64 v[12:13], s[40:41], 0, v[10:11]
	v_lshlrev_b64 v[14:15], 6, v[14:15]
	s_addc_u32 s43, s27, s1
	global_load_lds_dwordx4 v[8:9], off
	v_lshl_add_u64 v[12:13], v[12:13], 0, v[134:135]
	s_mov_b32 m0, s39
	v_lshl_add_u64 v[16:17], s[40:41], 0, v[14:15]
	v_readfirstlane_b32 s39, v18
	v_add_u32_e32 v20, 0x4000, v148
	global_load_lds_dwordx4 v[12:13], off
	v_lshl_add_u64 v[16:17], v[16:17], 0, v[134:135]
	s_mov_b32 m0, s39
	v_lshl_add_u64 v[18:19], s[42:43], 0, v[246:247]
	v_readfirstlane_b32 s39, v20
	v_add_u32_e32 v22, 0x5000, v148
	global_load_lds_dwordx4 v[16:17], off
	v_lshl_add_u64 v[18:19], v[18:19], 0, v[134:135]
	s_mov_b32 m0, s39
	v_lshl_add_u64 v[20:21], s[42:43], 0, v[248:249]
	v_readfirstlane_b32 s39, v22
	v_add_u32_e32 v22, 0x6000, v148
	global_load_lds_dwordx4 v[18:19], off
	v_lshl_add_u64 v[20:21], v[20:21], 0, v[134:135]
	s_mov_b32 m0, s39
	v_readfirstlane_b32 s39, v22
	global_load_lds_dwordx4 v[20:21], off
	v_lshl_add_u64 v[4:5], v[4:5], 0, s[86:87]
	s_mov_b32 m0, s39
	s_add_u32 s40, s5, s44
	global_load_lds_dwordx4 v[4:5], off
	v_lshl_add_u64 v[4:5], v[8:9], 0, s[86:87]
	v_add_u32_e32 v8, 0x7000, v148
	v_bfe_u32 v147, v144, 4, 2
	v_readfirstlane_b32 s39, v8
	v_add_u32_e32 v8, 0x8000, v148
	s_mov_b32 m0, s39
	v_readfirstlane_b32 s39, v8
	v_add_u32_e32 v8, 0x9000, v148
	global_load_lds_dwordx4 v[4:5], off
	v_lshl_add_u64 v[4:5], v[12:13], 0, s[86:87]
	s_mov_b32 m0, s39
	v_readfirstlane_b32 s39, v8
	v_add_u32_e32 v8, 0xa000, v148
	global_load_lds_dwordx4 v[4:5], off
	v_lshl_add_u64 v[4:5], v[16:17], 0, s[86:87]
	s_mov_b32 m0, s39
	v_readfirstlane_b32 s39, v8
	v_add_u32_e32 v8, 0xb000, v148
	global_load_lds_dwordx4 v[4:5], off
	v_lshl_add_u64 v[4:5], v[18:19], 0, s[88:89]
	s_mov_b32 m0, s39
	v_readfirstlane_b32 s39, v8
	global_load_lds_dwordx4 v[4:5], off
	v_lshl_add_u64 v[4:5], v[20:21], 0, s[88:89]
	s_mov_b32 m0, s39
	s_addc_u32 s41, s76, 0
	global_load_lds_dwordx4 v[4:5], off
	v_bfe_u32 v145, v144, 6, 1
	v_ashrrev_i32_e32 v159, 7, v144
	v_and_b32_e32 v146, 15, v144
	v_lshlrev_b32_e32 v8, 4, v147
	v_lshlrev_b32_e32 v253, 2, v144
	v_and_b32_e32 v253, 32, v253
	v_xor_b32_e32 v8, v8, v253
	s_add_u32 s0, s7, s0
	v_lshlrev_b32_e32 v4, 13, v159
	v_lshlrev_b32_e32 v5, 6, v146
	v_lshl_or_b32 v9, v145, 12, v8
	s_movk_i32 s39, 0x4000
	v_or_b32_e32 v2, v2, v134
	v_or_b32_e32 v6, v6, v134
	v_or_b32_e32 v10, v10, v134
	v_or_b32_e32 v14, v14, v134
	s_addc_u32 s1, s8, s1
	v_or3_b32 v149, v4, v8, v5
	v_or3_b32 v150, v5, v9, s39
	v_or_b32_e32 v246, v246, v134
	v_or_b32_e32 v248, v248, v134
	v_lshl_add_u64 v[130:131], s[40:41], 0, v[246:247]
	v_lshl_add_u64 v[132:133], s[40:41], 0, v[248:249]
	v_lshl_add_u64 v[136:137], s[40:41], 0, v[10:11]
	v_lshl_add_u64 v[138:139], s[40:41], 0, v[14:15]
	v_lshl_add_u64 v[140:141], s[0:1], 0, v[248:249]
	v_lshl_add_u64 v[142:143], s[0:1], 0, v[246:247]
	s_mov_b64 s[0:1], 0
	s_mov_b32 s39, 0
	s_mov_b32 s42, 0
	v_mov_b32_e32 v2, 0
	v_mov_b32_e32 v3, v135
	v_mov_b32_e32 v4, v135
	v_mov_b32_e32 v5, v135
	v_mov_b32_e32 v6, 0
	v_mov_b32_e32 v7, v135
	v_mov_b32_e32 v8, v135
	v_mov_b32_e32 v9, v135
	v_mov_b32_e32 v10, 0
	v_mov_b32_e32 v11, v135
	v_mov_b32_e32 v12, v135
	v_mov_b32_e32 v13, v135
	v_mov_b32_e32 v14, 0
	v_mov_b32_e32 v15, v135
	v_mov_b32_e32 v16, v135
	v_mov_b32_e32 v17, v135
	v_mov_b32_e32 v18, 0
	v_mov_b32_e32 v19, v135
	v_mov_b32_e32 v20, v135
	v_mov_b32_e32 v21, v135
	v_mov_b32_e32 v22, 0
	v_mov_b32_e32 v23, v135
	v_mov_b32_e32 v24, v135
	v_mov_b32_e32 v25, v135
	v_mov_b32_e32 v26, 0
	v_mov_b32_e32 v27, v135
	v_mov_b32_e32 v28, v135
	v_mov_b32_e32 v29, v135
	v_mov_b32_e32 v30, 0
	v_mov_b32_e32 v31, v135
	v_mov_b32_e32 v32, v135
	v_mov_b32_e32 v33, v135
	v_mov_b32_e32 v34, 0
	v_mov_b32_e32 v35, v135
	v_mov_b32_e32 v36, v135
	v_mov_b32_e32 v37, v135
	v_mov_b32_e32 v38, 0
	v_mov_b32_e32 v39, v135
	v_mov_b32_e32 v40, v135
	v_mov_b32_e32 v41, v135
	v_mov_b32_e32 v42, 0
	v_mov_b32_e32 v43, v135
	v_mov_b32_e32 v44, v135
	v_mov_b32_e32 v45, v135
	v_mov_b32_e32 v94, 0
	v_mov_b32_e32 v95, v135
	v_mov_b32_e32 v96, v135
	v_mov_b32_e32 v97, v135
	v_mov_b32_e32 v98, 0
	v_mov_b32_e32 v99, v135
	v_mov_b32_e32 v100, v135
	v_mov_b32_e32 v101, v135
	v_mov_b32_e32 v102, 0
	v_mov_b32_e32 v103, v135
	v_mov_b32_e32 v104, v135
	v_mov_b32_e32 v105, v135
	v_mov_b32_e32 v106, 0
	v_mov_b32_e32 v107, v135
	v_mov_b32_e32 v108, v135
	v_mov_b32_e32 v109, v135
	v_mov_b32_e32 v110, 0
	v_mov_b32_e32 v111, v135
	v_mov_b32_e32 v112, v135
	v_mov_b32_e32 v113, v135
	v_mov_b32_e32 v114, 0
	v_mov_b32_e32 v115, v135
	v_mov_b32_e32 v116, v135
	v_mov_b32_e32 v117, v135
	v_mov_b32_e32 v118, 0
	v_mov_b32_e32 v119, v135
	v_mov_b32_e32 v120, v135
	v_mov_b32_e32 v121, v135
	v_mov_b32_e32 v122, 0
	v_mov_b32_e32 v123, v135
	v_mov_b32_e32 v124, v135
	v_mov_b32_e32 v125, v135
	v_mov_b32_e32 v126, 0
	v_mov_b32_e32 v127, v135
	v_mov_b32_e32 v128, v135
	v_mov_b32_e32 v129, v135
	v_mov_b32_e32 v46, 0
	v_mov_b32_e32 v47, v135
	v_mov_b32_e32 v48, v135
	v_mov_b32_e32 v49, v135
	v_mov_b32_e32 v50, 0
	v_mov_b32_e32 v51, v135
	v_mov_b32_e32 v52, v135
	v_mov_b32_e32 v53, v135
	v_mov_b32_e32 v54, 0
	v_mov_b32_e32 v55, v135
	v_mov_b32_e32 v56, v135
	v_mov_b32_e32 v57, v135
	v_mov_b32_e32 v58, 0
	v_mov_b32_e32 v59, v135
	v_mov_b32_e32 v60, v135
	v_mov_b32_e32 v61, v135
	v_mov_b32_e32 v62, 0
	v_mov_b32_e32 v63, v135
	v_mov_b32_e32 v64, v135
	v_mov_b32_e32 v65, v135
	v_mov_b32_e32 v66, 0
	v_mov_b32_e32 v67, v135
	v_mov_b32_e32 v68, v135
	v_mov_b32_e32 v69, v135
	v_mov_b32_e32 v70, 0
	v_mov_b32_e32 v71, v135
	v_mov_b32_e32 v72, v135
	v_mov_b32_e32 v73, v135
	v_mov_b32_e32 v74, 0
	v_mov_b32_e32 v75, v135
	v_mov_b32_e32 v76, v135
	v_mov_b32_e32 v77, v135
	v_mov_b32_e32 v78, 0
	v_mov_b32_e32 v79, v135
	v_mov_b32_e32 v80, v135
	v_mov_b32_e32 v81, v135
	v_mov_b32_e32 v82, 0
	v_mov_b32_e32 v83, v135
	v_mov_b32_e32 v84, v135
	v_mov_b32_e32 v85, v135
	v_mov_b32_e32 v86, 0
	v_mov_b32_e32 v87, v135
	v_mov_b32_e32 v88, v135
	v_mov_b32_e32 v89, v135
	v_mov_b32_e32 v90, 0
	v_mov_b32_e32 v91, v135
	v_mov_b32_e32 v92, v135
	v_mov_b32_e32 v93, v135
	v_readlane_b32 s17, v254, 5
	v_readlane_b32 s18, v254, 6
	v_readlane_b32 s19, v254, 7
	v_readlane_b32 s20, v254, 8
	v_readlane_b32 s21, v254, 9
	v_readlane_b32 s22, v254, 10
	v_readlane_b32 s23, v254, 11
	v_readlane_b32 s24, v254, 12
	v_readlane_b32 s25, v254, 13
	v_readlane_b32 s28, v254, 16
	v_readlane_b32 s29, v254, 17
	v_readlane_b32 s30, v254, 18
	v_readlane_b32 s31, v254, 19
	s_branch .LBB0_249

; template <class AF, class EPI>
; DEV void gemm_tile256(AF aptr, const u16* Bt, int ldb, int K, EPI epi, char* smem) {
;     ...
;   for (int t = 0; t < nk; ++t) {
;     if (t + 1 < nk) asm volatile("s_waitcnt vmcnt(6)" ::: "memory");
;     else asm volatile("s_waitcnt vmcnt(0)" ::: "memory");
;     __builtin_amdgcn_s_barrier();
;     if (t + 2 < nk) { int nb2 = buf + 2; if (nb2 >= 3) nb2 -= 3; stage(t + 2, nb2); }
;     const unsigned sa = aoff + buf * 24576, sb = boff + buf * 24576;
;     u32x4 a0, a1, a2, a3, a4, a5, a6, a7, b0, b1, b2, b3;
;     asm volatile("ds_read_b128 %0, %1" : "=v"(b0) : "v"(sb));
;     asm volatile("ds_read_b128 %0, %1 offset:1024" : "=v"(b1) : "v"(sb));
;     asm volatile("ds_read_b128 %0, %1 offset:2048" : "=v"(b2) : "v"(sb));
;     asm volatile("ds_read_b128 %0, %1 offset:3072" : "=v"(b3) : "v"(sb));
;     asm volatile("ds_read_b128 %0, %1" : "=v"(a0) : "v"(sa));
;     asm volatile("ds_read_b128 %0, %1 offset:1024" : "=v"(a1) : "v"(sa));
;     asm volatile("ds_read_b128 %0, %1 offset:2048" : "=v"(a2) : "v"(sa));
;     asm volatile("ds_read_b128 %0, %1 offset:3072" : "=v"(a3) : "v"(sa));
;     asm volatile("ds_read_b128 %0, %1 offset:4096" : "=v"(a4) : "v"(sa));
;     asm volatile("ds_read_b128 %0, %1 offset:5120" : "=v"(a5) : "v"(sa));
;     asm volatile("ds_read_b128 %0, %1 offset:6144" : "=v"(a6) : "v"(sa));
;     asm volatile("ds_read_b128 %0, %1 offset:7168" : "=v"(a7) : "v"(sa));
;     asm volatile("s_waitcnt lgkmcnt(4)" : "+v"(a0), "+v"(a1), "+v"(a2), "+v"(a3), "+v"(b0), "+v"(b1), "+v"(b2), "+v"(b3));
;     bf16x8 Bv[4];
;     Bv[0] = __builtin_bit_cast(bf16x8, b0); Bv[1] = __builtin_bit_cast(bf16x8, b1); Bv[2] = __builtin_bit_cast(bf16x8, b2); Bv[3] = __builtin_bit_cast(bf16x8, b3);
;     {
;       bf16x8 At[4];
;       At[0] = __builtin_bit_cast(bf16x8, a0); At[1] = __builtin_bit_cast(bf16x8, a1); At[2] = __builtin_bit_cast(bf16x8, a2); At[3] = __builtin_bit_cast(bf16x8, a3);
; #pragma unroll
;       for (int m = 0; m < 4; ++m)
; #pragma unroll
;         for (int n = 0; n < 4; ++n) acc[m][n] = __builtin_amdgcn_mfma_f32_16x16x32_bf16(At[m], Bv[n], acc[m][n], 0, 0, 0);
;     }
;     asm volatile("s_waitcnt lgkmcnt(0)" : "+v"(a4), "+v"(a5), "+v"(a6), "+v"(a7));
;     {
;       bf16x8 At[4];
.LBB0_253:
	s_barrier
	s_mul_i32 s40, s39, 0x6000
	v_add_u32_e32 v134, s40, v149
	v_add_u32_e32 v151, s40, v150
	ds_read_b128 v[152:155], v151
	ds_read_b128 v[160:163], v151 offset:1024
	ds_read_b128 v[164:167], v151 offset:2048
	ds_read_b128 v[168:171], v151 offset:3072
	ds_read_b128 v[172:175], v134
	ds_read_b128 v[176:179], v134 offset:1024
	ds_read_b128 v[180:183], v134 offset:2048
	ds_read_b128 v[184:187], v134 offset:3072
	ds_read_b128 v[188:191], v134 offset:4096
	ds_read_b128 v[192:195], v134 offset:5120
	ds_read_b128 v[196:199], v134 offset:6144
	ds_read_b128 v[200:203], v134 offset:7168
	s_cmp_gt_u32 s42, 61
	s_cbranch_scc1 .Lgnodma_g2
	s_cmp_gt_i32 s39, 0
	s_cselect_b32 s40, -1, 2
	s_add_i32 s40, s40, s39
	s_mulk_i32 s40, 0x6000
	v_add_u32_e32 v252, s40, v148
	s_nop 0
	v_readfirstlane_b32 s40, v252
	s_waitcnt lgkmcnt(7)
	v_mfma_f32_16x16x32_bf16 v[126:129], v[172:175], v[152:155], v[126:129]
	v_mfma_f32_16x16x32_bf16 v[122:125], v[172:175], v[160:163], v[122:125]
	v_mfma_f32_16x16x32_bf16 v[118:121], v[172:175], v[164:167], v[118:121]
	v_mfma_f32_16x16x32_bf16 v[114:117], v[172:175], v[168:171], v[114:117]
	s_lshl_b64 s[86:87], s[0:1], 14
	v_lshl_add_u64 v[250:251], v[130:131], 0, s[86:87]
	s_mov_b32 m0, s40
	s_nop 0
	global_load_lds_dwordx4 v[250:251], off
	s_waitcnt lgkmcnt(6)
	v_mfma_f32_16x16x32_bf16 v[110:113], v[176:179], v[152:155], v[110:113]
	v_mfma_f32_16x16x32_bf16 v[106:109], v[176:179], v[160:163], v[106:109]
	v_mfma_f32_16x16x32_bf16 v[102:105], v[176:179], v[164:167], v[102:105]
	v_mfma_f32_16x16x32_bf16 v[98:101], v[176:179], v[168:171], v[98:101]
	v_lshl_add_u64 v[250:251], v[132:133], 0, s[86:87]
	s_add_u32 m0, s40, 0x1000
	s_nop 0
	global_load_lds_dwordx4 v[250:251], off
	s_waitcnt lgkmcnt(5)
	v_mfma_f32_16x16x32_bf16 v[94:97], v[180:183], v[152:155], v[94:97]
	v_mfma_f32_16x16x32_bf16 v[42:45], v[180:183], v[160:163], v[42:45]
	v_mfma_f32_16x16x32_bf16 v[38:41], v[180:183], v[164:167], v[38:41]
	v_mfma_f32_16x16x32_bf16 v[34:37], v[180:183], v[168:171], v[34:37]
	v_lshl_add_u64 v[250:251], v[136:137], 0, s[86:87]
	s_add_u32 m0, s40, 0x2000
	s_nop 0
	global_load_lds_dwordx4 v[250:251], off
	s_waitcnt lgkmcnt(4)
	v_mfma_f32_16x16x32_bf16 v[30:33], v[184:187], v[152:155], v[30:33]
	v_mfma_f32_16x16x32_bf16 v[26:29], v[184:187], v[160:163], v[26:29]
	v_mfma_f32_16x16x32_bf16 v[22:25], v[184:187], v[164:167], v[22:25]
	v_mfma_f32_16x16x32_bf16 v[18:21], v[184:187], v[168:171], v[18:21]
	v_lshl_add_u64 v[250:251], v[138:139], 0, s[86:87]
	s_add_u32 m0, s40, 0x3000
	s_nop 0
	global_load_lds_dwordx4 v[250:251], off
	s_waitcnt lgkmcnt(3)
	v_mfma_f32_16x16x32_bf16 v[14:17], v[188:191], v[152:155], v[14:17]
	v_mfma_f32_16x16x32_bf16 v[10:13], v[188:191], v[160:163], v[10:13]
	v_mfma_f32_16x16x32_bf16 v[6:9], v[188:191], v[164:167], v[6:9]
	v_mfma_f32_16x16x32_bf16 v[2:5], v[188:191], v[168:171], v[2:5]
	s_mul_i32 s88, s0, 4736
	s_mov_b32 s89, 0
	v_lshl_add_u64 v[250:251], v[142:143], 0, s[88:89]
	s_add_u32 m0, s40, 0x4000
	s_nop 0
	global_load_lds_dwordx4 v[250:251], off
	s_waitcnt lgkmcnt(2)
	v_mfma_f32_16x16x32_bf16 v[46:49], v[192:195], v[152:155], v[46:49]
	v_mfma_f32_16x16x32_bf16 v[50:53], v[192:195], v[160:163], v[50:53]
	v_mfma_f32_16x16x32_bf16 v[54:57], v[192:195], v[164:167], v[54:57]
	v_mfma_f32_16x16x32_bf16 v[58:61], v[192:195], v[168:171], v[58:61]
	v_lshl_add_u64 v[250:251], v[140:141], 0, s[88:89]
	s_add_u32 m0, s40, 0x5000
	s_nop 0
	global_load_lds_dwordx4 v[250:251], off
	s_waitcnt lgkmcnt(1)
	v_mfma_f32_16x16x32_bf16 v[62:65], v[196:199], v[152:155], v[62:65]
	v_mfma_f32_16x16x32_bf16 v[66:69], v[196:199], v[160:163], v[66:69]
	v_mfma_f32_16x16x32_bf16 v[70:73], v[196:199], v[164:167], v[70:73]
	v_mfma_f32_16x16x32_bf16 v[74:77], v[196:199], v[168:171], v[74:77]
	s_waitcnt lgkmcnt(0)
	v_mfma_f32_16x16x32_bf16 v[78:81], v[200:203], v[152:155], v[78:81]
	v_mfma_f32_16x16x32_bf16 v[82:85], v[200:203], v[160:163], v[82:85]
	v_mfma_f32_16x16x32_bf16 v[86:89], v[200:203], v[164:167], v[86:89]
	v_mfma_f32_16x16x32_bf16 v[90:93], v[200:203], v[168:171], v[90:93]
	s_branch .Lgjoin_g2

; DEV int ltid() { int t = threadIdx.x; asm volatile("" : "+v"(t)); return t; }
; DEV unsigned pack2(float a, float b) { float2v v = {a, b}; return __builtin_bit_cast(unsigned, __builtin_convertvector(v, bf16x2v)); }
; DEV float bflo(unsigned u) { return __uint_as_float(u << 16); }
; DEV float bfhi(unsigned u) { return __uint_as_float(u & 0xffff0000u); }
; DEV void ph_ynorm_row(const Params& p, int row) {
;   const int lane = ltid() & 63, c0 = lane * 16;
;   float va[16], vr[16];
; #pragma unroll
;   for (int e = 0; e < 16; ++e) va[e] = 0.f;
; #pragma unroll
;   for (int br = 0; br < 3; ++br) {
;     const u16* src = p.oattn3 + (size_t)br * T_ * 1024 + (size_t)row * 1024 + c0;
;     u32x4 a = *(const u32x4*)src, b2 = *(const u32x4*)(src + 8);
; #pragma unroll
;     for (int e = 0; e < 4; ++e) { va[2 * e] += bflo(a[e]); va[2 * e + 1] += bfhi(a[e]); va[8 + 2 * e] += bflo(b2[e]); va[8 + 2 * e + 1] += bfhi(b2[e]); }
;   }
;   {
;     const u16* src = p.orn + (size_t)row * 1024 + c0;
;     u32x4 a = *(const u32x4*)src, b2 = *(const u32x4*)(src + 8);
; #pragma unroll
;     for (int e = 0; e < 4; ++e) { vr[2 * e] = bflo(a[e]); vr[2 * e + 1] = bfhi(a[e]); vr[8 + 2 * e] = bflo(b2[e]); vr[8 + 2 * e + 1] = bfhi(b2[e]); }
;   }
;   float sa = 0.f, sr = 0.f;
; #pragma unroll
;   for (int e = 0; e < 16; ++e) { sa += va[e] * va[e]; sr += vr[e] * vr[e]; }
;   sa = wave_sum(sa); sr = wave_sum(sr);
;   const float ra = rsqrtf(sa * (1.f / 1024.f) + 1e-6f), rr = rsqrtf(sr * (1.f / 1024.f) + 1e-6f);
;   u32x4 o0, o1, o2, o3;
; #pragma unroll
;   for (int e = 0; e < 4; ++e) {
;     o0[e] = pack2(va[2 * e] * ra * p.out_g_attn[c0 + 2 * e], va[2 * e + 1] * ra * p.out_g_attn[c0 + 2 * e + 1]);
;     o1[e] = pack2(va[8 + 2 * e] * ra * p.out_g_attn[c0 + 8 + 2 * e], va[8 + 2 * e + 1] * ra * p.out_g_attn[c0 + 8 + 2 * e + 1]);
;     o2[e] = pack2(vr[2 * e] * rr * p.out_g_rnn[c0 + 2 * e], vr[2 * e + 1] * rr * p.out_g_rnn[c0 + 2 * e + 1]);
;     o3[e] = pack2(vr[8 + 2 * e] * rr * p.out_g_rnn[c0 + 8 + 2 * e], vr[8 + 2 * e + 1] * rr * p.out_g_rnn[c0 + 8 + 2 * e + 1]);
;   }
;   u16* dst = p.y + (size_t)row * 2048;
;   *(u32x4*)(dst + c0) = o0; *(u32x4*)(dst + c0 + 8) = o1;
;   *(u32x4*)(dst + 1024 + c0) = o2; *(u32x4*)(dst + 1024 + c0 + 8) = o3;
.LBB0_1184:
	s_or_b64 exec, exec, s[0:1]
	v_mov_b32_e32 v1, v0
	s_waitcnt lgkmcnt(0)
	s_barrier
	s_movk_i32 s0, 0x4000
	v_ashrrev_i32_e32 v2, 6, v1
	v_add_u32_e32 v1, s84, v2
	v_cmp_gt_i32_e32 vcc, s0, v1
	s_mov_b64 s[6:7], exec
	v_readlane_b32 s12, v254, 57
	v_readlane_b32 s13, v254, 58
	v_readlane_b32 s14, v254, 59
	v_readlane_b32 s15, v254, 60
	v_readlane_b32 s16, v254, 61
	v_readlane_b32 s17, v254, 62
	v_readlane_b32 s18, v254, 63
	v_readlane_b32 s19, v255, 0
	v_readlane_b32 s20, v255, 1
	v_readlane_b32 s21, v255, 2
	v_readlane_b32 s22, v255, 3
	v_readlane_b32 s23, v255, 4
	v_readlane_b32 s8, v255, 25
	v_readlane_b32 s22, v255, 39
	v_readlane_b32 s23, v255, 40
	v_readlane_b32 s9, v255, 26
	v_readlane_b32 s10, v255, 27
	v_readlane_b32 s11, v255, 28
	v_readlane_b32 s12, v255, 29
	v_readlane_b32 s13, v255, 30
	v_readlane_b32 s14, v255, 31
	v_readlane_b32 s15, v255, 32
	v_readlane_b32 s16, v255, 33
	v_readlane_b32 s17, v255, 34
	v_readlane_b32 s18, v255, 35
	v_readlane_b32 s19, v255, 36
	v_readlane_b32 s20, v255, 37
	v_readlane_b32 s21, v255, 38
	s_mov_b64 s[54:55], s[22:23]
	s_mov_b64 s[52:53], s[20:21]
	v_readlane_b32 s8, v255, 9
	v_readlane_b32 s14, v255, 15
	v_readlane_b32 s15, v255, 16
	v_readlane_b32 s10, v255, 11
	v_readlane_b32 s11, v255, 12
	v_readlane_b32 s12, v255, 13
	v_readlane_b32 s13, v255, 14
	s_mov_b64 s[82:83], s[14:15]
	s_and_b64 s[0:1], s[6:7], vcc
	v_readlane_b32 s24, v255, 5
	v_readlane_b32 s25, v255, 6
	v_readlane_b32 s26, v255, 7
	v_readlane_b32 s27, v255, 8
	s_mov_b64 s[80:81], s[12:13]
	s_mov_b64 s[78:79], s[10:11]
	v_readlane_b32 s9, v255, 10
	v_readlane_b32 s16, v255, 17
	v_readlane_b32 s17, v255, 18
	v_readlane_b32 s18, v255, 19
	v_readlane_b32 s19, v255, 20
	v_readlane_b32 s20, v255, 21
	v_readlane_b32 s21, v255, 22
	v_readlane_b32 s22, v255, 23
	v_readlane_b32 s23, v255, 24
	s_mov_b64 exec, s[0:1]
	s_cbranch_execz .LBB0_1187
	v_ashrrev_i32_e32 v3, 31, v2
	s_ashr_i32 s85, s84, 31
	v_lshl_add_u64 v[4:5], v[2:3], 0, s[84:85]
	v_mbcnt_lo_u32_b32 v6, -1, 0
	s_lshl_b32 s8, s92, 2
	v_lshlrev_b64 v[2:3], 11, v[4:5]
	v_lshlrev_b64 v[4:5], 6, v[4:5]
	v_mbcnt_hi_u32_b32 v9, -1, v6
	s_ashr_i32 s9, s8, 31
	v_lshl_add_u64 v[4:5], s[54:55], 0, v[4:5]
	s_mov_b64 s[0:1], 0x800
	v_and_b32_e32 v6, 64, v9
	s_lshl_b64 s[10:11], s[8:9], 11
	v_lshl_add_u64 v[4:5], v[4:5], 0, 0
	s_lshl_b64 s[12:13], s[8:9], 6
	s_mov_b64 s[16:17], 0
	v_mov_b32_e32 v7, 0
	s_mov_b64 s[18:19], 0x2000000
	s_brev_b32 s2, 64
	s_mov_b64 s[20:21], 0x4000000
	s_brev_b32 s3, 32
	v_add_u32_e32 v14, 64, v6
	v_xor_b32_e32 v15, 32, v9
	v_xor_b32_e32 v16, 16, v9
	v_xor_b32_e32 v17, 8, v9
	v_xor_b32_e32 v18, 4, v9
	v_xor_b32_e32 v19, 2, v9
	v_xor_b32_e32 v20, 1, v9
	s_mov_b32 s22, 0x3a800000
	v_mov_b32_e32 v8, 0x358637bd
	s_mov_b32 s4, 0x800000
	s_movk_i32 s5, 0x3fff
.LBB0_1186:
	v_cmp_lt_i32_e32 vcc, v15, v14
	v_mov_b32_e32 v6, v0
	v_lshl_add_u64 v[12:13], s[52:53], 0, v[2:3]
	v_cndmask_b32_e32 v21, v9, v15, vcc
	v_cmp_lt_i32_e32 vcc, v16, v14
	s_add_u32 s52, s52, s10
	s_addc_u32 s53, s53, s11
	v_cndmask_b32_e32 v22, v9, v16, vcc
	v_cmp_lt_i32_e32 vcc, v17, v14
	v_lshlrev_b32_e32 v138, 2, v22
	v_and_b32_e32 v22, 63, v6
	v_cndmask_b32_e32 v23, v9, v17, vcc
	v_cmp_lt_i32_e32 vcc, v18, v14
	v_lshl_add_u64 v[10:11], s[82:83], 0, v[2:3]
	v_add_u32_e32 v1, s8, v1
	v_cndmask_b32_e32 v24, v9, v18, vcc
	v_cmp_lt_i32_e32 vcc, v19, v14
	v_lshlrev_b32_e32 v139, 2, v23
	v_lshlrev_b32_e32 v23, 6, v6
	v_cndmask_b32_e32 v25, v9, v19, vcc
	v_cmp_lt_i32_e32 vcc, v20, v14
	s_add_u32 s82, s82, s10
	v_lshlrev_b32_e32 v6, 5, v22
	v_lshrrev_b32_e32 v144, 1, v22
	v_lshlrev_b32_e32 v144, 20, v144
	v_and_b32_e32 v145, 1, v22
	v_lshl_or_b32 v144, v145, 5, v144
	v_mov_b32_e32 v145, 0
	v_cndmask_b32_e32 v26, v9, v20, vcc
	v_cmp_lt_i32_e32 vcc, s5, v1
	s_addc_u32 s83, s83, s11
	v_lshl_add_u64 v[74:75], v[10:11], 0, v[6:7]
	s_or_b64 s[16:17], vcc, s[16:17]
	v_add_co_u32_e32 v70, vcc, s2, v74
	v_and_b32_e32 v46, 0xfc0, v23
	s_nop 0
	v_addc_co_u32_e32 v71, vcc, 0, v75, vcc
	v_lshl_add_u64 v[62:63], v[12:13], 0, v[6:7]
	v_lshl_add_u64 v[66:67], v[74:75], 0, s[18:19]
	v_add_co_u32_e32 v78, vcc, s3, v74
	v_lshlrev_b32_e32 v140, 2, v24
	v_lshlrev_b32_e32 v141, 2, v25
	v_lshlrev_b32_e32 v142, 2, v26
	global_load_dwordx4 v[10:13], v46, s[24:25] offset:48
	global_load_dwordx4 v[22:25], v46, s[26:27] offset:48
	global_load_dwordx4 v[26:29], v46, s[24:25] offset:32
	global_load_dwordx4 v[30:33], v46, s[26:27] offset:32
	global_load_dwordx4 v[34:37], v46, s[24:25] offset:16
	global_load_dwordx4 v[38:41], v46, s[26:27] offset:16
	global_load_dwordx4 v[42:45], v46, s[24:25]
	s_nop 0
	global_load_dwordx4 v[46:49], v46, s[26:27]
	s_nop 0
	global_load_dwordx4 v[50:53], v[74:75], off offset:16
	global_load_dwordx4 v[54:57], v[74:75], off
	global_load_dwordx4 v[58:61], v[62:63], off offset:16
	s_nop 0
	global_load_dwordx4 v[62:65], v[62:63], off
	v_lshl_add_u64 v[76:77], v[74:75], 0, s[20:21]
	global_load_dwordx4 v[66:69], v[66:67], off offset:16
	s_nop 0
	global_load_dwordx4 v[70:73], v[70:71], off
	v_addc_co_u32_e32 v79, vcc, 0, v75, vcc
	global_load_dwordx4 v[74:77], v[76:77], off offset:16
	s_nop 0
	global_load_dwordx4 v[78:81], v[78:79], off
	v_lshlrev_b32_e32 v21, 2, v21
	v_lshl_add_u64 v[82:83], v[4:5], 0, v[144:145]
	v_lshl_add_u64 v[146:147], v[82:83], 0, s[18:19]
	v_lshl_add_u64 v[4:5], v[4:5], 0, s[12:13]
	s_waitcnt vmcnt(7)
	v_lshlrev_b32_e32 v84, 16, v53
	v_and_b32_e32 v85, 0xffff0000, v53
	s_waitcnt vmcnt(6)
; DEV float bflo(unsigned u) { return __uint_as_float(u << 16); }
; DEV float bfhi(unsigned u) { return __uint_as_float(u & 0xffff0000u); }
; DEV void ph_ynorm_row(const Params& p, int row) {
;     ...
;   for (int br = 0; br < 3; ++br) {
;     const u16* src = p.oattn3 + (size_t)br * T_ * 1024 + (size_t)row * 1024 + c0;
;     u32x4 a = *(const u32x4*)src, b2 = *(const u32x4*)(src + 8);
; #pragma unroll
;     for (int e = 0; e < 4; ++e) { va[2 * e] += bflo(a[e]); va[2 * e + 1] += bfhi(a[e]); va[8 + 2 * e] += bflo(b2[e]); va[8 + 2 * e + 1] += bfhi(b2[e]); }
;   }
;   {
;     const u16* src = p.orn + (size_t)row * 1024 + c0;
;     u32x4 a = *(const u32x4*)src, b2 = *(const u32x4*)(src + 8);
; #pragma unroll
;     for (int e = 0; e < 4; ++e) { vr[2 * e] = bflo(a[e]); vr[2 * e + 1] = bfhi(a[e]); vr[8 + 2 * e] = bflo(b2[e]); vr[8 + 2 * e + 1] = bfhi(b2[e]); }
;   }
;   float sa = 0.f, sr = 0.f;
; #pragma unroll
;   for (int e = 0; e < 16; ++e) { sa += va[e] * va[e]; sr += vr[e] * vr[e]; }
;   sa = wave_sum(sa); sr = wave_sum(sr);
	v_lshlrev_b32_e32 v86, 16, v57
	v_and_b32_e32 v87, 0xffff0000, v57
	v_lshlrev_b32_e32 v88, 16, v52
	v_and_b32_e32 v89, 0xffff0000, v52
	v_lshlrev_b32_e32 v52, 16, v56
	v_and_b32_e32 v53, 0xffff0000, v56
	v_lshlrev_b32_e32 v56, 16, v51
	v_and_b32_e32 v57, 0xffff0000, v51
	v_lshlrev_b32_e32 v92, 16, v50
	v_and_b32_e32 v93, 0xffff0000, v50
	v_lshlrev_b32_e32 v50, 16, v54
	v_and_b32_e32 v51, 0xffff0000, v54
	v_pk_add_f32 v[50:51], v[50:51], 0 op_sel_hi:[1,0]
	s_waitcnt vmcnt(3)
	v_lshlrev_b32_e32 v128, 16, v69
	v_and_b32_e32 v129, 0xffff0000, v69
	s_waitcnt vmcnt(2)
	v_lshlrev_b32_e32 v130, 16, v73
	v_and_b32_e32 v131, 0xffff0000, v73
	v_lshlrev_b32_e32 v132, 16, v68
	v_and_b32_e32 v133, 0xffff0000, v68
	v_lshlrev_b32_e32 v68, 16, v72
	v_and_b32_e32 v69, 0xffff0000, v72
	v_lshlrev_b32_e32 v72, 16, v67
	v_and_b32_e32 v73, 0xffff0000, v67
	v_lshlrev_b32_e32 v136, 16, v66
	v_and_b32_e32 v137, 0xffff0000, v66
	v_lshlrev_b32_e32 v66, 16, v70
	v_and_b32_e32 v67, 0xffff0000, v70
	v_lshlrev_b32_e32 v90, 16, v55
	v_and_b32_e32 v91, 0xffff0000, v55
	v_pk_add_f32 v[50:51], v[50:51], v[66:67]
	s_waitcnt vmcnt(0)
	v_lshlrev_b32_e32 v66, 16, v78
	v_and_b32_e32 v67, 0xffff0000, v78
	v_lshlrev_b32_e32 v54, 16, v61
	v_and_b32_e32 v55, 0xffff0000, v61
	v_lshlrev_b32_e32 v94, 16, v65
	v_and_b32_e32 v95, 0xffff0000, v65
	v_lshlrev_b32_e32 v96, 16, v60
	v_and_b32_e32 v97, 0xffff0000, v60
	v_lshlrev_b32_e32 v60, 16, v64
	v_and_b32_e32 v61, 0xffff0000, v64
	v_lshlrev_b32_e32 v64, 16, v59
	v_and_b32_e32 v65, 0xffff0000, v59
	v_lshlrev_b32_e32 v98, 16, v63
	v_and_b32_e32 v99, 0xffff0000, v63
	v_lshlrev_b32_e32 v100, 16, v58
	v_and_b32_e32 v101, 0xffff0000, v58
	v_lshlrev_b32_e32 v58, 16, v62
	v_and_b32_e32 v59, 0xffff0000, v62
	v_pk_add_f32 v[62:63], v[84:85], 0 op_sel_hi:[1,0]
	v_pk_add_f32 v[84:85], v[86:87], 0 op_sel_hi:[1,0]
	v_pk_add_f32 v[86:87], v[88:89], 0 op_sel_hi:[1,0]
	v_pk_add_f32 v[52:53], v[52:53], 0 op_sel_hi:[1,0]
	v_pk_add_f32 v[88:89], v[90:91], 0 op_sel_hi:[1,0]
	v_lshlrev_b32_e32 v134, 16, v71
	v_and_b32_e32 v135, 0xffff0000, v71
	v_pk_add_f32 v[50:51], v[50:51], v[66:67]
	v_mov_b32_e32 v108, v59
	v_pk_add_f32 v[62:63], v[62:63], v[128:129]
	v_lshlrev_b32_e32 v128, 16, v77
	v_and_b32_e32 v129, 0xffff0000, v77
	v_pk_add_f32 v[84:85], v[84:85], v[130:131]
	v_lshlrev_b32_e32 v130, 16, v81
	v_and_b32_e32 v131, 0xffff0000, v81
	v_pk_add_f32 v[86:87], v[86:87], v[132:133]
	v_lshlrev_b32_e32 v132, 16, v76
	v_and_b32_e32 v133, 0xffff0000, v76
	v_pk_add_f32 v[52:53], v[52:53], v[68:69]
	v_lshlrev_b32_e32 v68, 16, v80
	v_and_b32_e32 v69, 0xffff0000, v80
	v_pk_add_f32 v[76:77], v[88:89], v[134:135]
	v_lshlrev_b32_e32 v80, 16, v79
	v_and_b32_e32 v81, 0xffff0000, v79
	v_mov_b32_e32 v109, v51
	v_mov_b32_e32 v106, v58
	v_pk_add_f32 v[52:53], v[52:53], v[68:69]
	v_pk_add_f32 v[68:69], v[76:77], v[80:81]
	v_mov_b32_e32 v107, v50
	v_pk_mul_f32 v[80:81], v[108:109], v[108:109]
	v_mov_b32_e32 v104, v98
	v_mov_b32_e32 v105, v68
	v_pk_fma_f32 v[80:81], v[106:107], v[106:107], v[80:81]
	v_mov_b32_e32 v122, v99
	v_mov_b32_e32 v123, v69
	v_pk_fma_f32 v[80:81], v[104:105], v[104:105], v[80:81]
	v_pk_add_f32 v[56:57], v[56:57], 0 op_sel_hi:[1,0]
	v_pk_add_f32 v[90:91], v[92:93], 0 op_sel_hi:[1,0]
	v_mov_b32_e32 v114, v60
	v_mov_b32_e32 v115, v52
	v_pk_fma_f32 v[80:81], v[122:123], v[122:123], v[80:81]
	v_mov_b32_e32 v116, v61
	v_pk_add_f32 v[56:57], v[56:57], v[72:73]
	v_lshlrev_b32_e32 v72, 16, v75
	v_and_b32_e32 v73, 0xffff0000, v75
	v_pk_add_f32 v[88:89], v[90:91], v[136:137]
	v_lshlrev_b32_e32 v90, 16, v74
	v_and_b32_e32 v91, 0xffff0000, v74
	v_pk_add_f32 v[74:75], v[84:85], v[130:131]
	v_mov_b32_e32 v117, v53
	v_pk_fma_f32 v[80:81], v[114:115], v[114:115], v[80:81]
	v_mov_b32_e32 v110, v94
	v_mov_b32_e32 v111, v74
	v_pk_fma_f32 v[80:81], v[116:117], v[116:117], v[80:81]
	v_mov_b32_e32 v112, v95
	v_pk_add_f32 v[56:57], v[56:57], v[72:73]
	v_pk_add_f32 v[72:73], v[88:89], v[90:91]
	v_mov_b32_e32 v113, v75
	v_pk_fma_f32 v[80:81], v[110:111], v[110:111], v[80:81]
	v_mov_b32_e32 v124, v100
	v_mov_b32_e32 v125, v72
	v_pk_fma_f32 v[80:81], v[112:113], v[112:113], v[80:81]
	v_mov_b32_e32 v126, v101
	v_mov_b32_e32 v127, v73
	v_pk_fma_f32 v[80:81], v[124:125], v[124:125], v[80:81]
	v_mov_b32_e32 v118, v64
	v_pk_add_f32 v[78:79], v[86:87], v[132:133]
	v_mov_b32_e32 v119, v56
	v_pk_fma_f32 v[80:81], v[126:127], v[126:127], v[80:81]
	v_pk_mul_f32 v[102:103], v[96:97], v[96:97]
	v_mov_b32_e32 v120, v65
	v_pk_mul_f32 v[76:77], v[78:79], v[78:79]
	v_mov_b32_e32 v121, v57
	v_pk_fma_f32 v[80:81], v[118:119], v[118:119], v[80:81]
	v_mov_b32_e32 v70, v102
	v_pk_add_f32 v[62:63], v[62:63], v[128:129]
	v_mov_b32_e32 v71, v76
	v_pk_fma_f32 v[80:81], v[120:121], v[120:121], v[80:81]
	v_pk_mul_f32 v[92:93], v[54:55], v[54:55]
	v_pk_mul_f32 v[66:67], v[62:63], v[62:63]
	v_mov_b32_e32 v76, v103
	v_pk_add_f32 v[70:71], v[70:71], v[80:81]
	v_mov_b32_e32 v102, v92
	v_mov_b32_e32 v103, v66
	v_pk_add_f32 v[70:71], v[76:77], v[70:71]
	v_mov_b32_e32 v66, v93
	v_pk_add_f32 v[70:71], v[102:103], v[70:71]
	s_nop 0
	v_pk_add_f32 v[66:67], v[66:67], v[70:71]
	ds_bpermute_b32 v71, v21, v67
	ds_bpermute_b32 v70, v21, v66
	s_waitcnt lgkmcnt(0)
; DEV unsigned pack2(float a, float b) { float2v v = {a, b}; return __builtin_bit_cast(unsigned, __builtin_convertvector(v, bf16x2v)); }
; DEV void ph_ynorm_row(const Params& p, int row) {
;     ...
;   sa = wave_sum(sa); sr = wave_sum(sr);
;   const float ra = rsqrtf(sa * (1.f / 1024.f) + 1e-6f), rr = rsqrtf(sr * (1.f / 1024.f) + 1e-6f);
;   u32x4 o0, o1, o2, o3;
; #pragma unroll
;   for (int e = 0; e < 4; ++e) {
;     o0[e] = pack2(va[2 * e] * ra * p.out_g_attn[c0 + 2 * e], va[2 * e + 1] * ra * p.out_g_attn[c0 + 2 * e + 1]);
;     o1[e] = pack2(va[8 + 2 * e] * ra * p.out_g_attn[c0 + 8 + 2 * e], va[8 + 2 * e + 1] * ra * p.out_g_attn[c0 + 8 + 2 * e + 1]);
;     o2[e] = pack2(vr[2 * e] * rr * p.out_g_rnn[c0 + 2 * e], vr[2 * e + 1] * rr * p.out_g_rnn[c0 + 2 * e + 1]);
;     o3[e] = pack2(vr[8 + 2 * e] * rr * p.out_g_rnn[c0 + 8 + 2 * e], vr[8 + 2 * e + 1] * rr * p.out_g_rnn[c0 + 8 + 2 * e + 1]);
;   }
;   u16* dst = p.y + (size_t)row * 2048;
;   *(u32x4*)(dst + c0) = o0; *(u32x4*)(dst + c0 + 8) = o1;
;   *(u32x4*)(dst + 1024 + c0) = o2; *(u32x4*)(dst + 1024 + c0 + 8) = o3;
	v_pk_add_f32 v[66:67], v[66:67], v[70:71]
	ds_bpermute_b32 v71, v138, v67
	ds_bpermute_b32 v70, v138, v66
	s_waitcnt lgkmcnt(0)
	v_pk_add_f32 v[66:67], v[66:67], v[70:71]
	ds_bpermute_b32 v71, v139, v67
	ds_bpermute_b32 v70, v139, v66
	s_waitcnt lgkmcnt(0)
	v_pk_add_f32 v[66:67], v[66:67], v[70:71]
	ds_bpermute_b32 v71, v140, v67
	ds_bpermute_b32 v70, v140, v66
	s_waitcnt lgkmcnt(0)
	v_pk_add_f32 v[66:67], v[66:67], v[70:71]
	ds_bpermute_b32 v71, v141, v67
	ds_bpermute_b32 v70, v141, v66
	s_waitcnt lgkmcnt(0)
	v_pk_add_f32 v[66:67], v[66:67], v[70:71]
	ds_bpermute_b32 v71, v142, v67
	ds_bpermute_b32 v70, v142, v66
	s_waitcnt lgkmcnt(0)
	v_pk_add_f32 v[66:67], v[66:67], v[70:71]
	s_nop 0
	v_pk_fma_f32 v[66:67], v[66:67], s[22:23], v[8:9] op_sel_hi:[1,0,0]
	s_nop 0
	v_mul_f32_e32 v6, 0x4b800000, v67
	v_cmp_gt_f32_e64 s[0:1], s4, v67
	v_mul_f32_e32 v21, 0x4b800000, v66
	v_cmp_gt_f32_e32 vcc, s4, v66
	v_cndmask_b32_e64 v6, v67, v6, s[0:1]
	v_rsq_f32_e32 v6, v6
	v_cndmask_b32_e32 v21, v66, v21, vcc
	v_rsq_f32_e32 v21, v21
	v_mul_f32_e32 v66, 0x45800000, v6
	v_cndmask_b32_e64 v6, v6, v66, s[0:1]
	v_mul_f32_e32 v67, 0x45800000, v21
	v_cndmask_b32_e32 v66, v21, v67, vcc
	v_pk_mul_f32 v[50:51], v[50:51], v[6:7] op_sel_hi:[1,0]
	v_pk_mul_f32 v[68:69], v[68:69], v[6:7] op_sel_hi:[1,0]
	v_pk_mul_f32 v[52:53], v[52:53], v[6:7] op_sel_hi:[1,0]
	v_pk_mul_f32 v[74:75], v[74:75], v[6:7] op_sel_hi:[1,0]
	v_pk_mul_f32 v[70:71], v[72:73], v[6:7] op_sel_hi:[1,0]
	v_pk_mul_f32 v[56:57], v[56:57], v[6:7] op_sel_hi:[1,0]
	v_pk_mul_f32 v[72:73], v[78:79], v[6:7] op_sel_hi:[1,0]
	v_pk_mul_f32 v[62:63], v[62:63], v[6:7] op_sel_hi:[1,0]
	v_pk_mul_f32 v[58:59], v[66:67], v[58:59] op_sel_hi:[0,1]
	v_pk_mul_f32 v[76:77], v[66:67], v[100:101] op_sel_hi:[0,1]
	v_pk_mul_f32 v[78:79], v[66:67], v[98:99] op_sel_hi:[0,1]
	v_pk_mul_f32 v[64:65], v[66:67], v[64:65] op_sel_hi:[0,1]
	v_pk_mul_f32 v[60:61], v[66:67], v[60:61] op_sel_hi:[0,1]
	v_pk_mul_f32 v[80:81], v[66:67], v[96:97] op_sel_hi:[0,1]
	v_pk_mul_f32 v[84:85], v[66:67], v[94:95] op_sel_hi:[0,1]
	v_pk_mul_f32 v[54:55], v[66:67], v[54:55] op_sel_hi:[0,1]
	v_pk_mul_f32 v[42:43], v[42:43], v[50:51]
	v_pk_mul_f32 v[44:45], v[44:45], v[68:69]
	v_pk_mul_f32 v[34:35], v[52:53], v[34:35]
	v_pk_mul_f32 v[36:37], v[74:75], v[36:37]
	v_pk_mul_f32 v[26:27], v[26:27], v[70:71]
	v_pk_mul_f32 v[28:29], v[28:29], v[56:57]
	v_pk_mul_f32 v[50:51], v[72:73], v[10:11]
	v_pk_mul_f32 v[52:53], v[62:63], v[12:13]
	v_pk_mul_f32 v[46:47], v[46:47], v[58:59]
	v_pk_mul_f32 v[30:31], v[30:31], v[76:77]
	v_pk_mul_f32 v[48:49], v[48:49], v[78:79]
	v_pk_mul_f32 v[32:33], v[32:33], v[64:65]
	v_pk_mul_f32 v[38:39], v[60:61], v[38:39]
	v_pk_mul_f32 v[56:57], v[80:81], v[22:23]
	v_pk_mul_f32 v[40:41], v[84:85], v[40:41]
	v_pk_mul_f32 v[54:55], v[54:55], v[24:25]
	v_cvt_pk_bf16_f32 v10, v42, v43
	v_cvt_pk_bf16_f32 v11, v44, v45
	v_cvt_pk_bf16_f32 v12, v34, v35
	v_cvt_pk_bf16_f32 v13, v36, v37
	v_cvt_pk_bf16_f32 v22, v26, v27
	v_cvt_pk_bf16_f32 v23, v28, v29
	v_cvt_pk_bf16_f32 v24, v50, v51
	v_cvt_pk_bf16_f32 v25, v52, v53
	v_cvt_pk_bf16_f32 v26, v46, v47
	v_cvt_pk_bf16_f32 v30, v30, v31
	v_cvt_pk_bf16_f32 v27, v48, v49
	v_cvt_pk_bf16_f32 v31, v32, v33
	v_cvt_pk_bf16_f32 v28, v38, v39
	v_cvt_pk_bf16_f32 v32, v56, v57
	v_cvt_pk_bf16_f32 v29, v40, v41
	v_cvt_pk_bf16_f32 v33, v54, v55
	global_store_dwordx4 v[82:83], v[10:13], off
	global_store_dwordx4 v[82:83], v[22:25], off offset:16
	global_store_dwordx4 v[146:147], v[26:29], off
	global_store_dwordx4 v[146:147], v[30:33], off offset:16
	s_andn2_b64 exec, exec, s[16:17]
	s_cbranch_execnz .LBB0_1186

; template <class AF, class EPI>
; DEV void gemm_tile256(AF aptr, const u16* Bt, int ldb, int K, EPI epi, char* smem) {
;     ...
;   auto stage = [&](int kt, int buf) {
;     char* SA = smem + buf * 24576;
;     char* SB = SA + 16384;
; #pragma unroll
;     for (int i = 0; i < 4; ++i) {
;       int bo = tid * 16 + i * 4096, r = bo >> 6, c = (bo & 63) >> 1;
;       __builtin_amdgcn_global_load_lds((const unsigned*)aptr(r, kt * 32 + c), (__attribute__((address_space(3))) unsigned*)(SA + bo), 16, 0, 0);
;     }
; #pragma unroll
;     for (int i = 0; i < 2; ++i) {
;       int bo = tid * 16 + i * 4096, r = bo >> 6, c = (bo & 63) >> 1;
;       __builtin_amdgcn_global_load_lds((const unsigned*)(Bt + (size_t)r * ldb + kt * 32 + c), (__attribute__((address_space(3))) unsigned*)(SB + bo), 16, 0, 0);
;     }
;   };
;   asm volatile("s_waitcnt vmcnt(0)" ::: "memory");
;   __syncthreads();
;   stage(0, 0);
;   stage(1, 1);
;   const unsigned lbase = (unsigned)(size_t)(const __attribute__((address_space(3))) char*)smem;
;   const unsigned aoff = lbase + (wr * 128 + fr) * 64 + fq * 16, boff = lbase + 16384 + (wc * 64 + fr) * 64 + fq * 16;
; __global__ void __launch_bounds__(256, 2) fwd_megakernel(Params p) {
;     ...
;   for (int jt = (bid >> 3); jt < 8 * 16; jt += (nb >> 3)) {
;     const int pn = jt >> 3, pm = (bid & 7) * 8 + (jt & 7), b = pm >> 3;
;     const u16* A = p.y + (size_t)pm * 256 * 2048;
;     const float* gt1 = p.mod + (size_t)b * 12288 + 4096 + pn * 128;
;     gemm_tile256([&](int r, int k) { return A + (size_t)r * 2048 + k; }, p.Wt_out + (size_t)pn * 128 * 2048, 2048, 2048,
.LBB0_1239:
	s_or_b64 exec, exec, s[0:1]
	s_cmpk_lt_i32 s58, 0x80
	v_mov_b32_e32 v1, v0
	s_cselect_b64 s[0:1], -1, 0
	s_cmpk_gt_i32 s58, 0x7f
	s_movk_i32 s2, 0x80
	s_waitcnt lgkmcnt(0)
	s_barrier
	s_cbranch_scc1 .LBB0_1258
	s_lshl_b32 s4, s94, 3
	s_and_b32 s6, s94, 7
	s_lshr_b32 s3, s94, 3
	s_and_b32 s4, s4, 56
	s_mul_i32 s5, s6, 0xc000
	s_mov_b64 s[10:11], s[78:79]
	s_add_u32 s5, s10, s5
	s_addc_u32 s7, s11, 0
	s_add_u32 s5, s5, 0x4000
	s_addc_u32 s12, s7, 0
	s_ashr_i32 s13, s92, 3
	s_mov_b64 s[14:15], s[54:55]
	v_readlane_b32 s36, v254, 4
	s_add_u32 s14, s14, 0x200000
	v_readlane_b32 s48, v254, 16
	v_readlane_b32 s49, v254, 17
	s_addc_u32 s15, s15, 0
	s_lshl_b32 s16, s6, 22
	v_readlane_b32 s50, v254, 18
	v_readlane_b32 s51, v254, 19
	s_mov_b64 s[28:29], s[48:49]
	v_readlane_b32 s37, v254, 5
	v_readlane_b32 s38, v254, 6
	v_readlane_b32 s39, v254, 7
	v_readlane_b32 s40, v254, 8
	v_readlane_b32 s41, v254, 9
	v_readlane_b32 s42, v254, 10
	v_readlane_b32 s43, v254, 11
	v_readlane_b32 s44, v254, 12
	v_readlane_b32 s45, v254, 13
	v_readlane_b32 s46, v254, 14
	v_readlane_b32 s47, v254, 15
	s_add_u32 s17, s28, 0x40000
	s_mov_b64 s[30:31], s[50:51]
	v_readlane_b32 s36, v254, 25
	s_addc_u32 s18, s29, 0
	v_mov_b32_e32 v135, 0
	s_movk_i32 s19, 0x4000
	s_movk_i32 s20, 0x210
	s_mov_b32 s21, 0x10000
	s_mov_b32 s22, 0x20000
	s_mov_b32 s23, 0x30000
	s_mov_b32 s24, s58
	v_readlane_b32 s37, v254, 26
	v_readlane_b32 s38, v254, 27
	v_readlane_b32 s39, v254, 28
	v_readlane_b32 s40, v254, 29
	v_readlane_b32 s41, v254, 30
	v_readlane_b32 s42, v254, 31
	v_readlane_b32 s43, v254, 32
	v_readlane_b32 s44, v254, 33
	v_readlane_b32 s45, v254, 34
	v_readlane_b32 s46, v254, 35
	v_readlane_b32 s47, v254, 36
	v_readlane_b32 s48, v254, 37
	v_readlane_b32 s49, v254, 38
	v_readlane_b32 s50, v254, 39
	v_readlane_b32 s51, v254, 40
.LBB0_1241:
	s_and_b32 s6, s3, 7
	s_lshl_b32 s6, s6, 19
	s_and_b32 s7, s24, 7
	s_add_i32 s25, s16, s6
	s_or_b32 s7, s7, s4
	v_mov_b32_e32 v144, v0
	s_lshr_b32 s28, s25, 5
	s_ashr_i32 s6, s24, 3
	s_lshl_b32 s7, s7, 14
	s_mov_b64 s[26:27], s[54:55]
	s_add_u32 s10, s26, s7
	v_ashrrev_i32_e32 v2, 2, v144
	v_lshlrev_b32_e32 v148, 4, v144
	v_ashrrev_i32_e32 v3, 31, v2
	s_addc_u32 s11, s27, 0
	s_ashr_i32 s7, s6, 31
	v_lshlrev_b64 v[2:3], 12, v[2:3]
	v_lshrrev_b64 v[246:247], 6, v[2:3]
	s_mov_b64 s[32:33], 0x100000
	s_mov_b64 s[34:35], 0x20000
	v_add_u32_e32 v10, 0x1000, v148
	s_lshl_b64 s[8:9], s[6:7], 13
	v_lshl_add_u64 v[4:5], s[10:11], 0, v[246:247]
	v_and_b32_e32 v134, 48, v148
	v_and_b32_e32 v253, 32, v144
	v_xor_b32_e32 v134, v134, v253
	v_readfirstlane_b32 s7, v148
	v_ashrrev_i32_e32 v6, 6, v10
	v_add_u32_e32 v14, 0x2000, v148
	v_lshl_add_u64 v[4:5], v[4:5], 0, v[134:135]
	s_mov_b32 m0, s7
	v_ashrrev_i32_e32 v7, 31, v6
	v_readfirstlane_b32 s7, v10
	v_ashrrev_i32_e32 v10, 6, v14
	v_add_u32_e32 v18, 0x3000, v148
	v_readlane_b32 s36, v254, 4
	s_waitcnt vmcnt(0)
	s_barrier
; template <class AF, class EPI>
; DEV void gemm_tile256(AF aptr, const u16* Bt, int ldb, int K, EPI epi, char* smem) {
;     ...
;   auto stage = [&](int kt, int buf) {
;     char* SA = smem + buf * 24576;
;     char* SB = SA + 16384;
; #pragma unroll
;     for (int i = 0; i < 4; ++i) {
;       int bo = tid * 16 + i * 4096, r = bo >> 6, c = (bo & 63) >> 1;
;       __builtin_amdgcn_global_load_lds((const unsigned*)aptr(r, kt * 32 + c), (__attribute__((address_space(3))) unsigned*)(SA + bo), 16, 0, 0);
;     }
; #pragma unroll
;     for (int i = 0; i < 2; ++i) {
;       int bo = tid * 16 + i * 4096, r = bo >> 6, c = (bo & 63) >> 1;
;       __builtin_amdgcn_global_load_lds((const unsigned*)(Bt + (size_t)r * ldb + kt * 32 + c), (__attribute__((address_space(3))) unsigned*)(SB + bo), 16, 0, 0);
;     }
;   };
;   asm volatile("s_waitcnt vmcnt(0)" ::: "memory");
;   __syncthreads();
;   stage(0, 0);
;   stage(1, 1);
;   const unsigned lbase = (unsigned)(size_t)(const __attribute__((address_space(3))) char*)smem;
;   const unsigned aoff = lbase + (wr * 128 + fr) * 64 + fq * 16, boff = lbase + 16384 + (wc * 64 + fr) * 64 + fq * 16;
	global_load_lds_dwordx4 v[4:5], off
	v_lshlrev_b64 v[6:7], 12, v[6:7]
	v_lshrrev_b64 v[248:249], 6, v[6:7]
	s_mov_b32 m0, s7
	v_ashrrev_i32_e32 v11, 31, v10
	v_readfirstlane_b32 s7, v14
	v_ashrrev_i32_e32 v14, 6, v18
	v_readlane_b32 s48, v254, 16
	v_lshl_add_u64 v[8:9], s[10:11], 0, v[248:249]
	v_lshlrev_b64 v[10:11], 6, v[10:11]
	v_ashrrev_i32_e32 v15, 31, v14
	v_readlane_b32 s49, v254, 17
	s_add_u32 s26, s48, s8
	v_lshl_add_u64 v[8:9], v[8:9], 0, v[134:135]
	v_lshl_add_u64 v[12:13], s[10:11], 0, v[10:11]
	v_lshlrev_b64 v[14:15], 6, v[14:15]
	s_addc_u32 s27, s49, s9
	global_load_lds_dwordx4 v[8:9], off
	v_lshl_add_u64 v[12:13], v[12:13], 0, v[134:135]
	s_mov_b32 m0, s7
	v_lshl_add_u64 v[16:17], s[10:11], 0, v[14:15]
	v_readfirstlane_b32 s7, v18
	v_add_u32_e32 v20, 0x4000, v148
	global_load_lds_dwordx4 v[12:13], off
	v_lshl_add_u64 v[16:17], v[16:17], 0, v[134:135]
	s_mov_b32 m0, s7
	v_lshl_add_u64 v[18:19], s[26:27], 0, v[246:247]
	v_readfirstlane_b32 s7, v20
	v_add_u32_e32 v22, 0x5000, v148
	global_load_lds_dwordx4 v[16:17], off
	v_lshl_add_u64 v[18:19], v[18:19], 0, v[134:135]
	s_mov_b32 m0, s7
	v_lshl_add_u64 v[20:21], s[26:27], 0, v[248:249]
	v_readfirstlane_b32 s7, v22
	v_add_u32_e32 v22, 0x6000, v148
	global_load_lds_dwordx4 v[18:19], off
	v_lshl_add_u64 v[20:21], v[20:21], 0, v[134:135]
	s_mov_b32 m0, s7
	v_readfirstlane_b32 s7, v22
	global_load_lds_dwordx4 v[20:21], off
	v_lshl_add_u64 v[4:5], v[4:5], 0, s[32:33]
	s_mov_b32 m0, s7
	s_add_u32 s10, s14, s28
	global_load_lds_dwordx4 v[4:5], off
	v_lshl_add_u64 v[4:5], v[8:9], 0, s[32:33]
	v_add_u32_e32 v8, 0x7000, v148
	v_bfe_u32 v147, v144, 4, 2
	v_readfirstlane_b32 s7, v8
	v_add_u32_e32 v8, 0x8000, v148
	s_mov_b32 m0, s7
	v_readfirstlane_b32 s7, v8
	v_add_u32_e32 v8, 0x9000, v148
	global_load_lds_dwordx4 v[4:5], off
	v_lshl_add_u64 v[4:5], v[12:13], 0, s[32:33]
	s_mov_b32 m0, s7
	v_readfirstlane_b32 s7, v8
	v_add_u32_e32 v8, 0xa000, v148
	global_load_lds_dwordx4 v[4:5], off
	v_lshl_add_u64 v[4:5], v[16:17], 0, s[32:33]
	s_mov_b32 m0, s7
	v_readfirstlane_b32 s7, v8
	v_add_u32_e32 v8, 0xb000, v148
	global_load_lds_dwordx4 v[4:5], off
	v_lshl_add_u64 v[4:5], v[18:19], 0, s[34:35]
	s_mov_b32 m0, s7
	v_readfirstlane_b32 s7, v8
	global_load_lds_dwordx4 v[4:5], off
	v_lshl_add_u64 v[4:5], v[20:21], 0, s[34:35]
	s_mov_b32 m0, s7
	s_addc_u32 s11, s15, 0
	global_load_lds_dwordx4 v[4:5], off
	v_bfe_u32 v145, v144, 6, 1
	v_ashrrev_i32_e32 v1, 7, v144
	v_and_b32_e32 v146, 15, v144
	v_lshlrev_b32_e32 v8, 4, v147
	v_lshlrev_b32_e32 v253, 2, v144
	v_and_b32_e32 v253, 32, v253
	v_xor_b32_e32 v8, v8, v253
	s_add_u32 s8, s17, s8
	v_lshlrev_b32_e32 v4, 13, v1
	v_lshlrev_b32_e32 v5, 6, v146
	v_lshl_or_b32 v9, v145, 12, v8
	v_or_b32_e32 v2, v2, v134
	v_or_b32_e32 v6, v6, v134
	v_or_b32_e32 v10, v10, v134
	v_or_b32_e32 v14, v14, v134
	s_addc_u32 s9, s18, s9
	v_or3_b32 v149, v4, v8, v5
	v_or3_b32 v150, v5, v9, s19
	v_or_b32_e32 v246, v246, v134
	v_or_b32_e32 v248, v248, v134
	v_lshl_add_u64 v[130:131], s[10:11], 0, v[246:247]
	v_lshl_add_u64 v[132:133], s[10:11], 0, v[248:249]
	v_lshl_add_u64 v[136:137], s[10:11], 0, v[10:11]
	v_lshl_add_u64 v[138:139], s[10:11], 0, v[14:15]
	v_lshl_add_u64 v[140:141], s[8:9], 0, v[248:249]
	v_lshl_add_u64 v[142:143], s[8:9], 0, v[246:247]
	s_mov_b64 s[8:9], 0
	s_mov_b32 s7, 0
	s_mov_b32 s26, 0
	v_mov_b32_e32 v2, 0
	v_mov_b32_e32 v3, v135
	v_mov_b32_e32 v4, v135
	v_mov_b32_e32 v5, v135
	v_mov_b32_e32 v6, 0
	v_mov_b32_e32 v7, v135
	v_mov_b32_e32 v8, v135
	v_mov_b32_e32 v9, v135
	v_mov_b32_e32 v10, 0
	v_mov_b32_e32 v11, v135
	v_mov_b32_e32 v12, v135
	v_mov_b32_e32 v13, v135
	v_mov_b32_e32 v14, 0
	v_mov_b32_e32 v15, v135
	v_mov_b32_e32 v16, v135
	v_mov_b32_e32 v17, v135
	v_mov_b32_e32 v18, 0
	v_mov_b32_e32 v19, v135
	v_mov_b32_e32 v20, v135
	v_mov_b32_e32 v21, v135
	v_mov_b32_e32 v22, 0
	v_mov_b32_e32 v23, v135
	v_mov_b32_e32 v24, v135
	v_mov_b32_e32 v25, v135
	v_mov_b32_e32 v26, 0
	v_mov_b32_e32 v27, v135
	v_mov_b32_e32 v28, v135
	v_mov_b32_e32 v29, v135
	v_mov_b32_e32 v30, 0
	v_mov_b32_e32 v31, v135
	v_mov_b32_e32 v32, v135
	v_mov_b32_e32 v33, v135
	v_mov_b32_e32 v34, 0
	v_mov_b32_e32 v35, v135
	v_mov_b32_e32 v36, v135
	v_mov_b32_e32 v37, v135
	v_mov_b32_e32 v38, 0
	v_mov_b32_e32 v39, v135
	v_mov_b32_e32 v40, v135
	v_mov_b32_e32 v41, v135
	v_mov_b32_e32 v42, 0
	v_mov_b32_e32 v43, v135
	v_mov_b32_e32 v44, v135
	v_mov_b32_e32 v45, v135
	v_mov_b32_e32 v94, 0
	v_mov_b32_e32 v95, v135
	v_mov_b32_e32 v96, v135
	v_mov_b32_e32 v97, v135
	v_mov_b32_e32 v98, 0
	v_mov_b32_e32 v99, v135
	v_mov_b32_e32 v100, v135
	v_mov_b32_e32 v101, v135
	v_mov_b32_e32 v102, 0
	v_mov_b32_e32 v103, v135
	v_mov_b32_e32 v104, v135
	v_mov_b32_e32 v105, v135
	v_mov_b32_e32 v106, 0
	v_mov_b32_e32 v107, v135
	v_mov_b32_e32 v108, v135
	v_mov_b32_e32 v109, v135
	v_mov_b32_e32 v110, 0
	v_mov_b32_e32 v111, v135
	v_mov_b32_e32 v112, v135
	v_mov_b32_e32 v113, v135
	v_mov_b32_e32 v114, 0
	v_mov_b32_e32 v115, v135
	v_mov_b32_e32 v116, v135
	v_mov_b32_e32 v117, v135
	v_mov_b32_e32 v118, 0
	v_mov_b32_e32 v119, v135
	v_mov_b32_e32 v120, v135
	v_mov_b32_e32 v121, v135
	v_mov_b32_e32 v122, 0
	v_mov_b32_e32 v123, v135
	v_mov_b32_e32 v124, v135
	v_mov_b32_e32 v125, v135
	v_mov_b32_e32 v126, 0
	v_mov_b32_e32 v127, v135
	v_mov_b32_e32 v128, v135
	v_mov_b32_e32 v129, v135
	v_mov_b32_e32 v46, 0
	v_mov_b32_e32 v47, v135
	v_mov_b32_e32 v48, v135
	v_mov_b32_e32 v49, v135
	v_mov_b32_e32 v50, 0
	v_mov_b32_e32 v51, v135
	v_mov_b32_e32 v52, v135
	v_mov_b32_e32 v53, v135
	v_mov_b32_e32 v54, 0
	v_mov_b32_e32 v55, v135
	v_mov_b32_e32 v56, v135
	v_mov_b32_e32 v57, v135
	v_mov_b32_e32 v58, 0
	v_mov_b32_e32 v59, v135
	v_mov_b32_e32 v60, v135
	v_mov_b32_e32 v61, v135
	v_mov_b32_e32 v62, 0
	v_mov_b32_e32 v63, v135
	v_mov_b32_e32 v64, v135
	v_mov_b32_e32 v65, v135
	v_mov_b32_e32 v66, 0
	v_mov_b32_e32 v67, v135
	v_mov_b32_e32 v68, v135
	v_mov_b32_e32 v69, v135
	v_mov_b32_e32 v70, 0
	v_mov_b32_e32 v71, v135
	v_mov_b32_e32 v72, v135
	v_mov_b32_e32 v73, v135
	v_mov_b32_e32 v74, 0
	v_mov_b32_e32 v75, v135
	v_mov_b32_e32 v76, v135
	v_mov_b32_e32 v77, v135
	v_mov_b32_e32 v78, 0
	v_mov_b32_e32 v79, v135
	v_mov_b32_e32 v80, v135
	v_mov_b32_e32 v81, v135
	v_mov_b32_e32 v82, 0
	v_mov_b32_e32 v83, v135
	v_mov_b32_e32 v84, v135
	v_mov_b32_e32 v85, v135
	v_mov_b32_e32 v86, 0
	v_mov_b32_e32 v87, v135
	v_mov_b32_e32 v88, v135
	v_mov_b32_e32 v89, v135
	v_mov_b32_e32 v90, 0
	v_mov_b32_e32 v91, v135
	v_mov_b32_e32 v92, v135
	v_mov_b32_e32 v93, v135
	v_readlane_b32 s37, v254, 5
	v_readlane_b32 s38, v254, 6
	v_readlane_b32 s39, v254, 7
	v_readlane_b32 s40, v254, 8
	v_readlane_b32 s41, v254, 9
	v_readlane_b32 s42, v254, 10
	v_readlane_b32 s43, v254, 11
	v_readlane_b32 s44, v254, 12
	v_readlane_b32 s45, v254, 13
	v_readlane_b32 s46, v254, 14
	v_readlane_b32 s47, v254, 15
	v_readlane_b32 s50, v254, 18
	v_readlane_b32 s51, v254, 19
	s_branch .LBB0_1243

; template <class AF, class EPI>
; DEV void gemm_tile256(AF aptr, const u16* Bt, int ldb, int K, EPI epi, char* smem) {
;     ...
;   for (int t = 0; t < nk; ++t) {
;     if (t + 1 < nk) asm volatile("s_waitcnt vmcnt(6)" ::: "memory");
;     else asm volatile("s_waitcnt vmcnt(0)" ::: "memory");
;     __builtin_amdgcn_s_barrier();
;     if (t + 2 < nk) { int nb2 = buf + 2; if (nb2 >= 3) nb2 -= 3; stage(t + 2, nb2); }
;     const unsigned sa = aoff + buf * 24576, sb = boff + buf * 24576;
;     u32x4 a0, a1, a2, a3, a4, a5, a6, a7, b0, b1, b2, b3;
;     asm volatile("ds_read_b128 %0, %1" : "=v"(b0) : "v"(sb));
;     asm volatile("ds_read_b128 %0, %1 offset:1024" : "=v"(b1) : "v"(sb));
;     asm volatile("ds_read_b128 %0, %1 offset:2048" : "=v"(b2) : "v"(sb));
;     asm volatile("ds_read_b128 %0, %1 offset:3072" : "=v"(b3) : "v"(sb));
;     asm volatile("ds_read_b128 %0, %1" : "=v"(a0) : "v"(sa));
;     asm volatile("ds_read_b128 %0, %1 offset:1024" : "=v"(a1) : "v"(sa));
;     asm volatile("ds_read_b128 %0, %1 offset:2048" : "=v"(a2) : "v"(sa));
;     asm volatile("ds_read_b128 %0, %1 offset:3072" : "=v"(a3) : "v"(sa));
;     asm volatile("ds_read_b128 %0, %1 offset:4096" : "=v"(a4) : "v"(sa));
;     asm volatile("ds_read_b128 %0, %1 offset:5120" : "=v"(a5) : "v"(sa));
;     asm volatile("ds_read_b128 %0, %1 offset:6144" : "=v"(a6) : "v"(sa));
;     asm volatile("ds_read_b128 %0, %1 offset:7168" : "=v"(a7) : "v"(sa));
;     asm volatile("s_waitcnt lgkmcnt(4)" : "+v"(a0), "+v"(a1), "+v"(a2), "+v"(a3), "+v"(b0), "+v"(b1), "+v"(b2), "+v"(b3));
;     bf16x8 Bv[4];
;     Bv[0] = __builtin_bit_cast(bf16x8, b0); Bv[1] = __builtin_bit_cast(bf16x8, b1); Bv[2] = __builtin_bit_cast(bf16x8, b2); Bv[3] = __builtin_bit_cast(bf16x8, b3);
;     {
;       bf16x8 At[4];
;       At[0] = __builtin_bit_cast(bf16x8, a0); At[1] = __builtin_bit_cast(bf16x8, a1); At[2] = __builtin_bit_cast(bf16x8, a2); At[3] = __builtin_bit_cast(bf16x8, a3);
; #pragma unroll
;       for (int m = 0; m < 4; ++m)
; #pragma unroll
;         for (int n = 0; n < 4; ++n) acc[m][n] = __builtin_amdgcn_mfma_f32_16x16x32_bf16(At[m], Bv[n], acc[m][n], 0, 0, 0);
;     }
;     asm volatile("s_waitcnt lgkmcnt(0)" : "+v"(a4), "+v"(a5), "+v"(a6), "+v"(a7));
;     {
;       bf16x8 At[4];
.LBB0_1247:
	s_barrier
	s_mul_i32 s10, s7, 0x6000
	v_add_u32_e32 v134, s10, v149
	v_add_u32_e32 v151, s10, v150
	ds_read_b128 v[152:155], v151
	ds_read_b128 v[156:159], v151 offset:1024
	ds_read_b128 v[160:163], v151 offset:2048
	ds_read_b128 v[164:167], v151 offset:3072
	ds_read_b128 v[168:171], v134
	ds_read_b128 v[172:175], v134 offset:1024
	ds_read_b128 v[176:179], v134 offset:2048
	ds_read_b128 v[180:183], v134 offset:3072
	ds_read_b128 v[184:187], v134 offset:4096
	ds_read_b128 v[188:191], v134 offset:5120
	ds_read_b128 v[192:195], v134 offset:6144
	ds_read_b128 v[196:199], v134 offset:7168
	s_cmp_gt_u32 s26, 61
	s_cbranch_scc1 .Lgnodma_g1
	s_cmp_gt_i32 s7, 0
	s_cselect_b32 s10, -1, 2
	s_add_i32 s10, s10, s7
	s_mulk_i32 s10, 0x6000
	v_add_u32_e32 v252, s10, v148
	s_nop 0
	v_readfirstlane_b32 s10, v252
	s_waitcnt lgkmcnt(7)
	v_mfma_f32_16x16x32_bf16 v[126:129], v[168:171], v[152:155], v[126:129]
	v_mfma_f32_16x16x32_bf16 v[122:125], v[168:171], v[156:159], v[122:125]
	v_mfma_f32_16x16x32_bf16 v[118:121], v[168:171], v[160:163], v[118:121]
	v_mfma_f32_16x16x32_bf16 v[114:117], v[168:171], v[164:167], v[114:117]
	s_lshl_b64 s[32:33], s[8:9], 14
	v_lshl_add_u64 v[250:251], v[130:131], 0, s[32:33]
	s_mov_b32 m0, s10
	s_nop 0
	global_load_lds_dwordx4 v[250:251], off
	s_waitcnt lgkmcnt(6)
	v_mfma_f32_16x16x32_bf16 v[110:113], v[172:175], v[152:155], v[110:113]
	v_mfma_f32_16x16x32_bf16 v[106:109], v[172:175], v[156:159], v[106:109]
	v_mfma_f32_16x16x32_bf16 v[102:105], v[172:175], v[160:163], v[102:105]
	v_mfma_f32_16x16x32_bf16 v[98:101], v[172:175], v[164:167], v[98:101]
	v_lshl_add_u64 v[250:251], v[132:133], 0, s[32:33]
	s_add_u32 m0, s10, 0x1000
	s_nop 0
	global_load_lds_dwordx4 v[250:251], off
	s_waitcnt lgkmcnt(5)
	v_mfma_f32_16x16x32_bf16 v[94:97], v[176:179], v[152:155], v[94:97]
	v_mfma_f32_16x16x32_bf16 v[42:45], v[176:179], v[156:159], v[42:45]
	v_mfma_f32_16x16x32_bf16 v[38:41], v[176:179], v[160:163], v[38:41]
	v_mfma_f32_16x16x32_bf16 v[34:37], v[176:179], v[164:167], v[34:37]
	v_lshl_add_u64 v[250:251], v[136:137], 0, s[32:33]
	s_add_u32 m0, s10, 0x2000
	s_nop 0
	global_load_lds_dwordx4 v[250:251], off
	s_waitcnt lgkmcnt(4)
	v_mfma_f32_16x16x32_bf16 v[30:33], v[180:183], v[152:155], v[30:33]
	v_mfma_f32_16x16x32_bf16 v[26:29], v[180:183], v[156:159], v[26:29]
	v_mfma_f32_16x16x32_bf16 v[22:25], v[180:183], v[160:163], v[22:25]
	v_mfma_f32_16x16x32_bf16 v[18:21], v[180:183], v[164:167], v[18:21]
	v_lshl_add_u64 v[250:251], v[138:139], 0, s[32:33]
	s_add_u32 m0, s10, 0x3000
	s_nop 0
	global_load_lds_dwordx4 v[250:251], off
	s_waitcnt lgkmcnt(3)
	v_mfma_f32_16x16x32_bf16 v[14:17], v[184:187], v[152:155], v[14:17]
	v_mfma_f32_16x16x32_bf16 v[10:13], v[184:187], v[156:159], v[10:13]
	v_mfma_f32_16x16x32_bf16 v[6:9], v[184:187], v[160:163], v[6:9]
	v_mfma_f32_16x16x32_bf16 v[2:5], v[184:187], v[164:167], v[2:5]
	s_mul_i32 s34, s8, 2048
	s_mov_b32 s35, 0
	v_lshl_add_u64 v[250:251], v[142:143], 0, s[34:35]
	s_add_u32 m0, s10, 0x4000
	s_nop 0
	global_load_lds_dwordx4 v[250:251], off
	s_waitcnt lgkmcnt(2)
	v_mfma_f32_16x16x32_bf16 v[46:49], v[188:191], v[152:155], v[46:49]
	v_mfma_f32_16x16x32_bf16 v[50:53], v[188:191], v[156:159], v[50:53]
	v_mfma_f32_16x16x32_bf16 v[54:57], v[188:191], v[160:163], v[54:57]
	v_mfma_f32_16x16x32_bf16 v[58:61], v[188:191], v[164:167], v[58:61]
	v_lshl_add_u64 v[250:251], v[140:141], 0, s[34:35]
	s_add_u32 m0, s10, 0x5000
	s_nop 0
	global_load_lds_dwordx4 v[250:251], off
	s_waitcnt lgkmcnt(1)
	v_mfma_f32_16x16x32_bf16 v[62:65], v[192:195], v[152:155], v[62:65]
	v_mfma_f32_16x16x32_bf16 v[66:69], v[192:195], v[156:159], v[66:69]
	v_mfma_f32_16x16x32_bf16 v[70:73], v[192:195], v[160:163], v[70:73]
	v_mfma_f32_16x16x32_bf16 v[74:77], v[192:195], v[164:167], v[74:77]
	s_waitcnt lgkmcnt(0)
	v_mfma_f32_16x16x32_bf16 v[78:81], v[196:199], v[152:155], v[78:81]
	v_mfma_f32_16x16x32_bf16 v[82:85], v[196:199], v[156:159], v[82:85]
	v_mfma_f32_16x16x32_bf16 v[86:89], v[196:199], v[160:163], v[86:89]
	v_mfma_f32_16x16x32_bf16 v[90:93], v[196:199], v[164:167], v[90:93]
	s_branch .Lgjoin_g1

; template <class AF, class EPI>
; DEV void gemm_tile256(AF aptr, const u16* Bt, int ldb, int K, EPI epi, char* smem) {
;     ...
;   auto stage = [&](int kt, int buf) {
;     char* SA = smem + buf * 24576;
;     char* SB = SA + 16384;
; #pragma unroll
;     for (int i = 0; i < 4; ++i) {
;       int bo = tid * 16 + i * 4096, r = bo >> 6, c = (bo & 63) >> 1;
;       __builtin_amdgcn_global_load_lds((const unsigned*)aptr(r, kt * 32 + c), (__attribute__((address_space(3))) unsigned*)(SA + bo), 16, 0, 0);
;     }
; #pragma unroll
;     for (int i = 0; i < 2; ++i) {
;       int bo = tid * 16 + i * 4096, r = bo >> 6, c = (bo & 63) >> 1;
;       __builtin_amdgcn_global_load_lds((const unsigned*)(Bt + (size_t)r * ldb + kt * 32 + c), (__attribute__((address_space(3))) unsigned*)(SB + bo), 16, 0, 0);
;     }
;   };
;   asm volatile("s_waitcnt vmcnt(0)" ::: "memory");
;   __syncthreads();
;   stage(0, 0);
;   stage(1, 1);
;   const unsigned lbase = (unsigned)(size_t)(const __attribute__((address_space(3))) char*)smem;
;   const unsigned aoff = lbase + (wr * 128 + fr) * 64 + fq * 16, boff = lbase + 16384 + (wc * 64 + fr) * 64 + fq * 16;
; __global__ void __launch_bounds__(256, 2) fwd_megakernel(Params p) {
;     ...
;   for (int jt = (bid >> 3); jt < 8 * 16; jt += (nb >> 3)) {
;     const int pn = jt >> 3, pm = (bid & 7) * 8 + (jt & 7);
;     const u16* A = p.h + (size_t)pm * 256 * 2048;
;     gemm_tile256([&](int r, int k) { return A + (size_t)r * 2048 + k; }, p.Wt_q + (size_t)pn * 128 * 2048, 2048, 2048,
.LBB0_1365:
	s_or_b64 exec, exec, s[6:7]
	v_mov_b32_e32 v1, v0
	s_andn2_b64 vcc, exec, s[0:1]
	s_waitcnt lgkmcnt(0)
	s_barrier
	s_cbranch_vccnz .LBB0_1384
	s_lshl_b32 s0, s94, 3
	s_lshr_b32 s2, s94, 3
	s_and_b32 s3, s0, 56
	s_ashr_i32 s4, s92, 3
	s_mov_b64 s[8:9], s[80:81]
	s_add_u32 s5, s8, 0x200000
	s_addc_u32 s10, s9, 0
	s_and_b32 s0, s94, 7
	s_lshl_b32 s11, s0, 22
	s_add_u32 s12, s50, 0x40000
	s_addc_u32 s13, s51, 0
	s_lshl_b32 s14, s0, 23
	v_mov_b32_e32 v131, 0
	s_movk_i32 s15, 0x4000
	s_movk_i32 s16, 0x210
	s_movk_i32 s17, 0x80
	s_mov_b32 s18, 0x10000
	s_mov_b32 s19, 0x20000
	s_mov_b32 s20, 0x30000
	s_mov_b32 s21, 0x80000
	s_mov_b32 s22, 0x90000
	s_mov_b32 s23, 0xa0000
	s_mov_b32 s24, 0xb0000
.LBB0_1367:
	s_and_b32 s25, s2, 7
	s_lshl_b32 s0, s25, 19
	s_and_b32 s1, s58, 7
	s_add_i32 s0, s11, s0
	s_or_b32 s1, s1, s3
	v_mov_b32_e32 v144, v0
	s_lshr_b32 s28, s0, 5
	s_ashr_i32 s0, s58, 3
	s_lshl_b32 s1, s1, 14
	s_mov_b64 s[8:9], s[80:81]
	s_add_u32 s8, s8, s1
	v_ashrrev_i32_e32 v2, 2, v144
	v_lshlrev_b32_e32 v148, 4, v144
	v_ashrrev_i32_e32 v3, 31, v2
	s_addc_u32 s9, s9, 0
	s_ashr_i32 s1, s0, 31
	v_lshlrev_b64 v[2:3], 12, v[2:3]
	v_lshrrev_b64 v[246:247], 6, v[2:3]
	s_mov_b64 s[30:31], 0x100000
	s_mov_b64 s[32:33], 0x20000
	v_add_u32_e32 v10, 0x1000, v148
	s_lshl_b64 s[6:7], s[0:1], 13
	v_lshl_add_u64 v[4:5], s[8:9], 0, v[246:247]
	v_and_b32_e32 v130, 48, v148
	v_and_b32_e32 v253, 32, v144
	v_xor_b32_e32 v130, v130, v253
	v_readfirstlane_b32 s1, v148
	v_ashrrev_i32_e32 v6, 6, v10
	v_add_u32_e32 v14, 0x2000, v148
	v_lshl_add_u64 v[4:5], v[4:5], 0, v[130:131]
	s_mov_b32 m0, s1
	v_ashrrev_i32_e32 v7, 31, v6
	v_readfirstlane_b32 s1, v10
	v_ashrrev_i32_e32 v10, 6, v14
	v_add_u32_e32 v18, 0x3000, v148
	s_waitcnt vmcnt(0)
	s_barrier
; template <class AF, class EPI>
; DEV void gemm_tile256(AF aptr, const u16* Bt, int ldb, int K, EPI epi, char* smem) {
;     ...
;   auto stage = [&](int kt, int buf) {
;     char* SA = smem + buf * 24576;
;     char* SB = SA + 16384;
; #pragma unroll
;     for (int i = 0; i < 4; ++i) {
;       int bo = tid * 16 + i * 4096, r = bo >> 6, c = (bo & 63) >> 1;
;       __builtin_amdgcn_global_load_lds((const unsigned*)aptr(r, kt * 32 + c), (__attribute__((address_space(3))) unsigned*)(SA + bo), 16, 0, 0);
;     }
; #pragma unroll
;     for (int i = 0; i < 2; ++i) {
;       int bo = tid * 16 + i * 4096, r = bo >> 6, c = (bo & 63) >> 1;
;       __builtin_amdgcn_global_load_lds((const unsigned*)(Bt + (size_t)r * ldb + kt * 32 + c), (__attribute__((address_space(3))) unsigned*)(SB + bo), 16, 0, 0);
;     }
;   };
;   asm volatile("s_waitcnt vmcnt(0)" ::: "memory");
;   __syncthreads();
;   stage(0, 0);
;   stage(1, 1);
;   const unsigned lbase = (unsigned)(size_t)(const __attribute__((address_space(3))) char*)smem;
;   const unsigned aoff = lbase + (wr * 128 + fr) * 64 + fq * 16, boff = lbase + 16384 + (wc * 64 + fr) * 64 + fq * 16;
	global_load_lds_dwordx4 v[4:5], off
	v_lshlrev_b64 v[6:7], 12, v[6:7]
	v_lshrrev_b64 v[248:249], 6, v[6:7]
	s_mov_b32 m0, s1
	v_ashrrev_i32_e32 v11, 31, v10
	v_readfirstlane_b32 s1, v14
	v_ashrrev_i32_e32 v14, 6, v18
	v_lshl_add_u64 v[8:9], s[8:9], 0, v[248:249]
	v_lshlrev_b64 v[10:11], 6, v[10:11]
	v_ashrrev_i32_e32 v15, 31, v14
	s_add_u32 s26, s50, s6
	v_lshl_add_u64 v[8:9], v[8:9], 0, v[130:131]
	v_lshl_add_u64 v[12:13], s[8:9], 0, v[10:11]
	v_lshlrev_b64 v[14:15], 6, v[14:15]
	s_addc_u32 s27, s51, s7
	global_load_lds_dwordx4 v[8:9], off
	v_lshl_add_u64 v[12:13], v[12:13], 0, v[130:131]
	s_mov_b32 m0, s1
	v_lshl_add_u64 v[16:17], s[8:9], 0, v[14:15]
	v_readfirstlane_b32 s1, v18
	v_add_u32_e32 v20, 0x4000, v148
	global_load_lds_dwordx4 v[12:13], off
	v_lshl_add_u64 v[16:17], v[16:17], 0, v[130:131]
	s_mov_b32 m0, s1
	v_lshl_add_u64 v[18:19], s[26:27], 0, v[246:247]
	v_readfirstlane_b32 s1, v20
	v_add_u32_e32 v22, 0x5000, v148
	global_load_lds_dwordx4 v[16:17], off
	v_lshl_add_u64 v[18:19], v[18:19], 0, v[130:131]
	s_mov_b32 m0, s1
	v_lshl_add_u64 v[20:21], s[26:27], 0, v[248:249]
	v_readfirstlane_b32 s1, v22
	v_add_u32_e32 v22, 0x6000, v148
	global_load_lds_dwordx4 v[18:19], off
	v_lshl_add_u64 v[20:21], v[20:21], 0, v[130:131]
	s_mov_b32 m0, s1
	v_readfirstlane_b32 s1, v22
	global_load_lds_dwordx4 v[20:21], off
	v_lshl_add_u64 v[4:5], v[4:5], 0, s[30:31]
	s_mov_b32 m0, s1
	s_add_u32 s8, s5, s28
	global_load_lds_dwordx4 v[4:5], off
	v_lshl_add_u64 v[4:5], v[8:9], 0, s[30:31]
	v_add_u32_e32 v8, 0x7000, v148
	v_bfe_u32 v147, v144, 4, 2
	v_readfirstlane_b32 s1, v8
	v_add_u32_e32 v8, 0x8000, v148
	s_mov_b32 m0, s1
	v_readfirstlane_b32 s1, v8
	v_add_u32_e32 v8, 0x9000, v148
	global_load_lds_dwordx4 v[4:5], off
	v_lshl_add_u64 v[4:5], v[12:13], 0, s[30:31]
	s_mov_b32 m0, s1
	v_readfirstlane_b32 s1, v8
	v_add_u32_e32 v8, 0xa000, v148
	global_load_lds_dwordx4 v[4:5], off
	v_lshl_add_u64 v[4:5], v[16:17], 0, s[30:31]
	s_mov_b32 m0, s1
	v_readfirstlane_b32 s1, v8
	v_add_u32_e32 v8, 0xb000, v148
	global_load_lds_dwordx4 v[4:5], off
	v_lshl_add_u64 v[4:5], v[18:19], 0, s[32:33]
	s_mov_b32 m0, s1
	v_readfirstlane_b32 s1, v8
	global_load_lds_dwordx4 v[4:5], off
	v_lshl_add_u64 v[4:5], v[20:21], 0, s[32:33]
	s_mov_b32 m0, s1
	s_addc_u32 s9, s10, 0
	global_load_lds_dwordx4 v[4:5], off
	v_bfe_u32 v145, v144, 6, 1
	v_ashrrev_i32_e32 v1, 7, v144
	v_and_b32_e32 v146, 15, v144
	v_lshlrev_b32_e32 v8, 4, v147
	v_lshlrev_b32_e32 v253, 2, v144
	v_and_b32_e32 v253, 32, v253
	v_xor_b32_e32 v8, v8, v253
	s_add_u32 s6, s12, s6
	v_lshlrev_b32_e32 v4, 13, v1
	v_lshlrev_b32_e32 v5, 6, v146
	v_lshl_or_b32 v9, v145, 12, v8
	v_or_b32_e32 v2, v2, v130
	v_or_b32_e32 v6, v6, v130
	v_or_b32_e32 v10, v10, v130
	v_or_b32_e32 v14, v14, v130
	s_addc_u32 s7, s13, s7
	v_or3_b32 v149, v4, v8, v5
	v_or3_b32 v150, v5, v9, s15
	v_or_b32_e32 v246, v246, v130
	v_or_b32_e32 v248, v248, v130
	v_lshl_add_u64 v[132:133], s[8:9], 0, v[246:247]
	v_lshl_add_u64 v[134:135], s[8:9], 0, v[248:249]
	v_lshl_add_u64 v[136:137], s[8:9], 0, v[10:11]
	v_lshl_add_u64 v[138:139], s[8:9], 0, v[14:15]
	v_lshl_add_u64 v[140:141], s[6:7], 0, v[248:249]
	v_lshl_add_u64 v[142:143], s[6:7], 0, v[246:247]
	s_mov_b64 s[6:7], 0
	s_mov_b32 s1, 0
	s_mov_b32 s26, 0
	v_mov_b32_e32 v2, 0
	v_mov_b32_e32 v3, v131
	v_mov_b32_e32 v4, v131
	v_mov_b32_e32 v5, v131
	v_mov_b32_e32 v6, 0
	v_mov_b32_e32 v7, v131
	v_mov_b32_e32 v8, v131
	v_mov_b32_e32 v9, v131
	v_mov_b32_e32 v10, 0
	v_mov_b32_e32 v11, v131
	v_mov_b32_e32 v12, v131
	v_mov_b32_e32 v13, v131
	v_mov_b32_e32 v14, 0
	v_mov_b32_e32 v15, v131
	v_mov_b32_e32 v16, v131
	v_mov_b32_e32 v17, v131
	v_mov_b32_e32 v18, 0
	v_mov_b32_e32 v19, v131
	v_mov_b32_e32 v20, v131
	v_mov_b32_e32 v21, v131
	v_mov_b32_e32 v22, 0
	v_mov_b32_e32 v23, v131
	v_mov_b32_e32 v24, v131
	v_mov_b32_e32 v25, v131
	v_mov_b32_e32 v26, 0
	v_mov_b32_e32 v27, v131
	v_mov_b32_e32 v28, v131
	v_mov_b32_e32 v29, v131
	v_mov_b32_e32 v30, 0
	v_mov_b32_e32 v31, v131
	v_mov_b32_e32 v32, v131
	v_mov_b32_e32 v33, v131
	v_mov_b32_e32 v34, 0
	v_mov_b32_e32 v35, v131
	v_mov_b32_e32 v36, v131
	v_mov_b32_e32 v37, v131
	v_mov_b32_e32 v38, 0
	v_mov_b32_e32 v39, v131
	v_mov_b32_e32 v40, v131
	v_mov_b32_e32 v41, v131
	v_mov_b32_e32 v42, 0
	v_mov_b32_e32 v43, v131
	v_mov_b32_e32 v44, v131
	v_mov_b32_e32 v45, v131
	v_mov_b32_e32 v94, 0
	v_mov_b32_e32 v95, v131
	v_mov_b32_e32 v96, v131
	v_mov_b32_e32 v97, v131
	v_mov_b32_e32 v98, 0
	v_mov_b32_e32 v99, v131
	v_mov_b32_e32 v100, v131
	v_mov_b32_e32 v101, v131
	v_mov_b32_e32 v102, 0
	v_mov_b32_e32 v103, v131
	v_mov_b32_e32 v104, v131
	v_mov_b32_e32 v105, v131
	v_mov_b32_e32 v106, 0
	v_mov_b32_e32 v107, v131
	v_mov_b32_e32 v108, v131
	v_mov_b32_e32 v109, v131
	v_mov_b32_e32 v110, 0
	v_mov_b32_e32 v111, v131
	v_mov_b32_e32 v112, v131
	v_mov_b32_e32 v113, v131
	v_mov_b32_e32 v114, 0
	v_mov_b32_e32 v115, v131
	v_mov_b32_e32 v116, v131
	v_mov_b32_e32 v117, v131
	v_mov_b32_e32 v118, 0
	v_mov_b32_e32 v119, v131
	v_mov_b32_e32 v120, v131
	v_mov_b32_e32 v121, v131
	v_mov_b32_e32 v122, 0
	v_mov_b32_e32 v123, v131
	v_mov_b32_e32 v124, v131
	v_mov_b32_e32 v125, v131
	v_mov_b32_e32 v126, 0
	v_mov_b32_e32 v127, v131
	v_mov_b32_e32 v128, v131
	v_mov_b32_e32 v129, v131
	v_mov_b32_e32 v46, 0
	v_mov_b32_e32 v47, v131
	v_mov_b32_e32 v48, v131
	v_mov_b32_e32 v49, v131
	v_mov_b32_e32 v50, 0
	v_mov_b32_e32 v51, v131
	v_mov_b32_e32 v52, v131
	v_mov_b32_e32 v53, v131
	v_mov_b32_e32 v54, 0
	v_mov_b32_e32 v55, v131
	v_mov_b32_e32 v56, v131
	v_mov_b32_e32 v57, v131
	v_mov_b32_e32 v58, 0
	v_mov_b32_e32 v59, v131
	v_mov_b32_e32 v60, v131
	v_mov_b32_e32 v61, v131
	v_mov_b32_e32 v62, 0
	v_mov_b32_e32 v63, v131
	v_mov_b32_e32 v64, v131
	v_mov_b32_e32 v65, v131
	v_mov_b32_e32 v66, 0
	v_mov_b32_e32 v67, v131
	v_mov_b32_e32 v68, v131
	v_mov_b32_e32 v69, v131
	v_mov_b32_e32 v70, 0
	v_mov_b32_e32 v71, v131
	v_mov_b32_e32 v72, v131
	v_mov_b32_e32 v73, v131
	v_mov_b32_e32 v74, 0
	v_mov_b32_e32 v75, v131
	v_mov_b32_e32 v76, v131
	v_mov_b32_e32 v77, v131
	v_mov_b32_e32 v78, 0
	v_mov_b32_e32 v79, v131
	v_mov_b32_e32 v80, v131
	v_mov_b32_e32 v81, v131
	v_mov_b32_e32 v82, 0
	v_mov_b32_e32 v83, v131
	v_mov_b32_e32 v84, v131
	v_mov_b32_e32 v85, v131
	v_mov_b32_e32 v86, 0
	v_mov_b32_e32 v87, v131
	v_mov_b32_e32 v88, v131
	v_mov_b32_e32 v89, v131
	v_mov_b32_e32 v90, 0
	v_mov_b32_e32 v91, v131
	v_mov_b32_e32 v92, v131
	v_mov_b32_e32 v93, v131
	s_branch .LBB0_1369

; template <class AF, class EPI>
; DEV void gemm_tile256(AF aptr, const u16* Bt, int ldb, int K, EPI epi, char* smem) {
;     ...
;   for (int t = 0; t < nk; ++t) {
;     if (t + 1 < nk) asm volatile("s_waitcnt vmcnt(6)" ::: "memory");
;     else asm volatile("s_waitcnt vmcnt(0)" ::: "memory");
;     __builtin_amdgcn_s_barrier();
;     if (t + 2 < nk) { int nb2 = buf + 2; if (nb2 >= 3) nb2 -= 3; stage(t + 2, nb2); }
;     const unsigned sa = aoff + buf * 24576, sb = boff + buf * 24576;
;     u32x4 a0, a1, a2, a3, a4, a5, a6, a7, b0, b1, b2, b3;
;     asm volatile("ds_read_b128 %0, %1" : "=v"(b0) : "v"(sb));
;     asm volatile("ds_read_b128 %0, %1 offset:1024" : "=v"(b1) : "v"(sb));
;     asm volatile("ds_read_b128 %0, %1 offset:2048" : "=v"(b2) : "v"(sb));
;     asm volatile("ds_read_b128 %0, %1 offset:3072" : "=v"(b3) : "v"(sb));
;     asm volatile("ds_read_b128 %0, %1" : "=v"(a0) : "v"(sa));
;     asm volatile("ds_read_b128 %0, %1 offset:1024" : "=v"(a1) : "v"(sa));
;     asm volatile("ds_read_b128 %0, %1 offset:2048" : "=v"(a2) : "v"(sa));
;     asm volatile("ds_read_b128 %0, %1 offset:3072" : "=v"(a3) : "v"(sa));
;     asm volatile("ds_read_b128 %0, %1 offset:4096" : "=v"(a4) : "v"(sa));
;     asm volatile("ds_read_b128 %0, %1 offset:5120" : "=v"(a5) : "v"(sa));
;     asm volatile("ds_read_b128 %0, %1 offset:6144" : "=v"(a6) : "v"(sa));
;     asm volatile("ds_read_b128 %0, %1 offset:7168" : "=v"(a7) : "v"(sa));
;     asm volatile("s_waitcnt lgkmcnt(4)" : "+v"(a0), "+v"(a1), "+v"(a2), "+v"(a3), "+v"(b0), "+v"(b1), "+v"(b2), "+v"(b3));
;     bf16x8 Bv[4];
;     Bv[0] = __builtin_bit_cast(bf16x8, b0); Bv[1] = __builtin_bit_cast(bf16x8, b1); Bv[2] = __builtin_bit_cast(bf16x8, b2); Bv[3] = __builtin_bit_cast(bf16x8, b3);
;     {
;       bf16x8 At[4];
;       At[0] = __builtin_bit_cast(bf16x8, a0); At[1] = __builtin_bit_cast(bf16x8, a1); At[2] = __builtin_bit_cast(bf16x8, a2); At[3] = __builtin_bit_cast(bf16x8, a3);
; #pragma unroll
;       for (int m = 0; m < 4; ++m)
; #pragma unroll
;         for (int n = 0; n < 4; ++n) acc[m][n] = __builtin_amdgcn_mfma_f32_16x16x32_bf16(At[m], Bv[n], acc[m][n], 0, 0, 0);
;     }
;     asm volatile("s_waitcnt lgkmcnt(0)" : "+v"(a4), "+v"(a5), "+v"(a6), "+v"(a7));
;     {
;       bf16x8 At[4];
.LBB0_1373:
	s_barrier
	s_mul_i32 s8, s1, 0x6000
	v_add_u32_e32 v130, s8, v149
	v_add_u32_e32 v151, s8, v150
	ds_read_b128 v[152:155], v151
	ds_read_b128 v[156:159], v151 offset:1024
	ds_read_b128 v[160:163], v151 offset:2048
	ds_read_b128 v[164:167], v151 offset:3072
	ds_read_b128 v[168:171], v130
	ds_read_b128 v[172:175], v130 offset:1024
	ds_read_b128 v[176:179], v130 offset:2048
	ds_read_b128 v[180:183], v130 offset:3072
	ds_read_b128 v[184:187], v130 offset:4096
	ds_read_b128 v[188:191], v130 offset:5120
	ds_read_b128 v[192:195], v130 offset:6144
	ds_read_b128 v[196:199], v130 offset:7168
	s_cmp_gt_u32 s26, 61
	s_cbranch_scc1 .Lgnodma_g0
	s_cmp_gt_i32 s1, 0
	s_cselect_b32 s8, -1, 2
	s_add_i32 s8, s8, s1
	s_mulk_i32 s8, 0x6000
	v_add_u32_e32 v252, s8, v148
	s_nop 0
	v_readfirstlane_b32 s8, v252
	s_waitcnt lgkmcnt(7)
	v_mfma_f32_16x16x32_bf16 v[126:129], v[168:171], v[152:155], v[126:129]
	v_mfma_f32_16x16x32_bf16 v[122:125], v[168:171], v[156:159], v[122:125]
	v_mfma_f32_16x16x32_bf16 v[118:121], v[168:171], v[160:163], v[118:121]
	v_mfma_f32_16x16x32_bf16 v[114:117], v[168:171], v[164:167], v[114:117]
	s_lshl_b64 s[30:31], s[6:7], 14
	v_lshl_add_u64 v[250:251], v[132:133], 0, s[30:31]
	s_mov_b32 m0, s8
	s_nop 0
	global_load_lds_dwordx4 v[250:251], off
	s_waitcnt lgkmcnt(6)
	v_mfma_f32_16x16x32_bf16 v[110:113], v[172:175], v[152:155], v[110:113]
	v_mfma_f32_16x16x32_bf16 v[106:109], v[172:175], v[156:159], v[106:109]
	v_mfma_f32_16x16x32_bf16 v[102:105], v[172:175], v[160:163], v[102:105]
	v_mfma_f32_16x16x32_bf16 v[98:101], v[172:175], v[164:167], v[98:101]
	v_lshl_add_u64 v[250:251], v[134:135], 0, s[30:31]
	s_add_u32 m0, s8, 0x1000
	s_nop 0
	global_load_lds_dwordx4 v[250:251], off
	s_waitcnt lgkmcnt(5)
	v_mfma_f32_16x16x32_bf16 v[94:97], v[176:179], v[152:155], v[94:97]
	v_mfma_f32_16x16x32_bf16 v[42:45], v[176:179], v[156:159], v[42:45]
	v_mfma_f32_16x16x32_bf16 v[38:41], v[176:179], v[160:163], v[38:41]
	v_mfma_f32_16x16x32_bf16 v[34:37], v[176:179], v[164:167], v[34:37]
	v_lshl_add_u64 v[250:251], v[136:137], 0, s[30:31]
	s_add_u32 m0, s8, 0x2000
	s_nop 0
	global_load_lds_dwordx4 v[250:251], off
	s_waitcnt lgkmcnt(4)
	v_mfma_f32_16x16x32_bf16 v[30:33], v[180:183], v[152:155], v[30:33]
	v_mfma_f32_16x16x32_bf16 v[26:29], v[180:183], v[156:159], v[26:29]
	v_mfma_f32_16x16x32_bf16 v[22:25], v[180:183], v[160:163], v[22:25]
	v_mfma_f32_16x16x32_bf16 v[18:21], v[180:183], v[164:167], v[18:21]
	v_lshl_add_u64 v[250:251], v[138:139], 0, s[30:31]
	s_add_u32 m0, s8, 0x3000
	s_nop 0
	global_load_lds_dwordx4 v[250:251], off
	s_waitcnt lgkmcnt(3)
	v_mfma_f32_16x16x32_bf16 v[14:17], v[184:187], v[152:155], v[14:17]
	v_mfma_f32_16x16x32_bf16 v[10:13], v[184:187], v[156:159], v[10:13]
	v_mfma_f32_16x16x32_bf16 v[6:9], v[184:187], v[160:163], v[6:9]
	v_mfma_f32_16x16x32_bf16 v[2:5], v[184:187], v[164:167], v[2:5]
	s_mul_i32 s32, s6, 2048
	s_mov_b32 s33, 0
	v_lshl_add_u64 v[250:251], v[142:143], 0, s[32:33]
	s_add_u32 m0, s8, 0x4000
	s_nop 0
	global_load_lds_dwordx4 v[250:251], off
	s_waitcnt lgkmcnt(2)
	v_mfma_f32_16x16x32_bf16 v[46:49], v[188:191], v[152:155], v[46:49]
	v_mfma_f32_16x16x32_bf16 v[50:53], v[188:191], v[156:159], v[50:53]
	v_mfma_f32_16x16x32_bf16 v[54:57], v[188:191], v[160:163], v[54:57]
	v_mfma_f32_16x16x32_bf16 v[58:61], v[188:191], v[164:167], v[58:61]
	v_lshl_add_u64 v[250:251], v[140:141], 0, s[32:33]
	s_add_u32 m0, s8, 0x5000
	s_nop 0
	global_load_lds_dwordx4 v[250:251], off
	s_waitcnt lgkmcnt(1)
	v_mfma_f32_16x16x32_bf16 v[62:65], v[192:195], v[152:155], v[62:65]
	v_mfma_f32_16x16x32_bf16 v[66:69], v[192:195], v[156:159], v[66:69]
	v_mfma_f32_16x16x32_bf16 v[70:73], v[192:195], v[160:163], v[70:73]
	v_mfma_f32_16x16x32_bf16 v[74:77], v[192:195], v[164:167], v[74:77]
	s_waitcnt lgkmcnt(0)
	v_mfma_f32_16x16x32_bf16 v[78:81], v[196:199], v[152:155], v[78:81]
	v_mfma_f32_16x16x32_bf16 v[82:85], v[196:199], v[156:159], v[82:85]
	v_mfma_f32_16x16x32_bf16 v[86:89], v[196:199], v[160:163], v[86:89]
	v_mfma_f32_16x16x32_bf16 v[90:93], v[196:199], v[164:167], v[90:93]
	s_branch .Lgjoin_g0
